# removed all s_setprio flips inside the 12 GEMM K-loops (A/B test)
# speedup vs baseline: 1.0028x; 1.0028x over previous
.LBB0_272:
	s_add_u32 s58, s22, 0xfff00000
	s_addc_u32 s59, s23, -1
	s_mov_b32 m0, s36
	ds_read_b128 v[154:157], v148
	global_load_lds_dwordx4 v130, s[58:59]
	s_mov_b32 m0, s37
	ds_read_b128 v[158:161], v148 offset:1024
	global_load_lds_dwordx4 v134, s[58:59]
	s_mov_b32 m0, s40
	ds_read_b128 v[164:167], v148 offset:2048
	global_load_lds_dwordx4 v142, s[22:23]
	s_mov_b32 m0, s41
	ds_read_b128 v[168:171], v148 offset:3072
	global_load_lds_dwordx4 v144, s[22:23]
	ds_read_b128 v[172:175], v149
	ds_read_b128 v[176:179], v149 offset:1024
	ds_read_b128 v[180:183], v149 offset:2048
	ds_read_b128 v[184:187], v149 offset:3072
	s_add_u32 s24, s22, 0xfff00080
	s_addc_u32 s25, s23, -1
	s_cmp_eq_u32 s56, 60
	s_cselect_b32 s27, s51, s25
	s_cselect_b32 s26, s52, s24
	s_cselect_b32 s25, s7, s55
	s_cselect_b32 s24, s53, s54
	ds_read_b128 v[188:191], v150
	ds_read_b128 v[192:195], v150 offset:1024
	ds_read_b128 v[196:199], v150 offset:2048
	ds_read_b128 v[200:203], v150 offset:3072
	ds_read_b128 v[204:207], v150 offset:4096
	ds_read_b128 v[208:211], v150 offset:5120
	ds_read_b128 v[212:215], v150 offset:6144
	ds_read_b128 v[216:219], v150 offset:7168
	s_waitcnt vmcnt(8)
	s_waitcnt lgkmcnt(0)
	s_barrier
	s_waitcnt lgkmcnt(0)
	v_mfma_f32_16x16x32_bf16 v[126:129], v[154:157], v[188:191], v[126:129]
	v_mfma_f32_16x16x32_bf16 v[126:129], v[158:161], v[192:195], v[126:129]
	v_mfma_f32_16x16x32_bf16 v[122:125], v[168:171], v[192:195], v[122:125]
	v_mfma_f32_16x16x32_bf16 v[122:125], v[164:167], v[188:191], v[122:125]
	v_mfma_f32_16x16x32_bf16 v[114:117], v[164:167], v[196:199], v[114:117]
	v_mfma_f32_16x16x32_bf16 v[114:117], v[168:171], v[200:203], v[114:117]
	v_mfma_f32_16x16x32_bf16 v[118:121], v[158:161], v[200:203], v[118:121]
	v_mfma_f32_16x16x32_bf16 v[118:121], v[154:157], v[196:199], v[118:121]
	v_mfma_f32_16x16x32_bf16 v[102:105], v[154:157], v[204:207], v[102:105]
	v_mfma_f32_16x16x32_bf16 v[102:105], v[158:161], v[208:211], v[102:105]
	v_mfma_f32_16x16x32_bf16 v[98:101], v[168:171], v[208:211], v[98:101]
	v_mfma_f32_16x16x32_bf16 v[98:101], v[164:167], v[204:207], v[98:101]
	v_mfma_f32_16x16x32_bf16 v[82:85], v[164:167], v[212:215], v[82:85]
	v_mfma_f32_16x16x32_bf16 v[82:85], v[168:171], v[216:219], v[82:85]
	v_mfma_f32_16x16x32_bf16 v[86:89], v[158:161], v[216:219], v[86:89]
	v_mfma_f32_16x16x32_bf16 v[86:89], v[154:157], v[212:215], v[86:89]
	v_mfma_f32_16x16x32_bf16 v[70:73], v[172:175], v[212:215], v[70:73]
	v_mfma_f32_16x16x32_bf16 v[70:73], v[176:179], v[216:219], v[70:73]
	v_mfma_f32_16x16x32_bf16 v[66:69], v[184:187], v[216:219], v[66:69]
	v_mfma_f32_16x16x32_bf16 v[66:69], v[180:183], v[212:215], v[66:69]
	v_mfma_f32_16x16x32_bf16 v[74:77], v[180:183], v[204:207], v[74:77]
	v_mfma_f32_16x16x32_bf16 v[74:77], v[184:187], v[208:211], v[74:77]
	v_mfma_f32_16x16x32_bf16 v[78:81], v[176:179], v[208:211], v[78:81]
	v_mfma_f32_16x16x32_bf16 v[78:81], v[172:175], v[204:207], v[78:81]
	v_mfma_f32_16x16x32_bf16 v[94:97], v[172:175], v[196:199], v[94:97]
	v_mfma_f32_16x16x32_bf16 v[94:97], v[176:179], v[200:203], v[94:97]
	v_mfma_f32_16x16x32_bf16 v[90:93], v[184:187], v[200:203], v[90:93]
	v_mfma_f32_16x16x32_bf16 v[90:93], v[180:183], v[196:199], v[90:93]
	v_mfma_f32_16x16x32_bf16 v[106:109], v[180:183], v[188:191], v[106:109]
	v_mfma_f32_16x16x32_bf16 v[106:109], v[184:187], v[192:195], v[106:109]
	v_mfma_f32_16x16x32_bf16 v[110:113], v[176:179], v[192:195], v[110:113]
	v_mfma_f32_16x16x32_bf16 v[110:113], v[172:175], v[188:191], v[110:113]
	s_barrier
	s_mov_b32 m0, s42
	s_add_u32 s58, s24, 0x100000
	global_load_lds_dwordx4 v132, s[24:25]
	s_mov_b32 m0, s43
	s_addc_u32 s59, s25, 0
	global_load_lds_dwordx4 v136, s[24:25]
	s_mov_b32 m0, s44
	ds_read_b128 v[188:191], v150 offset:16384
	global_load_lds_dwordx4 v132, s[58:59]
	s_mov_b32 m0, s45
	ds_read_b128 v[192:195], v150 offset:17408
	global_load_lds_dwordx4 v136, s[58:59]
	ds_read_b128 v[196:199], v150 offset:18432
	ds_read_b128 v[200:203], v150 offset:19456
	ds_read_b128 v[204:207], v150 offset:20480
	ds_read_b128 v[208:211], v150 offset:21504
	ds_read_b128 v[212:215], v150 offset:22528
	ds_read_b128 v[216:219], v150 offset:23552
	s_waitcnt vmcnt(6)
	s_waitcnt lgkmcnt(0)
	s_barrier
	s_waitcnt lgkmcnt(0)
	v_mfma_f32_16x16x32_bf16 v[62:65], v[154:157], v[188:191], v[62:65]
	v_mfma_f32_16x16x32_bf16 v[62:65], v[158:161], v[192:195], v[62:65]
	v_mfma_f32_16x16x32_bf16 v[58:61], v[168:171], v[192:195], v[58:61]
	v_mfma_f32_16x16x32_bf16 v[58:61], v[164:167], v[188:191], v[58:61]
	v_mfma_f32_16x16x32_bf16 v[50:53], v[164:167], v[196:199], v[50:53]
	v_mfma_f32_16x16x32_bf16 v[50:53], v[168:171], v[200:203], v[50:53]
	v_mfma_f32_16x16x32_bf16 v[54:57], v[158:161], v[200:203], v[54:57]
	v_mfma_f32_16x16x32_bf16 v[54:57], v[154:157], v[196:199], v[54:57]
	v_mfma_f32_16x16x32_bf16 v[38:41], v[154:157], v[204:207], v[38:41]
	v_mfma_f32_16x16x32_bf16 v[38:41], v[158:161], v[208:211], v[38:41]
	v_mfma_f32_16x16x32_bf16 v[34:37], v[168:171], v[208:211], v[34:37]
	v_mfma_f32_16x16x32_bf16 v[34:37], v[164:167], v[204:207], v[34:37]
	v_mfma_f32_16x16x32_bf16 v[18:21], v[164:167], v[212:215], v[18:21]
	v_mfma_f32_16x16x32_bf16 v[18:21], v[168:171], v[216:219], v[18:21]
	v_mfma_f32_16x16x32_bf16 v[22:25], v[158:161], v[216:219], v[22:25]
	v_mfma_f32_16x16x32_bf16 v[22:25], v[154:157], v[212:215], v[22:25]
	v_mfma_f32_16x16x32_bf16 v[6:9], v[172:175], v[212:215], v[6:9]
	v_mfma_f32_16x16x32_bf16 v[6:9], v[176:179], v[216:219], v[6:9]
	v_mfma_f32_16x16x32_bf16 v[2:5], v[184:187], v[216:219], v[2:5]
	v_mfma_f32_16x16x32_bf16 v[2:5], v[180:183], v[212:215], v[2:5]
	v_mfma_f32_16x16x32_bf16 v[10:13], v[180:183], v[204:207], v[10:13]
	v_mfma_f32_16x16x32_bf16 v[10:13], v[184:187], v[208:211], v[10:13]
	v_mfma_f32_16x16x32_bf16 v[14:17], v[176:179], v[208:211], v[14:17]
	v_mfma_f32_16x16x32_bf16 v[14:17], v[172:175], v[204:207], v[14:17]
	v_mfma_f32_16x16x32_bf16 v[30:33], v[172:175], v[196:199], v[30:33]
	v_mfma_f32_16x16x32_bf16 v[30:33], v[176:179], v[200:203], v[30:33]
	v_mfma_f32_16x16x32_bf16 v[26:29], v[184:187], v[200:203], v[26:29]
	v_mfma_f32_16x16x32_bf16 v[26:29], v[180:183], v[196:199], v[26:29]
	v_mfma_f32_16x16x32_bf16 v[42:45], v[180:183], v[188:191], v[42:45]
	v_mfma_f32_16x16x32_bf16 v[42:45], v[184:187], v[192:195], v[42:45]
	v_mfma_f32_16x16x32_bf16 v[46:49], v[176:179], v[192:195], v[46:49]
	v_mfma_f32_16x16x32_bf16 v[46:49], v[172:175], v[188:191], v[46:49]
	s_barrier
	s_mov_b32 m0, s30
	ds_read_b128 v[154:157], v151
	global_load_lds_dwordx4 v130, s[26:27]
	s_mov_b32 m0, s31
	ds_read_b128 v[158:161], v151 offset:1024
	global_load_lds_dwordx4 v134, s[26:27]
	s_add_u32 s26, s26, 0x100000
	s_addc_u32 s27, s27, 0
	s_mov_b32 m0, s33
	ds_read_b128 v[164:167], v151 offset:2048
	global_load_lds_dwordx4 v130, s[26:27]
	s_mov_b32 m0, s34
	ds_read_b128 v[168:171], v151 offset:3072
	global_load_lds_dwordx4 v134, s[26:27]
	ds_read_b128 v[172:175], v152
	ds_read_b128 v[176:179], v152 offset:1024
	ds_read_b128 v[180:183], v152 offset:2048
	ds_read_b128 v[184:187], v152 offset:3072
	ds_read_b128 v[188:191], v150 offset:32768
	ds_read_b128 v[192:195], v150 offset:33792
	ds_read_b128 v[196:199], v150 offset:34816
	ds_read_b128 v[200:203], v150 offset:35840
	ds_read_b128 v[204:207], v150 offset:36864
	ds_read_b128 v[208:211], v150 offset:37888
	ds_read_b128 v[212:215], v150 offset:38912
	ds_read_b128 v[216:219], v150 offset:39936
	s_waitcnt vmcnt(8)
	s_waitcnt lgkmcnt(0)
	s_barrier
	s_waitcnt lgkmcnt(0)
	v_mfma_f32_16x16x32_bf16 v[126:129], v[154:157], v[188:191], v[126:129]
	v_mfma_f32_16x16x32_bf16 v[126:129], v[158:161], v[192:195], v[126:129]
	v_mfma_f32_16x16x32_bf16 v[122:125], v[168:171], v[192:195], v[122:125]
	v_mfma_f32_16x16x32_bf16 v[122:125], v[164:167], v[188:191], v[122:125]
	v_mfma_f32_16x16x32_bf16 v[114:117], v[164:167], v[196:199], v[114:117]
	v_mfma_f32_16x16x32_bf16 v[114:117], v[168:171], v[200:203], v[114:117]
	v_mfma_f32_16x16x32_bf16 v[118:121], v[158:161], v[200:203], v[118:121]
	v_mfma_f32_16x16x32_bf16 v[118:121], v[154:157], v[196:199], v[118:121]
	v_mfma_f32_16x16x32_bf16 v[102:105], v[154:157], v[204:207], v[102:105]
	v_mfma_f32_16x16x32_bf16 v[102:105], v[158:161], v[208:211], v[102:105]
	v_mfma_f32_16x16x32_bf16 v[98:101], v[168:171], v[208:211], v[98:101]
	v_mfma_f32_16x16x32_bf16 v[98:101], v[164:167], v[204:207], v[98:101]
	v_mfma_f32_16x16x32_bf16 v[82:85], v[164:167], v[212:215], v[82:85]
	v_mfma_f32_16x16x32_bf16 v[82:85], v[168:171], v[216:219], v[82:85]
	v_mfma_f32_16x16x32_bf16 v[86:89], v[158:161], v[216:219], v[86:89]
	v_mfma_f32_16x16x32_bf16 v[86:89], v[154:157], v[212:215], v[86:89]
	v_mfma_f32_16x16x32_bf16 v[70:73], v[172:175], v[212:215], v[70:73]
	v_mfma_f32_16x16x32_bf16 v[70:73], v[176:179], v[216:219], v[70:73]
	v_mfma_f32_16x16x32_bf16 v[66:69], v[184:187], v[216:219], v[66:69]
	v_mfma_f32_16x16x32_bf16 v[66:69], v[180:183], v[212:215], v[66:69]
	v_mfma_f32_16x16x32_bf16 v[74:77], v[180:183], v[204:207], v[74:77]
	v_mfma_f32_16x16x32_bf16 v[74:77], v[184:187], v[208:211], v[74:77]
	v_mfma_f32_16x16x32_bf16 v[78:81], v[176:179], v[208:211], v[78:81]
	v_mfma_f32_16x16x32_bf16 v[78:81], v[172:175], v[204:207], v[78:81]
	v_mfma_f32_16x16x32_bf16 v[94:97], v[172:175], v[196:199], v[94:97]
	v_mfma_f32_16x16x32_bf16 v[94:97], v[176:179], v[200:203], v[94:97]
	v_mfma_f32_16x16x32_bf16 v[90:93], v[184:187], v[200:203], v[90:93]
	v_mfma_f32_16x16x32_bf16 v[90:93], v[180:183], v[196:199], v[90:93]
	v_mfma_f32_16x16x32_bf16 v[106:109], v[180:183], v[188:191], v[106:109]
	v_mfma_f32_16x16x32_bf16 v[106:109], v[184:187], v[192:195], v[106:109]
	v_mfma_f32_16x16x32_bf16 v[110:113], v[176:179], v[192:195], v[110:113]
	v_mfma_f32_16x16x32_bf16 v[110:113], v[172:175], v[188:191], v[110:113]
	s_barrier
	s_mov_b32 m0, s47
	s_add_u32 s24, s24, 0x80
	s_addc_u32 s25, s25, 0
	global_load_lds_dwordx4 v132, s[24:25]
	s_mov_b32 m0, s48
	ds_read_b128 v[188:191], v150 offset:49152
	global_load_lds_dwordx4 v136, s[24:25]
	s_add_i32 s26, s46, s29
	s_mov_b32 m0, s26
	s_add_u32 s24, s24, 0x100000
	s_addc_u32 s25, s25, 0
	global_load_lds_dwordx4 v132, s[24:25]
	s_add_i32 m0, s26, 0x2000
	ds_read_b128 v[192:195], v150 offset:50176
	global_load_lds_dwordx4 v136, s[24:25]
	ds_read_b128 v[196:199], v150 offset:51200
	ds_read_b128 v[200:203], v150 offset:52224
	ds_read_b128 v[204:207], v150 offset:53248
	ds_read_b128 v[208:211], v150 offset:54272
	ds_read_b128 v[212:215], v150 offset:55296
	ds_read_b128 v[216:219], v150 offset:56320
	s_waitcnt vmcnt(6)
	s_waitcnt lgkmcnt(0)
	s_barrier
	s_waitcnt lgkmcnt(0)
	v_mfma_f32_16x16x32_bf16 v[62:65], v[154:157], v[188:191], v[62:65]
	v_mfma_f32_16x16x32_bf16 v[62:65], v[158:161], v[192:195], v[62:65]
	v_mfma_f32_16x16x32_bf16 v[58:61], v[168:171], v[192:195], v[58:61]
	v_mfma_f32_16x16x32_bf16 v[58:61], v[164:167], v[188:191], v[58:61]
	v_mfma_f32_16x16x32_bf16 v[50:53], v[164:167], v[196:199], v[50:53]
	v_mfma_f32_16x16x32_bf16 v[50:53], v[168:171], v[200:203], v[50:53]
	v_mfma_f32_16x16x32_bf16 v[54:57], v[158:161], v[200:203], v[54:57]
	v_mfma_f32_16x16x32_bf16 v[54:57], v[154:157], v[196:199], v[54:57]
	v_mfma_f32_16x16x32_bf16 v[38:41], v[154:157], v[204:207], v[38:41]
	v_mfma_f32_16x16x32_bf16 v[38:41], v[158:161], v[208:211], v[38:41]
	v_mfma_f32_16x16x32_bf16 v[34:37], v[168:171], v[208:211], v[34:37]
	v_mfma_f32_16x16x32_bf16 v[34:37], v[164:167], v[204:207], v[34:37]
	v_mfma_f32_16x16x32_bf16 v[18:21], v[164:167], v[212:215], v[18:21]
	v_mfma_f32_16x16x32_bf16 v[18:21], v[168:171], v[216:219], v[18:21]
	v_mfma_f32_16x16x32_bf16 v[22:25], v[158:161], v[216:219], v[22:25]
	v_mfma_f32_16x16x32_bf16 v[22:25], v[154:157], v[212:215], v[22:25]
	v_mfma_f32_16x16x32_bf16 v[6:9], v[172:175], v[212:215], v[6:9]
	v_mfma_f32_16x16x32_bf16 v[6:9], v[176:179], v[216:219], v[6:9]
	v_mfma_f32_16x16x32_bf16 v[2:5], v[184:187], v[216:219], v[2:5]
	v_mfma_f32_16x16x32_bf16 v[2:5], v[180:183], v[212:215], v[2:5]
	v_mfma_f32_16x16x32_bf16 v[10:13], v[180:183], v[204:207], v[10:13]
	v_mfma_f32_16x16x32_bf16 v[10:13], v[184:187], v[208:211], v[10:13]
	v_mfma_f32_16x16x32_bf16 v[14:17], v[176:179], v[208:211], v[14:17]
	v_mfma_f32_16x16x32_bf16 v[14:17], v[172:175], v[204:207], v[14:17]
	v_mfma_f32_16x16x32_bf16 v[30:33], v[172:175], v[196:199], v[30:33]
	v_mfma_f32_16x16x32_bf16 v[30:33], v[176:179], v[200:203], v[30:33]
	v_mfma_f32_16x16x32_bf16 v[26:29], v[184:187], v[200:203], v[26:29]
	v_mfma_f32_16x16x32_bf16 v[26:29], v[180:183], v[196:199], v[26:29]
	v_mfma_f32_16x16x32_bf16 v[42:45], v[180:183], v[188:191], v[42:45]
	v_mfma_f32_16x16x32_bf16 v[42:45], v[184:187], v[192:195], v[42:45]
	v_mfma_f32_16x16x32_bf16 v[46:49], v[176:179], v[192:195], v[46:49]
	v_mfma_f32_16x16x32_bf16 v[46:49], v[172:175], v[188:191], v[46:49]
	s_barrier
	s_add_i32 s56, s56, 2
	s_add_u32 s22, s22, 0x100
	s_addc_u32 s23, s23, 0
	s_add_u32 s54, s54, 0x100
	s_addc_u32 s55, s55, 0
	s_cmp_gt_u32 s56, 61
	s_cbranch_scc0 .LBB0_272
	s_and_b64 vcc, exec, s[16:17]
	s_cbranch_vccz .LBB0_277
	s_barrier
	v_lshl_add_u32 v138, s50, 8, v1
	s_cmp_gt_i32 s49, 63
	s_mov_b64 s[22:23], -1
	s_cbranch_scc1 .LBB0_278

.LBB0_1009:
	ds_read_b128 v[142:145], v155
	ds_read_b128 v[158:161], v155 offset:1024
	ds_read_b128 v[168:171], v155 offset:2048
	ds_read_b128 v[176:179], v155 offset:3072
	ds_read_b128 v[180:183], v156
	ds_read_b128 v[184:187], v156 offset:1024
	ds_read_b128 v[188:191], v156 offset:2048
	ds_read_b128 v[192:195], v156 offset:3072
	s_add_u32 s24, s22, 0xfff00080
	s_addc_u32 s25, s23, -1
	s_cmp_eq_u32 s51, 60
	s_cselect_b32 s27, s19, s25
	s_cselect_b32 s26, s47, s24
	s_cselect_b32 s25, s7, s50
	s_cselect_b32 s24, s48, s49
	s_mov_b32 m0, s40
	ds_read_b128 v[202:205], v157
	ds_read_b128 v[206:209], v157 offset:1024
	ds_read_b128 v[210:213], v157 offset:2048
	ds_read_b128 v[214:217], v157 offset:3072
	ds_read_b128 v[218:221], v157 offset:4096
	ds_read_b128 v[222:225], v157 offset:5120
	ds_read_b128 v[226:229], v157 offset:6144
	ds_read_b128 v[230:233], v157 offset:7168
	global_load_lds_dwordx4 v138, s[22:23]
	s_mov_b32 m0, s41
	s_nop 0
	global_load_lds_dwordx4 v140, s[22:23]
	s_waitcnt vmcnt(8)
	s_waitcnt lgkmcnt(0)
	s_barrier
	s_waitcnt lgkmcnt(0)
	v_mfma_f32_16x16x32_bf16 v[126:129], v[142:145], v[202:205], v[126:129]
	v_mfma_f32_16x16x32_bf16 v[126:129], v[158:161], v[206:209], v[126:129]
	v_mfma_f32_16x16x32_bf16 v[122:125], v[176:179], v[206:209], v[122:125]
	v_mfma_f32_16x16x32_bf16 v[122:125], v[168:171], v[202:205], v[122:125]
	v_mfma_f32_16x16x32_bf16 v[106:109], v[168:171], v[210:213], v[106:109]
	v_mfma_f32_16x16x32_bf16 v[106:109], v[176:179], v[214:217], v[106:109]
	v_mfma_f32_16x16x32_bf16 v[110:113], v[158:161], v[214:217], v[110:113]
	v_mfma_f32_16x16x32_bf16 v[110:113], v[142:145], v[210:213], v[110:113]
	v_mfma_f32_16x16x32_bf16 v[94:97], v[142:145], v[218:221], v[94:97]
	v_mfma_f32_16x16x32_bf16 v[94:97], v[158:161], v[222:225], v[94:97]
	v_mfma_f32_16x16x32_bf16 v[90:93], v[176:179], v[222:225], v[90:93]
	v_mfma_f32_16x16x32_bf16 v[90:93], v[168:171], v[218:221], v[90:93]
	v_mfma_f32_16x16x32_bf16 v[74:77], v[168:171], v[226:229], v[74:77]
	v_mfma_f32_16x16x32_bf16 v[74:77], v[176:179], v[230:233], v[74:77]
	v_mfma_f32_16x16x32_bf16 v[78:81], v[158:161], v[230:233], v[78:81]
	v_mfma_f32_16x16x32_bf16 v[78:81], v[142:145], v[226:229], v[78:81]
	v_mfma_f32_16x16x32_bf16 v[70:73], v[180:183], v[226:229], v[70:73]
	v_mfma_f32_16x16x32_bf16 v[70:73], v[184:187], v[230:233], v[70:73]
	v_mfma_f32_16x16x32_bf16 v[66:69], v[192:195], v[230:233], v[66:69]
	v_mfma_f32_16x16x32_bf16 v[66:69], v[188:191], v[226:229], v[66:69]
	v_mfma_f32_16x16x32_bf16 v[82:85], v[188:191], v[218:221], v[82:85]
	v_mfma_f32_16x16x32_bf16 v[82:85], v[192:195], v[222:225], v[82:85]
	v_mfma_f32_16x16x32_bf16 v[86:89], v[184:187], v[222:225], v[86:89]
	v_mfma_f32_16x16x32_bf16 v[86:89], v[180:183], v[218:221], v[86:89]
	v_mfma_f32_16x16x32_bf16 v[102:105], v[180:183], v[210:213], v[102:105]
	v_mfma_f32_16x16x32_bf16 v[102:105], v[184:187], v[214:217], v[102:105]
	v_mfma_f32_16x16x32_bf16 v[98:101], v[192:195], v[214:217], v[98:101]
	v_mfma_f32_16x16x32_bf16 v[98:101], v[188:191], v[210:213], v[98:101]
	v_mfma_f32_16x16x32_bf16 v[114:117], v[188:191], v[202:205], v[114:117]
	v_mfma_f32_16x16x32_bf16 v[114:117], v[192:195], v[206:209], v[114:117]
	v_mfma_f32_16x16x32_bf16 v[118:121], v[184:187], v[206:209], v[118:121]
	v_mfma_f32_16x16x32_bf16 v[118:121], v[180:183], v[202:205], v[118:121]
	s_barrier
	s_mov_b32 m0, s42
	s_add_u32 s52, s24, 0x100000
	ds_read_b128 v[202:205], v157 offset:16384
	ds_read_b128 v[206:209], v157 offset:17408
	ds_read_b128 v[210:213], v157 offset:18432
	ds_read_b128 v[214:217], v157 offset:19456
	ds_read_b128 v[218:221], v157 offset:20480
	ds_read_b128 v[222:225], v157 offset:21504
	ds_read_b128 v[226:229], v157 offset:22528
	ds_read_b128 v[230:233], v157 offset:23552
	global_load_lds_dwordx4 v132, s[24:25]
	s_mov_b32 m0, s43
	s_addc_u32 s53, s25, 0
	global_load_lds_dwordx4 v136, s[24:25]
	s_mov_b32 m0, s44
	s_nop 0
	global_load_lds_dwordx4 v132, s[52:53]
	s_add_i32 m0, s44, 0x2000
	s_nop 0
	global_load_lds_dwordx4 v136, s[52:53]
	s_mov_b32 m0, s33
	s_nop 0
	global_load_lds_dwordx4 v130, s[26:27]
	s_mov_b32 m0, s34
	s_nop 0
	global_load_lds_dwordx4 v134, s[26:27]
	s_waitcnt vmcnt(8)
	s_waitcnt lgkmcnt(0)
	s_barrier
	s_waitcnt lgkmcnt(0)
	v_mfma_f32_16x16x32_bf16 v[62:65], v[142:145], v[202:205], v[62:65]
	v_mfma_f32_16x16x32_bf16 v[62:65], v[158:161], v[206:209], v[62:65]
	v_mfma_f32_16x16x32_bf16 v[58:61], v[176:179], v[206:209], v[58:61]
	v_mfma_f32_16x16x32_bf16 v[58:61], v[168:171], v[202:205], v[58:61]
	v_mfma_f32_16x16x32_bf16 v[42:45], v[168:171], v[210:213], v[42:45]
	v_mfma_f32_16x16x32_bf16 v[42:45], v[176:179], v[214:217], v[42:45]
	v_mfma_f32_16x16x32_bf16 v[46:49], v[158:161], v[214:217], v[46:49]
	v_mfma_f32_16x16x32_bf16 v[46:49], v[142:145], v[210:213], v[46:49]
	v_mfma_f32_16x16x32_bf16 v[30:33], v[142:145], v[218:221], v[30:33]
	v_mfma_f32_16x16x32_bf16 v[30:33], v[158:161], v[222:225], v[30:33]
	v_mfma_f32_16x16x32_bf16 v[26:29], v[176:179], v[222:225], v[26:29]
	v_mfma_f32_16x16x32_bf16 v[26:29], v[168:171], v[218:221], v[26:29]
	v_mfma_f32_16x16x32_bf16 v[10:13], v[168:171], v[226:229], v[10:13]
	v_mfma_f32_16x16x32_bf16 v[10:13], v[176:179], v[230:233], v[10:13]
	v_mfma_f32_16x16x32_bf16 v[14:17], v[158:161], v[230:233], v[14:17]
	v_mfma_f32_16x16x32_bf16 v[14:17], v[142:145], v[226:229], v[14:17]
	v_mfma_f32_16x16x32_bf16 v[6:9], v[180:183], v[226:229], v[6:9]
	v_mfma_f32_16x16x32_bf16 v[6:9], v[184:187], v[230:233], v[6:9]
	v_mfma_f32_16x16x32_bf16 v[2:5], v[192:195], v[230:233], v[2:5]
	v_mfma_f32_16x16x32_bf16 v[2:5], v[188:191], v[226:229], v[2:5]
	v_mfma_f32_16x16x32_bf16 v[18:21], v[188:191], v[218:221], v[18:21]
	v_mfma_f32_16x16x32_bf16 v[18:21], v[192:195], v[222:225], v[18:21]
	v_mfma_f32_16x16x32_bf16 v[22:25], v[184:187], v[222:225], v[22:25]
	v_mfma_f32_16x16x32_bf16 v[22:25], v[180:183], v[218:221], v[22:25]
	v_mfma_f32_16x16x32_bf16 v[38:41], v[180:183], v[210:213], v[38:41]
	v_mfma_f32_16x16x32_bf16 v[38:41], v[184:187], v[214:217], v[38:41]
	v_mfma_f32_16x16x32_bf16 v[34:37], v[192:195], v[214:217], v[34:37]
	v_mfma_f32_16x16x32_bf16 v[34:37], v[188:191], v[210:213], v[34:37]
	v_mfma_f32_16x16x32_bf16 v[50:53], v[188:191], v[202:205], v[50:53]
	v_mfma_f32_16x16x32_bf16 v[50:53], v[192:195], v[206:209], v[50:53]
	v_mfma_f32_16x16x32_bf16 v[54:57], v[184:187], v[206:209], v[54:57]
	v_mfma_f32_16x16x32_bf16 v[54:57], v[180:183], v[202:205], v[54:57]
	s_barrier
	s_add_i32 s52, 0, 0x18000
	v_add_u32_e32 v166, s52, v153
	s_add_i32 s53, 0, 0x1c000
	ds_read_b128 v[142:145], v166
	ds_read_b128 v[158:161], v166 offset:1024
	ds_read_b128 v[168:171], v166 offset:2048
	ds_read_b128 v[176:179], v166 offset:3072
	v_add_u32_e32 v166, s53, v153
	ds_read_b128 v[180:183], v166
	ds_read_b128 v[184:187], v166 offset:1024
	ds_read_b128 v[188:191], v166 offset:2048
	ds_read_b128 v[192:195], v166 offset:3072
	s_add_u32 s26, s26, 0x100000
	s_addc_u32 s27, s27, 0
	s_mov_b32 m0, s35
	ds_read_b128 v[202:205], v157 offset:32768
	ds_read_b128 v[206:209], v157 offset:33792
	ds_read_b128 v[210:213], v157 offset:34816
	ds_read_b128 v[214:217], v157 offset:35840
	ds_read_b128 v[218:221], v157 offset:36864
	ds_read_b128 v[222:225], v157 offset:37888
	ds_read_b128 v[226:229], v157 offset:38912
	ds_read_b128 v[230:233], v157 offset:39936
	global_load_lds_dwordx4 v130, s[26:27]
	s_mov_b32 m0, s36
	s_nop 0
	global_load_lds_dwordx4 v134, s[26:27]
	s_waitcnt vmcnt(8)
	s_waitcnt lgkmcnt(0)
	s_barrier
	s_waitcnt lgkmcnt(0)
	v_mfma_f32_16x16x32_bf16 v[126:129], v[142:145], v[202:205], v[126:129]
	v_mfma_f32_16x16x32_bf16 v[126:129], v[158:161], v[206:209], v[126:129]
	v_mfma_f32_16x16x32_bf16 v[122:125], v[176:179], v[206:209], v[122:125]
	v_mfma_f32_16x16x32_bf16 v[122:125], v[168:171], v[202:205], v[122:125]
	v_mfma_f32_16x16x32_bf16 v[106:109], v[168:171], v[210:213], v[106:109]
	v_mfma_f32_16x16x32_bf16 v[106:109], v[176:179], v[214:217], v[106:109]
	v_mfma_f32_16x16x32_bf16 v[110:113], v[158:161], v[214:217], v[110:113]
	v_mfma_f32_16x16x32_bf16 v[110:113], v[142:145], v[210:213], v[110:113]
	v_mfma_f32_16x16x32_bf16 v[94:97], v[142:145], v[218:221], v[94:97]
	v_mfma_f32_16x16x32_bf16 v[94:97], v[158:161], v[222:225], v[94:97]
	v_mfma_f32_16x16x32_bf16 v[90:93], v[176:179], v[222:225], v[90:93]
	v_mfma_f32_16x16x32_bf16 v[90:93], v[168:171], v[218:221], v[90:93]
	v_mfma_f32_16x16x32_bf16 v[74:77], v[168:171], v[226:229], v[74:77]
	v_mfma_f32_16x16x32_bf16 v[74:77], v[176:179], v[230:233], v[74:77]
	v_mfma_f32_16x16x32_bf16 v[78:81], v[158:161], v[230:233], v[78:81]
	v_mfma_f32_16x16x32_bf16 v[78:81], v[142:145], v[226:229], v[78:81]
	v_mfma_f32_16x16x32_bf16 v[70:73], v[180:183], v[226:229], v[70:73]
	v_mfma_f32_16x16x32_bf16 v[70:73], v[184:187], v[230:233], v[70:73]
	v_mfma_f32_16x16x32_bf16 v[66:69], v[192:195], v[230:233], v[66:69]
	v_mfma_f32_16x16x32_bf16 v[66:69], v[188:191], v[226:229], v[66:69]
	v_mfma_f32_16x16x32_bf16 v[82:85], v[188:191], v[218:221], v[82:85]
	v_mfma_f32_16x16x32_bf16 v[82:85], v[192:195], v[222:225], v[82:85]
	v_mfma_f32_16x16x32_bf16 v[86:89], v[184:187], v[222:225], v[86:89]
	v_mfma_f32_16x16x32_bf16 v[86:89], v[180:183], v[218:221], v[86:89]
	v_mfma_f32_16x16x32_bf16 v[102:105], v[180:183], v[210:213], v[102:105]
	v_mfma_f32_16x16x32_bf16 v[102:105], v[184:187], v[214:217], v[102:105]
	v_mfma_f32_16x16x32_bf16 v[98:101], v[192:195], v[214:217], v[98:101]
	v_mfma_f32_16x16x32_bf16 v[98:101], v[188:191], v[210:213], v[98:101]
	v_mfma_f32_16x16x32_bf16 v[114:117], v[188:191], v[202:205], v[114:117]
	v_mfma_f32_16x16x32_bf16 v[114:117], v[192:195], v[206:209], v[114:117]
	v_mfma_f32_16x16x32_bf16 v[118:121], v[184:187], v[206:209], v[118:121]
	v_mfma_f32_16x16x32_bf16 v[118:121], v[180:183], v[202:205], v[118:121]
	s_barrier
	s_add_u32 s98, s26, 0xfff00080
	s_addc_u32 s99, s27, -1
	s_add_u32 s24, s24, 0x80
	s_addc_u32 s25, s25, 0
	s_add_i32 s26, s52, s30
	s_mov_b32 m0, s26
	ds_read_b128 v[202:205], v157 offset:49152
	ds_read_b128 v[206:209], v157 offset:50176
	ds_read_b128 v[210:213], v157 offset:51200
	ds_read_b128 v[214:217], v157 offset:52224
	ds_read_b128 v[218:221], v157 offset:53248
	ds_read_b128 v[222:225], v157 offset:54272
	ds_read_b128 v[226:229], v157 offset:55296
	ds_read_b128 v[230:233], v157 offset:56320
	global_load_lds_dwordx4 v132, s[24:25]
	s_add_i32 m0, s26, 0x2000
	s_add_i32 s26, s53, s30
	global_load_lds_dwordx4 v136, s[24:25]
	s_add_u32 s24, s24, 0x100000
	s_addc_u32 s25, s25, 0
	s_mov_b32 m0, s26
	s_nop 0
	global_load_lds_dwordx4 v132, s[24:25]
	s_add_i32 m0, s26, 0x2000
	s_nop 0
	global_load_lds_dwordx4 v136, s[24:25]
	s_mov_b32 m0, s38
	s_nop 0
	global_load_lds_dwordx4 v130, s[98:99]
	s_mov_b32 m0, s39
	s_nop 0
	global_load_lds_dwordx4 v134, s[98:99]
	s_waitcnt vmcnt(8)
	s_waitcnt lgkmcnt(0)
	s_barrier
	s_waitcnt lgkmcnt(0)
	v_mfma_f32_16x16x32_bf16 v[62:65], v[142:145], v[202:205], v[62:65]
	v_mfma_f32_16x16x32_bf16 v[62:65], v[158:161], v[206:209], v[62:65]
	v_mfma_f32_16x16x32_bf16 v[58:61], v[176:179], v[206:209], v[58:61]
	v_mfma_f32_16x16x32_bf16 v[58:61], v[168:171], v[202:205], v[58:61]
	v_mfma_f32_16x16x32_bf16 v[42:45], v[168:171], v[210:213], v[42:45]
	v_mfma_f32_16x16x32_bf16 v[42:45], v[176:179], v[214:217], v[42:45]
	v_mfma_f32_16x16x32_bf16 v[46:49], v[158:161], v[214:217], v[46:49]
	v_mfma_f32_16x16x32_bf16 v[46:49], v[142:145], v[210:213], v[46:49]
	v_mfma_f32_16x16x32_bf16 v[30:33], v[142:145], v[218:221], v[30:33]
	v_mfma_f32_16x16x32_bf16 v[30:33], v[158:161], v[222:225], v[30:33]
	v_mfma_f32_16x16x32_bf16 v[26:29], v[176:179], v[222:225], v[26:29]
	v_mfma_f32_16x16x32_bf16 v[26:29], v[168:171], v[218:221], v[26:29]
	v_mfma_f32_16x16x32_bf16 v[10:13], v[168:171], v[226:229], v[10:13]
	v_mfma_f32_16x16x32_bf16 v[10:13], v[176:179], v[230:233], v[10:13]
	v_mfma_f32_16x16x32_bf16 v[14:17], v[158:161], v[230:233], v[14:17]
	v_mfma_f32_16x16x32_bf16 v[14:17], v[142:145], v[226:229], v[14:17]
	v_mfma_f32_16x16x32_bf16 v[6:9], v[180:183], v[226:229], v[6:9]
	v_mfma_f32_16x16x32_bf16 v[6:9], v[184:187], v[230:233], v[6:9]
	v_mfma_f32_16x16x32_bf16 v[2:5], v[192:195], v[230:233], v[2:5]
	v_mfma_f32_16x16x32_bf16 v[2:5], v[188:191], v[226:229], v[2:5]
	v_mfma_f32_16x16x32_bf16 v[18:21], v[188:191], v[218:221], v[18:21]
	v_mfma_f32_16x16x32_bf16 v[18:21], v[192:195], v[222:225], v[18:21]
	v_mfma_f32_16x16x32_bf16 v[22:25], v[184:187], v[222:225], v[22:25]
	v_mfma_f32_16x16x32_bf16 v[22:25], v[180:183], v[218:221], v[22:25]
	v_mfma_f32_16x16x32_bf16 v[38:41], v[180:183], v[210:213], v[38:41]
	v_mfma_f32_16x16x32_bf16 v[38:41], v[184:187], v[214:217], v[38:41]
	v_mfma_f32_16x16x32_bf16 v[34:37], v[192:195], v[214:217], v[34:37]
	v_mfma_f32_16x16x32_bf16 v[34:37], v[188:191], v[210:213], v[34:37]
	v_mfma_f32_16x16x32_bf16 v[50:53], v[188:191], v[202:205], v[50:53]
	v_mfma_f32_16x16x32_bf16 v[50:53], v[192:195], v[206:209], v[50:53]
	v_mfma_f32_16x16x32_bf16 v[54:57], v[184:187], v[206:209], v[54:57]
	v_mfma_f32_16x16x32_bf16 v[54:57], v[180:183], v[202:205], v[54:57]
	s_barrier
	s_add_i32 s51, s51, 2
	s_add_u32 s22, s22, 0x100
	s_addc_u32 s23, s23, 0
	s_add_u32 s49, s49, 0x100
	s_addc_u32 s50, s50, 0
	s_cmp_gt_u32 s51, 61
	s_cbranch_scc0 .LBB0_1009
	s_and_b64 vcc, exec, s[16:17]
	s_cbranch_vccz .LBB0_1012
	s_barrier

.LBB0_1019:
	s_add_i32 s21, s20, 0x100
	s_and_b64 s[18:19], s[18:19], exec
	s_cselect_b32 s19, 0, s21
	s_cselect_b32 s18, 0, 0
	s_add_u32 s22, s8, s19
	s_addc_u32 s23, s9, s18
	ds_read_b128 v[144:147], v139
	ds_read_b128 v[150:153], v139 offset:1024
	ds_read_b128 v[154:157], v139 offset:2048
	ds_read_b128 v[158:161], v139 offset:3072
	ds_read_b128 v[168:171], v140
	ds_read_b128 v[176:179], v140 offset:1024
	ds_read_b128 v[180:183], v140 offset:2048
	ds_read_b128 v[184:187], v140 offset:3072
	s_add_u32 s24, s10, s19
	s_addc_u32 s25, s11, s18
	s_add_u32 s30, s12, s20
	s_addc_u32 s31, s13, 0
	s_add_u32 s26, s24, 0x100000
	s_addc_u32 s27, s25, 0
	s_add_u32 s20, s22, 0x100000
	s_addc_u32 s21, s23, 0
	s_add_u32 s18, s24, 0x100080
	s_addc_u32 s19, s25, 0
	v_lshl_add_u64 v[172:173], s[30:31], 0, v[130:131]
	s_mov_b32 m0, s40
	v_lshl_add_u64 v[172:173], v[172:173], 0, s[14:15]
	ds_read_b128 v[188:191], v141
	ds_read_b128 v[192:195], v141 offset:1024
	ds_read_b128 v[202:205], v141 offset:2048
	ds_read_b128 v[206:209], v141 offset:3072
	ds_read_b128 v[210:213], v141 offset:4096
	ds_read_b128 v[214:217], v141 offset:5120
	ds_read_b128 v[218:221], v141 offset:6144
	ds_read_b128 v[222:225], v141 offset:7168
	global_load_lds_dwordx4 v[172:173], off
	v_lshl_add_u64 v[172:173], s[30:31], 0, v[134:135]
	v_lshl_add_u64 v[172:173], v[172:173], 0, s[14:15]
	s_mov_b32 m0, s41
	s_nop 0
	global_load_lds_dwordx4 v[172:173], off
	s_waitcnt vmcnt(8)
	s_waitcnt lgkmcnt(0)
	s_barrier
	s_waitcnt lgkmcnt(0)
	v_mfma_f32_16x16x32_bf16 v[126:129], v[144:147], v[188:191], v[126:129]
	v_mfma_f32_16x16x32_bf16 v[126:129], v[150:153], v[192:195], v[126:129]
	v_mfma_f32_16x16x32_bf16 v[122:125], v[158:161], v[192:195], v[122:125]
	v_mfma_f32_16x16x32_bf16 v[122:125], v[154:157], v[188:191], v[122:125]
	v_mfma_f32_16x16x32_bf16 v[114:117], v[154:157], v[202:205], v[114:117]
	v_mfma_f32_16x16x32_bf16 v[114:117], v[158:161], v[206:209], v[114:117]
	v_mfma_f32_16x16x32_bf16 v[118:121], v[150:153], v[206:209], v[118:121]
	v_mfma_f32_16x16x32_bf16 v[118:121], v[144:147], v[202:205], v[118:121]
	v_mfma_f32_16x16x32_bf16 v[102:105], v[144:147], v[210:213], v[102:105]
	v_mfma_f32_16x16x32_bf16 v[102:105], v[150:153], v[214:217], v[102:105]
	v_mfma_f32_16x16x32_bf16 v[98:101], v[158:161], v[214:217], v[98:101]
	v_mfma_f32_16x16x32_bf16 v[98:101], v[154:157], v[210:213], v[98:101]
	v_mfma_f32_16x16x32_bf16 v[82:85], v[154:157], v[218:221], v[82:85]
	v_mfma_f32_16x16x32_bf16 v[82:85], v[158:161], v[222:225], v[82:85]
	v_mfma_f32_16x16x32_bf16 v[86:89], v[150:153], v[222:225], v[86:89]
	v_mfma_f32_16x16x32_bf16 v[86:89], v[144:147], v[218:221], v[86:89]
	v_mfma_f32_16x16x32_bf16 v[70:73], v[168:171], v[218:221], v[70:73]
	v_mfma_f32_16x16x32_bf16 v[70:73], v[176:179], v[222:225], v[70:73]
	v_mfma_f32_16x16x32_bf16 v[66:69], v[184:187], v[222:225], v[66:69]
	v_mfma_f32_16x16x32_bf16 v[66:69], v[180:183], v[218:221], v[66:69]
	v_mfma_f32_16x16x32_bf16 v[74:77], v[180:183], v[210:213], v[74:77]
	v_mfma_f32_16x16x32_bf16 v[74:77], v[184:187], v[214:217], v[74:77]
	v_mfma_f32_16x16x32_bf16 v[78:81], v[176:179], v[214:217], v[78:81]
	v_mfma_f32_16x16x32_bf16 v[78:81], v[168:171], v[210:213], v[78:81]
	v_mfma_f32_16x16x32_bf16 v[94:97], v[168:171], v[202:205], v[94:97]
	v_mfma_f32_16x16x32_bf16 v[94:97], v[176:179], v[206:209], v[94:97]
	v_mfma_f32_16x16x32_bf16 v[90:93], v[184:187], v[206:209], v[90:93]
	v_mfma_f32_16x16x32_bf16 v[90:93], v[180:183], v[202:205], v[90:93]
	v_mfma_f32_16x16x32_bf16 v[106:109], v[180:183], v[188:191], v[106:109]
	v_mfma_f32_16x16x32_bf16 v[106:109], v[184:187], v[192:195], v[106:109]
	v_mfma_f32_16x16x32_bf16 v[110:113], v[176:179], v[192:195], v[110:113]
	v_mfma_f32_16x16x32_bf16 v[110:113], v[168:171], v[188:191], v[110:113]
	s_barrier
	s_mov_b32 m0, s42
	v_lshl_add_u64 v[172:173], s[24:25], 0, v[132:133]
	ds_read_b128 v[188:191], v141 offset:16384
	ds_read_b128 v[192:195], v141 offset:17408
	ds_read_b128 v[202:205], v141 offset:18432
	ds_read_b128 v[206:209], v141 offset:19456
	ds_read_b128 v[210:213], v141 offset:20480
	ds_read_b128 v[214:217], v141 offset:21504
	ds_read_b128 v[218:221], v141 offset:22528
	ds_read_b128 v[222:225], v141 offset:23552
	global_load_lds_dwordx4 v[172:173], off
	v_lshl_add_u64 v[196:197], s[24:25], 0, v[136:137]
	s_mov_b32 m0, s43
	v_lshl_add_u64 v[226:227], s[26:27], 0, v[132:133]
	global_load_lds_dwordx4 v[196:197], off
	s_mov_b32 m0, s44
	v_lshl_add_u64 v[228:229], s[22:23], 0, v[134:135]
	global_load_lds_dwordx4 v[226:227], off
	v_lshl_add_u64 v[226:227], s[26:27], 0, v[136:137]
	s_mov_b32 m0, s45
	s_nop 0
	global_load_lds_dwordx4 v[226:227], off
	v_lshl_add_u64 v[226:227], s[22:23], 0, v[130:131]
	s_mov_b32 m0, s7
	s_nop 0
	global_load_lds_dwordx4 v[226:227], off
	s_mov_b32 m0, s34
	s_nop 0
	global_load_lds_dwordx4 v[228:229], off
	s_waitcnt vmcnt(8)
	s_waitcnt lgkmcnt(0)
	s_barrier
	s_waitcnt lgkmcnt(0)
	v_mfma_f32_16x16x32_bf16 v[62:65], v[144:147], v[188:191], v[62:65]
	v_mfma_f32_16x16x32_bf16 v[62:65], v[150:153], v[192:195], v[62:65]
	v_mfma_f32_16x16x32_bf16 v[58:61], v[158:161], v[192:195], v[58:61]
	v_mfma_f32_16x16x32_bf16 v[58:61], v[154:157], v[188:191], v[58:61]
	v_mfma_f32_16x16x32_bf16 v[50:53], v[154:157], v[202:205], v[50:53]
	v_mfma_f32_16x16x32_bf16 v[50:53], v[158:161], v[206:209], v[50:53]
	v_mfma_f32_16x16x32_bf16 v[54:57], v[150:153], v[206:209], v[54:57]
	v_mfma_f32_16x16x32_bf16 v[54:57], v[144:147], v[202:205], v[54:57]
	v_mfma_f32_16x16x32_bf16 v[38:41], v[144:147], v[210:213], v[38:41]
	v_mfma_f32_16x16x32_bf16 v[38:41], v[150:153], v[214:217], v[38:41]
	v_mfma_f32_16x16x32_bf16 v[34:37], v[158:161], v[214:217], v[34:37]
	v_mfma_f32_16x16x32_bf16 v[34:37], v[154:157], v[210:213], v[34:37]
	v_mfma_f32_16x16x32_bf16 v[18:21], v[154:157], v[218:221], v[18:21]
	v_mfma_f32_16x16x32_bf16 v[18:21], v[158:161], v[222:225], v[18:21]
	v_mfma_f32_16x16x32_bf16 v[22:25], v[150:153], v[222:225], v[22:25]
	v_mfma_f32_16x16x32_bf16 v[22:25], v[144:147], v[218:221], v[22:25]
	v_mfma_f32_16x16x32_bf16 v[6:9], v[168:171], v[218:221], v[6:9]
	v_mfma_f32_16x16x32_bf16 v[6:9], v[176:179], v[222:225], v[6:9]
	v_mfma_f32_16x16x32_bf16 v[2:5], v[184:187], v[222:225], v[2:5]
	v_mfma_f32_16x16x32_bf16 v[2:5], v[180:183], v[218:221], v[2:5]
	v_mfma_f32_16x16x32_bf16 v[10:13], v[180:183], v[210:213], v[10:13]
	v_mfma_f32_16x16x32_bf16 v[10:13], v[184:187], v[214:217], v[10:13]
	v_mfma_f32_16x16x32_bf16 v[14:17], v[176:179], v[214:217], v[14:17]
	v_mfma_f32_16x16x32_bf16 v[14:17], v[168:171], v[210:213], v[14:17]
	v_mfma_f32_16x16x32_bf16 v[30:33], v[168:171], v[202:205], v[30:33]
	v_mfma_f32_16x16x32_bf16 v[30:33], v[176:179], v[206:209], v[30:33]
	v_mfma_f32_16x16x32_bf16 v[26:29], v[184:187], v[206:209], v[26:29]
	v_mfma_f32_16x16x32_bf16 v[26:29], v[180:183], v[202:205], v[26:29]
	v_mfma_f32_16x16x32_bf16 v[42:45], v[180:183], v[188:191], v[42:45]
	v_mfma_f32_16x16x32_bf16 v[42:45], v[184:187], v[192:195], v[42:45]
	v_mfma_f32_16x16x32_bf16 v[46:49], v[176:179], v[192:195], v[46:49]
	v_mfma_f32_16x16x32_bf16 v[46:49], v[168:171], v[188:191], v[46:49]
	s_barrier
	ds_read_b128 v[144:147], v142
	ds_read_b128 v[150:153], v142 offset:1024
	ds_read_b128 v[154:157], v142 offset:2048
	ds_read_b128 v[158:161], v142 offset:3072
	ds_read_b128 v[168:171], v143
	ds_read_b128 v[176:179], v143 offset:1024
	ds_read_b128 v[180:183], v143 offset:2048
	ds_read_b128 v[184:187], v143 offset:3072
	s_mov_b32 m0, s35
	v_lshl_add_u64 v[230:231], s[20:21], 0, v[130:131]
	ds_read_b128 v[188:191], v141 offset:32768
	ds_read_b128 v[192:195], v141 offset:33792
	ds_read_b128 v[202:205], v141 offset:34816
	ds_read_b128 v[206:209], v141 offset:35840
	ds_read_b128 v[210:213], v141 offset:36864
	ds_read_b128 v[214:217], v141 offset:37888
	ds_read_b128 v[218:221], v141 offset:38912
	ds_read_b128 v[222:225], v141 offset:39936
	global_load_lds_dwordx4 v[230:231], off
	v_lshl_add_u64 v[230:231], s[20:21], 0, v[134:135]
	s_mov_b32 m0, s36
	s_nop 0
	global_load_lds_dwordx4 v[230:231], off
	s_waitcnt vmcnt(8)
	s_waitcnt lgkmcnt(0)
	s_barrier
	s_waitcnt lgkmcnt(0)
	v_mfma_f32_16x16x32_bf16 v[126:129], v[144:147], v[188:191], v[126:129]
	v_mfma_f32_16x16x32_bf16 v[126:129], v[150:153], v[192:195], v[126:129]
	v_mfma_f32_16x16x32_bf16 v[122:125], v[158:161], v[192:195], v[122:125]
	v_mfma_f32_16x16x32_bf16 v[122:125], v[154:157], v[188:191], v[122:125]
	v_mfma_f32_16x16x32_bf16 v[114:117], v[154:157], v[202:205], v[114:117]
	v_mfma_f32_16x16x32_bf16 v[114:117], v[158:161], v[206:209], v[114:117]
	v_mfma_f32_16x16x32_bf16 v[118:121], v[150:153], v[206:209], v[118:121]
	v_mfma_f32_16x16x32_bf16 v[118:121], v[144:147], v[202:205], v[118:121]
	v_mfma_f32_16x16x32_bf16 v[102:105], v[144:147], v[210:213], v[102:105]
	v_mfma_f32_16x16x32_bf16 v[102:105], v[150:153], v[214:217], v[102:105]
	v_mfma_f32_16x16x32_bf16 v[98:101], v[158:161], v[214:217], v[98:101]
	v_mfma_f32_16x16x32_bf16 v[98:101], v[154:157], v[210:213], v[98:101]
	v_mfma_f32_16x16x32_bf16 v[82:85], v[154:157], v[218:221], v[82:85]
	v_mfma_f32_16x16x32_bf16 v[82:85], v[158:161], v[222:225], v[82:85]
	v_mfma_f32_16x16x32_bf16 v[86:89], v[150:153], v[222:225], v[86:89]
	v_mfma_f32_16x16x32_bf16 v[86:89], v[144:147], v[218:221], v[86:89]
	v_mfma_f32_16x16x32_bf16 v[70:73], v[168:171], v[218:221], v[70:73]
	v_mfma_f32_16x16x32_bf16 v[70:73], v[176:179], v[222:225], v[70:73]
	v_mfma_f32_16x16x32_bf16 v[66:69], v[184:187], v[222:225], v[66:69]
	v_mfma_f32_16x16x32_bf16 v[66:69], v[180:183], v[218:221], v[66:69]
	v_mfma_f32_16x16x32_bf16 v[74:77], v[180:183], v[210:213], v[74:77]
	v_mfma_f32_16x16x32_bf16 v[74:77], v[184:187], v[214:217], v[74:77]
	v_mfma_f32_16x16x32_bf16 v[78:81], v[176:179], v[214:217], v[78:81]
	v_mfma_f32_16x16x32_bf16 v[78:81], v[168:171], v[210:213], v[78:81]
	v_mfma_f32_16x16x32_bf16 v[94:97], v[168:171], v[202:205], v[94:97]
	v_mfma_f32_16x16x32_bf16 v[94:97], v[176:179], v[206:209], v[94:97]
	v_mfma_f32_16x16x32_bf16 v[90:93], v[184:187], v[206:209], v[90:93]
	v_mfma_f32_16x16x32_bf16 v[90:93], v[180:183], v[202:205], v[90:93]
	v_mfma_f32_16x16x32_bf16 v[106:109], v[180:183], v[188:191], v[106:109]
	v_mfma_f32_16x16x32_bf16 v[106:109], v[184:187], v[192:195], v[106:109]
	v_mfma_f32_16x16x32_bf16 v[110:113], v[176:179], v[192:195], v[110:113]
	v_mfma_f32_16x16x32_bf16 v[110:113], v[168:171], v[188:191], v[110:113]
	s_barrier
	s_mov_b32 m0, s46
	v_lshl_add_u64 v[172:173], v[172:173], 0, s[14:15]
	ds_read_b128 v[188:191], v141 offset:49152
	ds_read_b128 v[192:195], v141 offset:50176
	ds_read_b128 v[202:205], v141 offset:51200
	ds_read_b128 v[206:209], v141 offset:52224
	ds_read_b128 v[210:213], v141 offset:53248
	ds_read_b128 v[214:217], v141 offset:54272
	ds_read_b128 v[218:221], v141 offset:55296
	ds_read_b128 v[222:225], v141 offset:56320
	global_load_lds_dwordx4 v[172:173], off
	v_lshl_add_u64 v[172:173], v[196:197], 0, s[14:15]
	s_mov_b32 m0, s47
	s_nop 0
	global_load_lds_dwordx4 v[172:173], off
	v_lshl_add_u64 v[172:173], s[18:19], 0, v[132:133]
	s_mov_b32 m0, s48
	s_nop 0
	global_load_lds_dwordx4 v[172:173], off
	v_lshl_add_u64 v[172:173], s[18:19], 0, v[136:137]
	s_mov_b32 m0, s49
	s_nop 0
	global_load_lds_dwordx4 v[172:173], off
	v_lshl_add_u64 v[172:173], v[226:227], 0, s[14:15]
	s_mov_b32 m0, s38
	s_nop 0
	global_load_lds_dwordx4 v[172:173], off
	v_lshl_add_u64 v[172:173], v[228:229], 0, s[14:15]
	s_mov_b32 m0, s39
	s_nop 0
	global_load_lds_dwordx4 v[172:173], off
	s_waitcnt vmcnt(8)
	s_waitcnt lgkmcnt(0)
	s_barrier
	s_waitcnt lgkmcnt(0)
	v_mfma_f32_16x16x32_bf16 v[62:65], v[144:147], v[188:191], v[62:65]
	v_mfma_f32_16x16x32_bf16 v[62:65], v[150:153], v[192:195], v[62:65]
	v_mfma_f32_16x16x32_bf16 v[58:61], v[158:161], v[192:195], v[58:61]
	v_mfma_f32_16x16x32_bf16 v[58:61], v[154:157], v[188:191], v[58:61]
	v_mfma_f32_16x16x32_bf16 v[50:53], v[154:157], v[202:205], v[50:53]
	v_mfma_f32_16x16x32_bf16 v[50:53], v[158:161], v[206:209], v[50:53]
	v_mfma_f32_16x16x32_bf16 v[54:57], v[150:153], v[206:209], v[54:57]
	v_mfma_f32_16x16x32_bf16 v[54:57], v[144:147], v[202:205], v[54:57]
	v_mfma_f32_16x16x32_bf16 v[38:41], v[144:147], v[210:213], v[38:41]
	v_mfma_f32_16x16x32_bf16 v[38:41], v[150:153], v[214:217], v[38:41]
	v_mfma_f32_16x16x32_bf16 v[34:37], v[158:161], v[214:217], v[34:37]
	v_mfma_f32_16x16x32_bf16 v[34:37], v[154:157], v[210:213], v[34:37]
	v_mfma_f32_16x16x32_bf16 v[18:21], v[154:157], v[218:221], v[18:21]
	v_mfma_f32_16x16x32_bf16 v[18:21], v[158:161], v[222:225], v[18:21]
	v_mfma_f32_16x16x32_bf16 v[22:25], v[150:153], v[222:225], v[22:25]
	v_mfma_f32_16x16x32_bf16 v[22:25], v[144:147], v[218:221], v[22:25]
	v_mfma_f32_16x16x32_bf16 v[6:9], v[168:171], v[218:221], v[6:9]
	v_mfma_f32_16x16x32_bf16 v[6:9], v[176:179], v[222:225], v[6:9]
	v_mfma_f32_16x16x32_bf16 v[2:5], v[184:187], v[222:225], v[2:5]
	v_mfma_f32_16x16x32_bf16 v[2:5], v[180:183], v[218:221], v[2:5]
	v_mfma_f32_16x16x32_bf16 v[10:13], v[180:183], v[210:213], v[10:13]
	v_mfma_f32_16x16x32_bf16 v[10:13], v[184:187], v[214:217], v[10:13]
	v_mfma_f32_16x16x32_bf16 v[14:17], v[176:179], v[214:217], v[14:17]
	v_mfma_f32_16x16x32_bf16 v[14:17], v[168:171], v[210:213], v[14:17]
	v_mfma_f32_16x16x32_bf16 v[30:33], v[168:171], v[202:205], v[30:33]
	v_mfma_f32_16x16x32_bf16 v[30:33], v[176:179], v[206:209], v[30:33]
	v_mfma_f32_16x16x32_bf16 v[26:29], v[184:187], v[206:209], v[26:29]
	v_mfma_f32_16x16x32_bf16 v[26:29], v[180:183], v[202:205], v[26:29]
	v_mfma_f32_16x16x32_bf16 v[42:45], v[180:183], v[188:191], v[42:45]
	v_mfma_f32_16x16x32_bf16 v[42:45], v[184:187], v[192:195], v[42:45]
	v_mfma_f32_16x16x32_bf16 v[46:49], v[176:179], v[192:195], v[46:49]
	v_mfma_f32_16x16x32_bf16 v[46:49], v[168:171], v[188:191], v[46:49]
	s_barrier
	s_andn2_b64 vcc, exec, s[16:17]
	s_mov_b64 s[18:19], -1
	s_mov_b64 s[16:17], 0
	s_movk_i32 s20, 0x100
	s_cbranch_vccz .LBB0_1019
	s_lshl_b32 s7, s33, 21
	v_readlane_b32 s0, v249, 29
	v_lshl_or_b32 v130, s6, 8, v148
	v_mov_b32_e32 v139, 0
	s_add_u32 s8, s0, s7
	v_readlane_b32 s0, v249, 31
	v_or_b32_e32 v130, s37, v130
	v_cvt_pk_bf16_f32 v70, v70, v71
	v_cvt_pk_bf16_f32 v71, v72, v73
	v_cvt_pk_bf16_f32 v72, v66, v67
	v_add_u32_e32 v66, 0x80, v138
	v_mov_b32_e32 v67, v139
	s_addc_u32 s9, s0, 0
	v_ashrrev_i32_e32 v131, 31, v130
	v_lshlrev_b64 v[132:133], 13, v[138:139]
	v_cvt_pk_bf16_f32 v110, v110, v111
	v_cvt_pk_bf16_f32 v111, v112, v113
	v_cvt_pk_bf16_f32 v112, v106, v107
	v_or_b32_e32 v106, 16, v138
	v_mov_b32_e32 v107, v139
	v_lshlrev_b64 v[66:67], 13, v[66:67]
	v_cvt_pk_bf16_f32 v46, v46, v47
	v_cvt_pk_bf16_f32 v47, v48, v49
	v_cvt_pk_bf16_f32 v48, v42, v43
	v_add_u32_e32 v42, 0x90, v138
	v_mov_b32_e32 v43, v139
	v_lshl_add_u64 v[132:133], s[8:9], 0, v[132:133]
	v_lshlrev_b64 v[130:131], 1, v[130:131]
	v_lshlrev_b64 v[106:107], 13, v[106:107]
	v_cvt_pk_bf16_f32 v94, v94, v95
	v_cvt_pk_bf16_f32 v95, v96, v97
	v_cvt_pk_bf16_f32 v96, v90, v91
	v_or_b32_e32 v90, 32, v138
	v_mov_b32_e32 v91, v139
	v_lshl_add_u64 v[66:67], s[8:9], 0, v[66:67]
	v_lshlrev_b64 v[42:43], 13, v[42:43]
	v_cvt_pk_bf16_f32 v30, v30, v31
	v_cvt_pk_bf16_f32 v31, v32, v33
	v_cvt_pk_bf16_f32 v32, v26, v27
	v_add_u32_e32 v26, 0xa0, v138
	v_mov_b32_e32 v27, v139
	v_lshl_add_u64 v[132:133], v[132:133], 0, v[130:131]
	v_cvt_pk_bf16_f32 v113, v108, v109
	v_lshl_add_u64 v[106:107], s[8:9], 0, v[106:107]
	v_lshlrev_b64 v[90:91], 13, v[90:91]
	v_cvt_pk_bf16_f32 v78, v78, v79
	v_cvt_pk_bf16_f32 v79, v80, v81
	v_cvt_pk_bf16_f32 v80, v74, v75
	v_or_b32_e32 v74, 48, v138
	v_mov_b32_e32 v75, v139
	v_lshl_add_u64 v[66:67], v[66:67], 0, v[130:131]
	v_cvt_pk_bf16_f32 v49, v44, v45
	v_lshl_add_u64 v[42:43], s[8:9], 0, v[42:43]
	v_lshlrev_b64 v[26:27], 13, v[26:27]
	v_add_u32_e32 v138, 0xb0, v138
	global_store_dwordx4 v[132:133], v[110:113], off offset:256
	v_cvt_pk_bf16_f32 v97, v92, v93
	v_lshl_add_u64 v[90:91], s[8:9], 0, v[90:91]
	v_lshl_add_u64 v[110:111], v[106:107], 0, v[130:131]
	v_lshlrev_b64 v[74:75], 13, v[74:75]
	global_store_dwordx4 v[66:67], v[46:49], off offset:256
	v_cvt_pk_bf16_f32 v33, v28, v29
	v_lshl_add_u64 v[26:27], s[8:9], 0, v[26:27]
	v_lshl_add_u64 v[46:47], v[42:43], 0, v[130:131]
	v_cvt_pk_bf16_f32 v14, v14, v15
	v_cvt_pk_bf16_f32 v15, v16, v17
	v_cvt_pk_bf16_f32 v16, v10, v11
	v_lshlrev_b64 v[10:11], 13, v[138:139]
	global_store_dwordx4 v[110:111], v[94:97], off offset:256
	v_cvt_pk_bf16_f32 v81, v76, v77
	v_lshl_add_u64 v[74:75], s[8:9], 0, v[74:75]
	v_lshl_add_u64 v[94:95], v[90:91], 0, v[130:131]
	global_store_dwordx4 v[46:47], v[30:33], off offset:256
	v_cvt_pk_bf16_f32 v17, v12, v13
	v_lshl_add_u64 v[10:11], s[8:9], 0, v[10:11]
	v_lshl_add_u64 v[30:31], v[26:27], 0, v[130:131]
	v_cvt_pk_bf16_f32 v126, v126, v127
	v_cvt_pk_bf16_f32 v127, v128, v129
	v_cvt_pk_bf16_f32 v128, v122, v123
	v_cvt_pk_bf16_f32 v129, v124, v125
	v_cvt_pk_bf16_f32 v106, v118, v119
	v_cvt_pk_bf16_f32 v107, v120, v121
	v_cvt_pk_bf16_f32 v108, v114, v115
	v_cvt_pk_bf16_f32 v109, v116, v117
	v_cvt_pk_bf16_f32 v90, v102, v103
	v_cvt_pk_bf16_f32 v91, v104, v105
	v_cvt_pk_bf16_f32 v92, v98, v99
	v_cvt_pk_bf16_f32 v93, v100, v101
	global_store_dwordx4 v[94:95], v[78:81], off offset:256
	v_cvt_pk_bf16_f32 v76, v82, v83
	v_cvt_pk_bf16_f32 v77, v84, v85
	v_lshl_add_u64 v[78:79], v[74:75], 0, v[130:131]
	v_cvt_pk_bf16_f32 v74, v86, v87
	v_cvt_pk_bf16_f32 v75, v88, v89
	v_cvt_pk_bf16_f32 v73, v68, v69
	v_cvt_pk_bf16_f32 v62, v62, v63
	v_cvt_pk_bf16_f32 v63, v64, v65
	v_cvt_pk_bf16_f32 v64, v58, v59
	v_cvt_pk_bf16_f32 v65, v60, v61
	v_cvt_pk_bf16_f32 v42, v54, v55
	v_cvt_pk_bf16_f32 v43, v56, v57
	v_cvt_pk_bf16_f32 v44, v50, v51
	v_cvt_pk_bf16_f32 v45, v52, v53
	v_cvt_pk_bf16_f32 v26, v38, v39
	v_cvt_pk_bf16_f32 v27, v40, v41
	v_cvt_pk_bf16_f32 v28, v34, v35
	v_cvt_pk_bf16_f32 v29, v36, v37
	global_store_dwordx4 v[30:31], v[14:17], off offset:256
	v_cvt_pk_bf16_f32 v12, v18, v19
	v_cvt_pk_bf16_f32 v13, v20, v21
	v_lshl_add_u64 v[14:15], v[10:11], 0, v[130:131]
	v_cvt_pk_bf16_f32 v10, v22, v23
	v_cvt_pk_bf16_f32 v11, v24, v25
	v_cvt_pk_bf16_f32 v6, v6, v7
	v_cvt_pk_bf16_f32 v7, v8, v9
	v_cvt_pk_bf16_f32 v8, v2, v3
	v_cvt_pk_bf16_f32 v9, v4, v5
	global_store_dwordx4 v[132:133], v[126:129], off
	global_store_dwordx4 v[110:111], v[106:109], off
	global_store_dwordx4 v[94:95], v[90:93], off
	global_store_dwordx4 v[78:79], v[74:77], off
	global_store_dwordx4 v[78:79], v[70:73], off offset:256
	global_store_dwordx4 v[66:67], v[62:65], off
	global_store_dwordx4 v[46:47], v[42:45], off
	global_store_dwordx4 v[30:31], v[26:29], off
	global_store_dwordx4 v[14:15], v[10:13], off
	global_store_dwordx4 v[14:15], v[6:9], off offset:256
	s_waitcnt vmcnt(0)
	s_cmpk_lt_u32 s3, 0x100
	s_cbranch_scc0 .LBB0_1022
	s_barrier

.LBB0_1172:
	s_add_u32 s62, s20, 0xfff00000
	s_addc_u32 s63, s21, -1
	s_mov_b32 m0, s37
	ds_read_b128 v[142:145], v148
	global_load_lds_dwordx4 v130, s[62:63]
	s_mov_b32 m0, s38
	ds_read_b128 v[154:157], v148 offset:1024
	global_load_lds_dwordx4 v134, s[62:63]
	s_mov_b32 m0, s42
	ds_read_b128 v[158:161], v148 offset:2048
	global_load_lds_dwordx4 v138, s[20:21]
	s_mov_b32 m0, s43
	ds_read_b128 v[168:171], v148 offset:3072
	global_load_lds_dwordx4 v140, s[20:21]
	ds_read_b128 v[176:179], v149
	ds_read_b128 v[180:183], v149 offset:1024
	ds_read_b128 v[184:187], v149 offset:2048
	ds_read_b128 v[188:191], v149 offset:3072
	s_add_u32 s22, s20, 0xfff00080
	s_addc_u32 s23, s21, -1
	s_cmp_eq_u32 s61, 60
	s_cselect_b32 s25, s54, s23
	s_cselect_b32 s24, s55, s22
	s_cselect_b32 s23, s7, s60
	s_cselect_b32 s22, s56, s57
	ds_read_b128 v[192:195], v150
	ds_read_b128 v[202:205], v150 offset:1024
	ds_read_b128 v[206:209], v150 offset:2048
	ds_read_b128 v[210:213], v150 offset:3072
	ds_read_b128 v[214:217], v150 offset:4096
	ds_read_b128 v[218:221], v150 offset:5120
	ds_read_b128 v[222:225], v150 offset:6144
	ds_read_b128 v[226:229], v150 offset:7168
	s_waitcnt vmcnt(8)
	s_waitcnt lgkmcnt(0)
	s_barrier
	s_waitcnt lgkmcnt(0)
	v_mfma_f32_16x16x32_bf16 v[126:129], v[142:145], v[192:195], v[126:129]
	v_mfma_f32_16x16x32_bf16 v[126:129], v[154:157], v[202:205], v[126:129]
	v_mfma_f32_16x16x32_bf16 v[118:121], v[168:171], v[202:205], v[118:121]
	v_mfma_f32_16x16x32_bf16 v[118:121], v[158:161], v[192:195], v[118:121]
	v_mfma_f32_16x16x32_bf16 v[102:105], v[158:161], v[206:209], v[102:105]
	v_mfma_f32_16x16x32_bf16 v[102:105], v[168:171], v[210:213], v[102:105]
	v_mfma_f32_16x16x32_bf16 v[110:113], v[154:157], v[210:213], v[110:113]
	v_mfma_f32_16x16x32_bf16 v[110:113], v[142:145], v[206:209], v[110:113]
	v_mfma_f32_16x16x32_bf16 v[94:97], v[142:145], v[214:217], v[94:97]
	v_mfma_f32_16x16x32_bf16 v[94:97], v[154:157], v[218:221], v[94:97]
	v_mfma_f32_16x16x32_bf16 v[86:89], v[168:171], v[218:221], v[86:89]
	v_mfma_f32_16x16x32_bf16 v[86:89], v[158:161], v[214:217], v[86:89]
	v_mfma_f32_16x16x32_bf16 v[70:73], v[158:161], v[222:225], v[70:73]
	v_mfma_f32_16x16x32_bf16 v[70:73], v[168:171], v[226:229], v[70:73]
	v_mfma_f32_16x16x32_bf16 v[78:81], v[154:157], v[226:229], v[78:81]
	v_mfma_f32_16x16x32_bf16 v[78:81], v[142:145], v[222:225], v[78:81]
	v_mfma_f32_16x16x32_bf16 v[74:77], v[176:179], v[222:225], v[74:77]
	v_mfma_f32_16x16x32_bf16 v[74:77], v[180:183], v[226:229], v[74:77]
	v_mfma_f32_16x16x32_bf16 v[66:69], v[188:191], v[226:229], v[66:69]
	v_mfma_f32_16x16x32_bf16 v[66:69], v[184:187], v[222:225], v[66:69]
	v_mfma_f32_16x16x32_bf16 v[82:85], v[184:187], v[214:217], v[82:85]
	v_mfma_f32_16x16x32_bf16 v[82:85], v[188:191], v[218:221], v[82:85]
	v_mfma_f32_16x16x32_bf16 v[90:93], v[180:183], v[218:221], v[90:93]
	v_mfma_f32_16x16x32_bf16 v[90:93], v[176:179], v[214:217], v[90:93]
	v_mfma_f32_16x16x32_bf16 v[106:109], v[176:179], v[206:209], v[106:109]
	v_mfma_f32_16x16x32_bf16 v[106:109], v[180:183], v[210:213], v[106:109]
	v_mfma_f32_16x16x32_bf16 v[98:101], v[188:191], v[210:213], v[98:101]
	v_mfma_f32_16x16x32_bf16 v[98:101], v[184:187], v[206:209], v[98:101]
	v_mfma_f32_16x16x32_bf16 v[114:117], v[184:187], v[192:195], v[114:117]
	v_mfma_f32_16x16x32_bf16 v[114:117], v[188:191], v[202:205], v[114:117]
	v_mfma_f32_16x16x32_bf16 v[122:125], v[180:183], v[202:205], v[122:125]
	v_mfma_f32_16x16x32_bf16 v[122:125], v[176:179], v[192:195], v[122:125]
	s_barrier
	s_mov_b32 m0, s44
	s_add_u32 s62, s22, 0x100000
	global_load_lds_dwordx4 v132, s[22:23]
	s_mov_b32 m0, s45
	s_addc_u32 s63, s23, 0
	global_load_lds_dwordx4 v136, s[22:23]
	s_mov_b32 m0, s46
	ds_read_b128 v[192:195], v150 offset:16384
	global_load_lds_dwordx4 v132, s[62:63]
	s_mov_b32 m0, s47
	ds_read_b128 v[202:205], v150 offset:17408
	global_load_lds_dwordx4 v136, s[62:63]
	ds_read_b128 v[206:209], v150 offset:18432
	ds_read_b128 v[210:213], v150 offset:19456
	ds_read_b128 v[214:217], v150 offset:20480
	ds_read_b128 v[218:221], v150 offset:21504
	ds_read_b128 v[222:225], v150 offset:22528
	ds_read_b128 v[226:229], v150 offset:23552
	s_waitcnt vmcnt(6)
	s_waitcnt lgkmcnt(0)
	s_barrier
	s_waitcnt lgkmcnt(0)
	v_mfma_f32_16x16x32_bf16 v[62:65], v[142:145], v[192:195], v[62:65]
	v_mfma_f32_16x16x32_bf16 v[62:65], v[154:157], v[202:205], v[62:65]
	v_mfma_f32_16x16x32_bf16 v[54:57], v[168:171], v[202:205], v[54:57]
	v_mfma_f32_16x16x32_bf16 v[54:57], v[158:161], v[192:195], v[54:57]
	v_mfma_f32_16x16x32_bf16 v[38:41], v[158:161], v[206:209], v[38:41]
	v_mfma_f32_16x16x32_bf16 v[38:41], v[168:171], v[210:213], v[38:41]
	v_mfma_f32_16x16x32_bf16 v[46:49], v[154:157], v[210:213], v[46:49]
	v_mfma_f32_16x16x32_bf16 v[46:49], v[142:145], v[206:209], v[46:49]
	v_mfma_f32_16x16x32_bf16 v[30:33], v[142:145], v[214:217], v[30:33]
	v_mfma_f32_16x16x32_bf16 v[30:33], v[154:157], v[218:221], v[30:33]
	v_mfma_f32_16x16x32_bf16 v[22:25], v[168:171], v[218:221], v[22:25]
	v_mfma_f32_16x16x32_bf16 v[22:25], v[158:161], v[214:217], v[22:25]
	v_mfma_f32_16x16x32_bf16 v[6:9], v[158:161], v[222:225], v[6:9]
	v_mfma_f32_16x16x32_bf16 v[6:9], v[168:171], v[226:229], v[6:9]
	v_mfma_f32_16x16x32_bf16 v[14:17], v[154:157], v[226:229], v[14:17]
	v_mfma_f32_16x16x32_bf16 v[14:17], v[142:145], v[222:225], v[14:17]
	v_mfma_f32_16x16x32_bf16 v[10:13], v[176:179], v[222:225], v[10:13]
	v_mfma_f32_16x16x32_bf16 v[10:13], v[180:183], v[226:229], v[10:13]
	v_mfma_f32_16x16x32_bf16 v[2:5], v[188:191], v[226:229], v[2:5]
	v_mfma_f32_16x16x32_bf16 v[2:5], v[184:187], v[222:225], v[2:5]
	v_mfma_f32_16x16x32_bf16 v[18:21], v[184:187], v[214:217], v[18:21]
	v_mfma_f32_16x16x32_bf16 v[18:21], v[188:191], v[218:221], v[18:21]
	v_mfma_f32_16x16x32_bf16 v[26:29], v[180:183], v[218:221], v[26:29]
	v_mfma_f32_16x16x32_bf16 v[26:29], v[176:179], v[214:217], v[26:29]
	v_mfma_f32_16x16x32_bf16 v[42:45], v[176:179], v[206:209], v[42:45]
	v_mfma_f32_16x16x32_bf16 v[42:45], v[180:183], v[210:213], v[42:45]
	v_mfma_f32_16x16x32_bf16 v[34:37], v[188:191], v[210:213], v[34:37]
	v_mfma_f32_16x16x32_bf16 v[34:37], v[184:187], v[206:209], v[34:37]
	v_mfma_f32_16x16x32_bf16 v[50:53], v[184:187], v[192:195], v[50:53]
	v_mfma_f32_16x16x32_bf16 v[50:53], v[188:191], v[202:205], v[50:53]
	v_mfma_f32_16x16x32_bf16 v[58:61], v[180:183], v[202:205], v[58:61]
	v_mfma_f32_16x16x32_bf16 v[58:61], v[176:179], v[192:195], v[58:61]
	s_barrier
	s_mov_b32 m0, s31
	ds_read_b128 v[142:145], v151
	global_load_lds_dwordx4 v130, s[24:25]
	s_mov_b32 m0, s33
	ds_read_b128 v[154:157], v151 offset:1024
	global_load_lds_dwordx4 v134, s[24:25]
	s_add_u32 s24, s24, 0x100000
	s_addc_u32 s25, s25, 0
	s_mov_b32 m0, s34
	ds_read_b128 v[158:161], v151 offset:2048
	global_load_lds_dwordx4 v130, s[24:25]
	s_mov_b32 m0, s35
	ds_read_b128 v[168:171], v151 offset:3072
	global_load_lds_dwordx4 v134, s[24:25]
	ds_read_b128 v[176:179], v152
	ds_read_b128 v[180:183], v152 offset:1024
	ds_read_b128 v[184:187], v152 offset:2048
	ds_read_b128 v[188:191], v152 offset:3072
	ds_read_b128 v[192:195], v150 offset:32768
	ds_read_b128 v[202:205], v150 offset:33792
	ds_read_b128 v[206:209], v150 offset:34816
	ds_read_b128 v[210:213], v150 offset:35840
	ds_read_b128 v[214:217], v150 offset:36864
	ds_read_b128 v[218:221], v150 offset:37888
	ds_read_b128 v[222:225], v150 offset:38912
	ds_read_b128 v[226:229], v150 offset:39936
	s_waitcnt vmcnt(8)
	s_waitcnt lgkmcnt(0)
	s_barrier
	s_waitcnt lgkmcnt(0)
	v_mfma_f32_16x16x32_bf16 v[126:129], v[142:145], v[192:195], v[126:129]
	v_mfma_f32_16x16x32_bf16 v[126:129], v[154:157], v[202:205], v[126:129]
	v_mfma_f32_16x16x32_bf16 v[118:121], v[168:171], v[202:205], v[118:121]
	v_mfma_f32_16x16x32_bf16 v[118:121], v[158:161], v[192:195], v[118:121]
	v_mfma_f32_16x16x32_bf16 v[102:105], v[158:161], v[206:209], v[102:105]
	v_mfma_f32_16x16x32_bf16 v[102:105], v[168:171], v[210:213], v[102:105]
	v_mfma_f32_16x16x32_bf16 v[110:113], v[154:157], v[210:213], v[110:113]
	v_mfma_f32_16x16x32_bf16 v[110:113], v[142:145], v[206:209], v[110:113]
	v_mfma_f32_16x16x32_bf16 v[94:97], v[142:145], v[214:217], v[94:97]
	v_mfma_f32_16x16x32_bf16 v[94:97], v[154:157], v[218:221], v[94:97]
	v_mfma_f32_16x16x32_bf16 v[86:89], v[168:171], v[218:221], v[86:89]
	v_mfma_f32_16x16x32_bf16 v[86:89], v[158:161], v[214:217], v[86:89]
	v_mfma_f32_16x16x32_bf16 v[70:73], v[158:161], v[222:225], v[70:73]
	v_mfma_f32_16x16x32_bf16 v[70:73], v[168:171], v[226:229], v[70:73]
	v_mfma_f32_16x16x32_bf16 v[78:81], v[154:157], v[226:229], v[78:81]
	v_mfma_f32_16x16x32_bf16 v[78:81], v[142:145], v[222:225], v[78:81]
	v_mfma_f32_16x16x32_bf16 v[74:77], v[176:179], v[222:225], v[74:77]
	v_mfma_f32_16x16x32_bf16 v[74:77], v[180:183], v[226:229], v[74:77]
	v_mfma_f32_16x16x32_bf16 v[66:69], v[188:191], v[226:229], v[66:69]
	v_mfma_f32_16x16x32_bf16 v[66:69], v[184:187], v[222:225], v[66:69]
	v_mfma_f32_16x16x32_bf16 v[82:85], v[184:187], v[214:217], v[82:85]
	v_mfma_f32_16x16x32_bf16 v[82:85], v[188:191], v[218:221], v[82:85]
	v_mfma_f32_16x16x32_bf16 v[90:93], v[180:183], v[218:221], v[90:93]
	v_mfma_f32_16x16x32_bf16 v[90:93], v[176:179], v[214:217], v[90:93]
	v_mfma_f32_16x16x32_bf16 v[106:109], v[176:179], v[206:209], v[106:109]
	v_mfma_f32_16x16x32_bf16 v[106:109], v[180:183], v[210:213], v[106:109]
	v_mfma_f32_16x16x32_bf16 v[98:101], v[188:191], v[210:213], v[98:101]
	v_mfma_f32_16x16x32_bf16 v[98:101], v[184:187], v[206:209], v[98:101]
	v_mfma_f32_16x16x32_bf16 v[114:117], v[184:187], v[192:195], v[114:117]
	v_mfma_f32_16x16x32_bf16 v[114:117], v[188:191], v[202:205], v[114:117]
	v_mfma_f32_16x16x32_bf16 v[122:125], v[180:183], v[202:205], v[122:125]
	v_mfma_f32_16x16x32_bf16 v[122:125], v[176:179], v[192:195], v[122:125]
	s_barrier
	s_mov_b32 m0, s48
	s_add_u32 s22, s22, 0x80
	s_addc_u32 s23, s23, 0
	global_load_lds_dwordx4 v132, s[22:23]
	s_mov_b32 m0, s49
	ds_read_b128 v[192:195], v150 offset:49152
	global_load_lds_dwordx4 v136, s[22:23]
	s_mov_b32 m0, s50
	s_add_u32 s22, s22, 0x100000
	s_addc_u32 s23, s23, 0
	global_load_lds_dwordx4 v132, s[22:23]
	s_mov_b32 m0, s51
	ds_read_b128 v[202:205], v150 offset:50176
	global_load_lds_dwordx4 v136, s[22:23]
	ds_read_b128 v[206:209], v150 offset:51200
	ds_read_b128 v[210:213], v150 offset:52224
	ds_read_b128 v[214:217], v150 offset:53248
	ds_read_b128 v[218:221], v150 offset:54272
	ds_read_b128 v[222:225], v150 offset:55296
	ds_read_b128 v[226:229], v150 offset:56320
	s_waitcnt vmcnt(6)
	s_waitcnt lgkmcnt(0)
	s_barrier
	s_waitcnt lgkmcnt(0)
	v_mfma_f32_16x16x32_bf16 v[62:65], v[142:145], v[192:195], v[62:65]
	v_mfma_f32_16x16x32_bf16 v[62:65], v[154:157], v[202:205], v[62:65]
	v_mfma_f32_16x16x32_bf16 v[54:57], v[168:171], v[202:205], v[54:57]
	v_mfma_f32_16x16x32_bf16 v[54:57], v[158:161], v[192:195], v[54:57]
	v_mfma_f32_16x16x32_bf16 v[38:41], v[158:161], v[206:209], v[38:41]
	v_mfma_f32_16x16x32_bf16 v[38:41], v[168:171], v[210:213], v[38:41]
	v_mfma_f32_16x16x32_bf16 v[46:49], v[154:157], v[210:213], v[46:49]
	v_mfma_f32_16x16x32_bf16 v[46:49], v[142:145], v[206:209], v[46:49]
	v_mfma_f32_16x16x32_bf16 v[30:33], v[142:145], v[214:217], v[30:33]
	v_mfma_f32_16x16x32_bf16 v[30:33], v[154:157], v[218:221], v[30:33]
	v_mfma_f32_16x16x32_bf16 v[22:25], v[168:171], v[218:221], v[22:25]
	v_mfma_f32_16x16x32_bf16 v[22:25], v[158:161], v[214:217], v[22:25]
	v_mfma_f32_16x16x32_bf16 v[6:9], v[158:161], v[222:225], v[6:9]
	v_mfma_f32_16x16x32_bf16 v[6:9], v[168:171], v[226:229], v[6:9]
	v_mfma_f32_16x16x32_bf16 v[14:17], v[154:157], v[226:229], v[14:17]
	v_mfma_f32_16x16x32_bf16 v[14:17], v[142:145], v[222:225], v[14:17]
	v_mfma_f32_16x16x32_bf16 v[10:13], v[176:179], v[222:225], v[10:13]
	v_mfma_f32_16x16x32_bf16 v[10:13], v[180:183], v[226:229], v[10:13]
	v_mfma_f32_16x16x32_bf16 v[2:5], v[188:191], v[226:229], v[2:5]
	v_mfma_f32_16x16x32_bf16 v[2:5], v[184:187], v[222:225], v[2:5]
	v_mfma_f32_16x16x32_bf16 v[18:21], v[184:187], v[214:217], v[18:21]
	v_mfma_f32_16x16x32_bf16 v[18:21], v[188:191], v[218:221], v[18:21]
	v_mfma_f32_16x16x32_bf16 v[26:29], v[180:183], v[218:221], v[26:29]
	v_mfma_f32_16x16x32_bf16 v[26:29], v[176:179], v[214:217], v[26:29]
	v_mfma_f32_16x16x32_bf16 v[42:45], v[176:179], v[206:209], v[42:45]
	v_mfma_f32_16x16x32_bf16 v[42:45], v[180:183], v[210:213], v[42:45]
	v_mfma_f32_16x16x32_bf16 v[34:37], v[188:191], v[210:213], v[34:37]
	v_mfma_f32_16x16x32_bf16 v[34:37], v[184:187], v[206:209], v[34:37]
	v_mfma_f32_16x16x32_bf16 v[50:53], v[184:187], v[192:195], v[50:53]
	v_mfma_f32_16x16x32_bf16 v[50:53], v[188:191], v[202:205], v[50:53]
	v_mfma_f32_16x16x32_bf16 v[58:61], v[180:183], v[202:205], v[58:61]
	v_mfma_f32_16x16x32_bf16 v[58:61], v[176:179], v[192:195], v[58:61]
	s_barrier
	s_add_i32 s61, s61, 2
	s_add_u32 s20, s20, 0x100
	s_addc_u32 s21, s21, 0
	s_add_u32 s57, s57, 0x100
	s_addc_u32 s60, s60, 0
	s_cmp_gt_u32 s61, 61
	s_cbranch_scc0 .LBB0_1172
	s_and_b64 vcc, exec, s[16:17]
	s_cbranch_vccz .LBB0_1175
	s_barrier

.LBB0_1418:
	s_add_u32 s56, s22, 0xffd50000
	s_addc_u32 s57, s23, -1
	s_mov_b32 m0, s40
	ds_read_b128 v[142:145], v156
	global_load_lds_dwordx4 v130, s[56:57]
	s_mov_b32 m0, s41
	ds_read_b128 v[168:171], v156 offset:1024
	global_load_lds_dwordx4 v134, s[56:57]
	s_mov_b32 m0, s42
	ds_read_b128 v[176:179], v156 offset:2048
	global_load_lds_dwordx4 v138, s[22:23]
	s_mov_b32 m0, s43
	ds_read_b128 v[180:183], v156 offset:3072
	global_load_lds_dwordx4 v140, s[22:23]
	ds_read_b128 v[184:187], v157
	ds_read_b128 v[188:191], v157 offset:1024
	ds_read_b128 v[192:195], v157 offset:2048
	ds_read_b128 v[204:207], v157 offset:3072
	s_add_u32 s24, s22, 0xffd50080
	s_addc_u32 s25, s23, -1
	s_cmpk_eq_i32 s55, 0xa8
	s_cselect_b32 s27, s19, s25
	s_cselect_b32 s26, s18, s24
	s_cselect_b32 s25, s17, s54
	s_cselect_b32 s24, s16, s53
	ds_read_b128 v[208:211], v158
	ds_read_b128 v[212:215], v158 offset:1024
	ds_read_b128 v[216:219], v158 offset:2048
	ds_read_b128 v[220:223], v158 offset:3072
	ds_read_b128 v[224:227], v158 offset:4096
	ds_read_b128 v[228:231], v158 offset:5120
	ds_read_b128 v[232:235], v158 offset:6144
	ds_read_b128 v[236:239], v158 offset:7168
	s_waitcnt vmcnt(8)
	s_waitcnt lgkmcnt(0)
	s_barrier
	s_waitcnt lgkmcnt(0)
	v_mfma_f32_16x16x32_bf16 v[126:129], v[142:145], v[208:211], v[126:129]
	v_mfma_f32_16x16x32_bf16 v[126:129], v[168:171], v[212:215], v[126:129]
	v_mfma_f32_16x16x32_bf16 v[122:125], v[180:183], v[212:215], v[122:125]
	v_mfma_f32_16x16x32_bf16 v[122:125], v[176:179], v[208:211], v[122:125]
	v_mfma_f32_16x16x32_bf16 v[106:109], v[176:179], v[216:219], v[106:109]
	v_mfma_f32_16x16x32_bf16 v[106:109], v[180:183], v[220:223], v[106:109]
	v_mfma_f32_16x16x32_bf16 v[110:113], v[168:171], v[220:223], v[110:113]
	v_mfma_f32_16x16x32_bf16 v[110:113], v[142:145], v[216:219], v[110:113]
	v_mfma_f32_16x16x32_bf16 v[94:97], v[142:145], v[224:227], v[94:97]
	v_mfma_f32_16x16x32_bf16 v[94:97], v[168:171], v[228:231], v[94:97]
	v_mfma_f32_16x16x32_bf16 v[90:93], v[180:183], v[228:231], v[90:93]
	v_mfma_f32_16x16x32_bf16 v[90:93], v[176:179], v[224:227], v[90:93]
	v_mfma_f32_16x16x32_bf16 v[74:77], v[176:179], v[232:235], v[74:77]
	v_mfma_f32_16x16x32_bf16 v[74:77], v[180:183], v[236:239], v[74:77]
	v_mfma_f32_16x16x32_bf16 v[78:81], v[168:171], v[236:239], v[78:81]
	v_mfma_f32_16x16x32_bf16 v[78:81], v[142:145], v[232:235], v[78:81]
	v_mfma_f32_16x16x32_bf16 v[70:73], v[184:187], v[232:235], v[70:73]
	v_mfma_f32_16x16x32_bf16 v[70:73], v[188:191], v[236:239], v[70:73]
	v_mfma_f32_16x16x32_bf16 v[66:69], v[204:207], v[236:239], v[66:69]
	v_mfma_f32_16x16x32_bf16 v[66:69], v[192:195], v[232:235], v[66:69]
	v_mfma_f32_16x16x32_bf16 v[82:85], v[192:195], v[224:227], v[82:85]
	v_mfma_f32_16x16x32_bf16 v[82:85], v[204:207], v[228:231], v[82:85]
	v_mfma_f32_16x16x32_bf16 v[86:89], v[188:191], v[228:231], v[86:89]
	v_mfma_f32_16x16x32_bf16 v[86:89], v[184:187], v[224:227], v[86:89]
	v_mfma_f32_16x16x32_bf16 v[102:105], v[184:187], v[216:219], v[102:105]
	v_mfma_f32_16x16x32_bf16 v[102:105], v[188:191], v[220:223], v[102:105]
	v_mfma_f32_16x16x32_bf16 v[98:101], v[204:207], v[220:223], v[98:101]
	v_mfma_f32_16x16x32_bf16 v[98:101], v[192:195], v[216:219], v[98:101]
	v_mfma_f32_16x16x32_bf16 v[114:117], v[192:195], v[208:211], v[114:117]
	v_mfma_f32_16x16x32_bf16 v[114:117], v[204:207], v[212:215], v[114:117]
	v_mfma_f32_16x16x32_bf16 v[118:121], v[188:191], v[212:215], v[118:121]
	v_mfma_f32_16x16x32_bf16 v[118:121], v[184:187], v[208:211], v[118:121]
	s_barrier
	s_mov_b32 m0, s44
	s_add_u32 s56, s24, 0x2b0000
	global_load_lds_dwordx4 v132, s[24:25]
	s_mov_b32 m0, s45
	s_addc_u32 s57, s25, 0
	global_load_lds_dwordx4 v136, s[24:25]
	s_mov_b32 m0, s46
	ds_read_b128 v[208:211], v158 offset:16384
	global_load_lds_dwordx4 v132, s[56:57]
	s_mov_b32 m0, s47
	ds_read_b128 v[212:215], v158 offset:17408
	global_load_lds_dwordx4 v136, s[56:57]
	ds_read_b128 v[216:219], v158 offset:18432
	ds_read_b128 v[220:223], v158 offset:19456
	ds_read_b128 v[224:227], v158 offset:20480
	ds_read_b128 v[228:231], v158 offset:21504
	ds_read_b128 v[232:235], v158 offset:22528
	ds_read_b128 v[236:239], v158 offset:23552
	s_waitcnt vmcnt(6)
	s_waitcnt lgkmcnt(0)
	s_barrier
	s_waitcnt lgkmcnt(0)
	v_mfma_f32_16x16x32_bf16 v[62:65], v[142:145], v[208:211], v[62:65]
	v_mfma_f32_16x16x32_bf16 v[62:65], v[168:171], v[212:215], v[62:65]
	v_mfma_f32_16x16x32_bf16 v[58:61], v[180:183], v[212:215], v[58:61]
	v_mfma_f32_16x16x32_bf16 v[58:61], v[176:179], v[208:211], v[58:61]
	v_mfma_f32_16x16x32_bf16 v[42:45], v[176:179], v[216:219], v[42:45]
	v_mfma_f32_16x16x32_bf16 v[42:45], v[180:183], v[220:223], v[42:45]
	v_mfma_f32_16x16x32_bf16 v[46:49], v[168:171], v[220:223], v[46:49]
	v_mfma_f32_16x16x32_bf16 v[46:49], v[142:145], v[216:219], v[46:49]
	v_mfma_f32_16x16x32_bf16 v[30:33], v[142:145], v[224:227], v[30:33]
	v_mfma_f32_16x16x32_bf16 v[30:33], v[168:171], v[228:231], v[30:33]
	v_mfma_f32_16x16x32_bf16 v[26:29], v[180:183], v[228:231], v[26:29]
	v_mfma_f32_16x16x32_bf16 v[26:29], v[176:179], v[224:227], v[26:29]
	v_mfma_f32_16x16x32_bf16 v[10:13], v[176:179], v[232:235], v[10:13]
	v_mfma_f32_16x16x32_bf16 v[10:13], v[180:183], v[236:239], v[10:13]
	v_mfma_f32_16x16x32_bf16 v[14:17], v[168:171], v[236:239], v[14:17]
	v_mfma_f32_16x16x32_bf16 v[14:17], v[142:145], v[232:235], v[14:17]
	v_mfma_f32_16x16x32_bf16 v[6:9], v[184:187], v[232:235], v[6:9]
	v_mfma_f32_16x16x32_bf16 v[6:9], v[188:191], v[236:239], v[6:9]
	v_mfma_f32_16x16x32_bf16 v[2:5], v[204:207], v[236:239], v[2:5]
	v_mfma_f32_16x16x32_bf16 v[2:5], v[192:195], v[232:235], v[2:5]
	v_mfma_f32_16x16x32_bf16 v[18:21], v[192:195], v[224:227], v[18:21]
	v_mfma_f32_16x16x32_bf16 v[18:21], v[204:207], v[228:231], v[18:21]
	v_mfma_f32_16x16x32_bf16 v[22:25], v[188:191], v[228:231], v[22:25]
	v_mfma_f32_16x16x32_bf16 v[22:25], v[184:187], v[224:227], v[22:25]
	v_mfma_f32_16x16x32_bf16 v[38:41], v[184:187], v[216:219], v[38:41]
	v_mfma_f32_16x16x32_bf16 v[38:41], v[188:191], v[220:223], v[38:41]
	v_mfma_f32_16x16x32_bf16 v[34:37], v[204:207], v[220:223], v[34:37]
	v_mfma_f32_16x16x32_bf16 v[34:37], v[192:195], v[216:219], v[34:37]
	v_mfma_f32_16x16x32_bf16 v[50:53], v[192:195], v[208:211], v[50:53]
	v_mfma_f32_16x16x32_bf16 v[50:53], v[204:207], v[212:215], v[50:53]
	v_mfma_f32_16x16x32_bf16 v[54:57], v[188:191], v[212:215], v[54:57]
	v_mfma_f32_16x16x32_bf16 v[54:57], v[184:187], v[208:211], v[54:57]
	s_barrier
	s_mov_b32 m0, s35
	ds_read_b128 v[142:145], v159
	global_load_lds_dwordx4 v130, s[26:27]
	s_mov_b32 m0, s36
	ds_read_b128 v[168:171], v159 offset:1024
	global_load_lds_dwordx4 v134, s[26:27]
	s_add_u32 s26, s26, 0x2b0000
	s_addc_u32 s27, s27, 0
	s_mov_b32 m0, s37
	ds_read_b128 v[176:179], v159 offset:2048
	global_load_lds_dwordx4 v130, s[26:27]
	s_mov_b32 m0, s38
	ds_read_b128 v[180:183], v159 offset:3072
	global_load_lds_dwordx4 v134, s[26:27]
	ds_read_b128 v[184:187], v160
	ds_read_b128 v[188:191], v160 offset:1024
	ds_read_b128 v[192:195], v160 offset:2048
	ds_read_b128 v[204:207], v160 offset:3072
	ds_read_b128 v[208:211], v158 offset:32768
	ds_read_b128 v[212:215], v158 offset:33792
	ds_read_b128 v[216:219], v158 offset:34816
	ds_read_b128 v[220:223], v158 offset:35840
	ds_read_b128 v[224:227], v158 offset:36864
	ds_read_b128 v[228:231], v158 offset:37888
	ds_read_b128 v[232:235], v158 offset:38912
	ds_read_b128 v[236:239], v158 offset:39936
	s_waitcnt vmcnt(8)
	s_waitcnt lgkmcnt(0)
	s_barrier
	s_waitcnt lgkmcnt(0)
	v_mfma_f32_16x16x32_bf16 v[126:129], v[142:145], v[208:211], v[126:129]
	v_mfma_f32_16x16x32_bf16 v[126:129], v[168:171], v[212:215], v[126:129]
	v_mfma_f32_16x16x32_bf16 v[122:125], v[180:183], v[212:215], v[122:125]
	v_mfma_f32_16x16x32_bf16 v[122:125], v[176:179], v[208:211], v[122:125]
	v_mfma_f32_16x16x32_bf16 v[106:109], v[176:179], v[216:219], v[106:109]
	v_mfma_f32_16x16x32_bf16 v[106:109], v[180:183], v[220:223], v[106:109]
	v_mfma_f32_16x16x32_bf16 v[110:113], v[168:171], v[220:223], v[110:113]
	v_mfma_f32_16x16x32_bf16 v[110:113], v[142:145], v[216:219], v[110:113]
	v_mfma_f32_16x16x32_bf16 v[94:97], v[142:145], v[224:227], v[94:97]
	v_mfma_f32_16x16x32_bf16 v[94:97], v[168:171], v[228:231], v[94:97]
	v_mfma_f32_16x16x32_bf16 v[90:93], v[180:183], v[228:231], v[90:93]
	v_mfma_f32_16x16x32_bf16 v[90:93], v[176:179], v[224:227], v[90:93]
	v_mfma_f32_16x16x32_bf16 v[74:77], v[176:179], v[232:235], v[74:77]
	v_mfma_f32_16x16x32_bf16 v[74:77], v[180:183], v[236:239], v[74:77]
	v_mfma_f32_16x16x32_bf16 v[78:81], v[168:171], v[236:239], v[78:81]
	v_mfma_f32_16x16x32_bf16 v[78:81], v[142:145], v[232:235], v[78:81]
	v_mfma_f32_16x16x32_bf16 v[70:73], v[184:187], v[232:235], v[70:73]
	v_mfma_f32_16x16x32_bf16 v[70:73], v[188:191], v[236:239], v[70:73]
	v_mfma_f32_16x16x32_bf16 v[66:69], v[204:207], v[236:239], v[66:69]
	v_mfma_f32_16x16x32_bf16 v[66:69], v[192:195], v[232:235], v[66:69]
	v_mfma_f32_16x16x32_bf16 v[82:85], v[192:195], v[224:227], v[82:85]
	v_mfma_f32_16x16x32_bf16 v[82:85], v[204:207], v[228:231], v[82:85]
	v_mfma_f32_16x16x32_bf16 v[86:89], v[188:191], v[228:231], v[86:89]
	v_mfma_f32_16x16x32_bf16 v[86:89], v[184:187], v[224:227], v[86:89]
	v_mfma_f32_16x16x32_bf16 v[102:105], v[184:187], v[216:219], v[102:105]
	v_mfma_f32_16x16x32_bf16 v[102:105], v[188:191], v[220:223], v[102:105]
	v_mfma_f32_16x16x32_bf16 v[98:101], v[204:207], v[220:223], v[98:101]
	v_mfma_f32_16x16x32_bf16 v[98:101], v[192:195], v[216:219], v[98:101]
	v_mfma_f32_16x16x32_bf16 v[114:117], v[192:195], v[208:211], v[114:117]
	v_mfma_f32_16x16x32_bf16 v[114:117], v[204:207], v[212:215], v[114:117]
	v_mfma_f32_16x16x32_bf16 v[118:121], v[188:191], v[212:215], v[118:121]
	v_mfma_f32_16x16x32_bf16 v[118:121], v[184:187], v[208:211], v[118:121]
	s_barrier
	s_mov_b32 m0, s48
	s_add_u32 s24, s24, 0x80
	s_addc_u32 s25, s25, 0
	global_load_lds_dwordx4 v132, s[24:25]
	s_mov_b32 m0, s49
	ds_read_b128 v[208:211], v158 offset:49152
	global_load_lds_dwordx4 v136, s[24:25]
	s_mov_b32 m0, s50
	s_add_u32 s24, s24, 0x2b0000
	s_addc_u32 s25, s25, 0
	global_load_lds_dwordx4 v132, s[24:25]
	s_add_i32 m0, s50, 0x2000
	ds_read_b128 v[212:215], v158 offset:50176
	global_load_lds_dwordx4 v136, s[24:25]
	ds_read_b128 v[216:219], v158 offset:51200
	ds_read_b128 v[220:223], v158 offset:52224
	ds_read_b128 v[224:227], v158 offset:53248
	ds_read_b128 v[228:231], v158 offset:54272
	ds_read_b128 v[232:235], v158 offset:55296
	ds_read_b128 v[236:239], v158 offset:56320
	s_waitcnt vmcnt(6)
	s_waitcnt lgkmcnt(0)
	s_barrier
	s_waitcnt lgkmcnt(0)
	v_mfma_f32_16x16x32_bf16 v[62:65], v[142:145], v[208:211], v[62:65]
	v_mfma_f32_16x16x32_bf16 v[62:65], v[168:171], v[212:215], v[62:65]
	v_mfma_f32_16x16x32_bf16 v[58:61], v[180:183], v[212:215], v[58:61]
	v_mfma_f32_16x16x32_bf16 v[58:61], v[176:179], v[208:211], v[58:61]
	v_mfma_f32_16x16x32_bf16 v[42:45], v[176:179], v[216:219], v[42:45]
	v_mfma_f32_16x16x32_bf16 v[42:45], v[180:183], v[220:223], v[42:45]
	v_mfma_f32_16x16x32_bf16 v[46:49], v[168:171], v[220:223], v[46:49]
	v_mfma_f32_16x16x32_bf16 v[46:49], v[142:145], v[216:219], v[46:49]
	v_mfma_f32_16x16x32_bf16 v[30:33], v[142:145], v[224:227], v[30:33]
	v_mfma_f32_16x16x32_bf16 v[30:33], v[168:171], v[228:231], v[30:33]
	v_mfma_f32_16x16x32_bf16 v[26:29], v[180:183], v[228:231], v[26:29]
	v_mfma_f32_16x16x32_bf16 v[26:29], v[176:179], v[224:227], v[26:29]
	v_mfma_f32_16x16x32_bf16 v[10:13], v[176:179], v[232:235], v[10:13]
	v_mfma_f32_16x16x32_bf16 v[10:13], v[180:183], v[236:239], v[10:13]
	v_mfma_f32_16x16x32_bf16 v[14:17], v[168:171], v[236:239], v[14:17]
	v_mfma_f32_16x16x32_bf16 v[14:17], v[142:145], v[232:235], v[14:17]
	v_mfma_f32_16x16x32_bf16 v[6:9], v[184:187], v[232:235], v[6:9]
	v_mfma_f32_16x16x32_bf16 v[6:9], v[188:191], v[236:239], v[6:9]
	v_mfma_f32_16x16x32_bf16 v[2:5], v[204:207], v[236:239], v[2:5]
	v_mfma_f32_16x16x32_bf16 v[2:5], v[192:195], v[232:235], v[2:5]
	v_mfma_f32_16x16x32_bf16 v[18:21], v[192:195], v[224:227], v[18:21]
	v_mfma_f32_16x16x32_bf16 v[18:21], v[204:207], v[228:231], v[18:21]
	v_mfma_f32_16x16x32_bf16 v[22:25], v[188:191], v[228:231], v[22:25]
	v_mfma_f32_16x16x32_bf16 v[22:25], v[184:187], v[224:227], v[22:25]
	v_mfma_f32_16x16x32_bf16 v[38:41], v[184:187], v[216:219], v[38:41]
	v_mfma_f32_16x16x32_bf16 v[38:41], v[188:191], v[220:223], v[38:41]
	v_mfma_f32_16x16x32_bf16 v[34:37], v[204:207], v[220:223], v[34:37]
	v_mfma_f32_16x16x32_bf16 v[34:37], v[192:195], v[216:219], v[34:37]
	v_mfma_f32_16x16x32_bf16 v[50:53], v[192:195], v[208:211], v[50:53]
	v_mfma_f32_16x16x32_bf16 v[50:53], v[204:207], v[212:215], v[50:53]
	v_mfma_f32_16x16x32_bf16 v[54:57], v[188:191], v[212:215], v[54:57]
	v_mfma_f32_16x16x32_bf16 v[54:57], v[184:187], v[208:211], v[54:57]
	s_barrier
	s_add_i32 s55, s55, 2
	s_add_u32 s22, s22, 0x100
	s_addc_u32 s23, s23, 0
	s_add_u32 s53, s53, 0x100
	s_addc_u32 s54, s54, 0
	s_cmpk_gt_u32 s55, 0xa9
	s_cbranch_scc0 .LBB0_1418
	s_and_b64 vcc, exec, s[14:15]
	s_cbranch_vccz .LBB0_1421
	s_barrier

.LBB0_1432:
	ds_read_b128 v[150:153], v139
	ds_read_b128 v[154:157], v139 offset:1024
	ds_read_b128 v[158:161], v139 offset:2048
	ds_read_b128 v[168:171], v139 offset:3072
	ds_read_b128 v[176:179], v144
	ds_read_b128 v[180:183], v144 offset:1024
	ds_read_b128 v[184:187], v144 offset:2048
	ds_read_b128 v[188:191], v144 offset:3072
	s_add_i32 s42, s15, 2
	s_add_u32 s14, s12, 0xc2050080
	s_addc_u32 s16, s13, -1
	s_cmp_lg_u32 s30, s15
	s_cselect_b32 s14, s14, 0
	s_cselect_b32 s15, s16, 0
	s_add_u32 s16, s4, s14
	s_addc_u32 s17, s5, s15
	s_add_u32 s14, s8, s14
	s_addc_u32 s15, s9, s15
	s_mov_b32 m0, s31
	v_lshl_add_u64 v[172:173], v[140:141], 0, s[12:13]
	ds_read_b128 v[192:195], v145
	ds_read_b128 v[204:207], v145 offset:1024
	ds_read_b128 v[208:211], v145 offset:2048
	ds_read_b128 v[212:215], v145 offset:3072
	ds_read_b128 v[216:219], v145 offset:4096
	ds_read_b128 v[220:223], v145 offset:5120
	ds_read_b128 v[224:227], v145 offset:6144
	ds_read_b128 v[228:231], v145 offset:7168
	global_load_lds_dwordx4 v[172:173], off
	v_lshl_add_u64 v[172:173], v[142:143], 0, s[12:13]
	s_mov_b32 m0, s33
	s_nop 0
	global_load_lds_dwordx4 v[172:173], off
	s_waitcnt vmcnt(8)
	s_waitcnt lgkmcnt(0)
	s_barrier
	s_waitcnt lgkmcnt(0)
	v_mfma_f32_16x16x32_bf16 v[126:129], v[150:153], v[192:195], v[126:129]
	v_mfma_f32_16x16x32_bf16 v[126:129], v[154:157], v[204:207], v[126:129]
	v_mfma_f32_16x16x32_bf16 v[122:125], v[168:171], v[204:207], v[122:125]
	v_mfma_f32_16x16x32_bf16 v[122:125], v[158:161], v[192:195], v[122:125]
	v_mfma_f32_16x16x32_bf16 v[114:117], v[158:161], v[208:211], v[114:117]
	v_mfma_f32_16x16x32_bf16 v[114:117], v[168:171], v[212:215], v[114:117]
	v_mfma_f32_16x16x32_bf16 v[118:121], v[154:157], v[212:215], v[118:121]
	v_mfma_f32_16x16x32_bf16 v[118:121], v[150:153], v[208:211], v[118:121]
	v_mfma_f32_16x16x32_bf16 v[102:105], v[150:153], v[216:219], v[102:105]
	v_mfma_f32_16x16x32_bf16 v[102:105], v[154:157], v[220:223], v[102:105]
	v_mfma_f32_16x16x32_bf16 v[98:101], v[168:171], v[220:223], v[98:101]
	v_mfma_f32_16x16x32_bf16 v[98:101], v[158:161], v[216:219], v[98:101]
	v_mfma_f32_16x16x32_bf16 v[82:85], v[158:161], v[224:227], v[82:85]
	v_mfma_f32_16x16x32_bf16 v[82:85], v[168:171], v[228:231], v[82:85]
	v_mfma_f32_16x16x32_bf16 v[86:89], v[154:157], v[228:231], v[86:89]
	v_mfma_f32_16x16x32_bf16 v[86:89], v[150:153], v[224:227], v[86:89]
	v_mfma_f32_16x16x32_bf16 v[70:73], v[176:179], v[224:227], v[70:73]
	v_mfma_f32_16x16x32_bf16 v[70:73], v[180:183], v[228:231], v[70:73]
	v_mfma_f32_16x16x32_bf16 v[66:69], v[188:191], v[228:231], v[66:69]
	v_mfma_f32_16x16x32_bf16 v[66:69], v[184:187], v[224:227], v[66:69]
	v_mfma_f32_16x16x32_bf16 v[74:77], v[184:187], v[216:219], v[74:77]
	v_mfma_f32_16x16x32_bf16 v[74:77], v[188:191], v[220:223], v[74:77]
	v_mfma_f32_16x16x32_bf16 v[78:81], v[180:183], v[220:223], v[78:81]
	v_mfma_f32_16x16x32_bf16 v[78:81], v[176:179], v[216:219], v[78:81]
	v_mfma_f32_16x16x32_bf16 v[94:97], v[176:179], v[208:211], v[94:97]
	v_mfma_f32_16x16x32_bf16 v[94:97], v[180:183], v[212:215], v[94:97]
	v_mfma_f32_16x16x32_bf16 v[90:93], v[188:191], v[212:215], v[90:93]
	v_mfma_f32_16x16x32_bf16 v[90:93], v[184:187], v[208:211], v[90:93]
	v_mfma_f32_16x16x32_bf16 v[106:109], v[184:187], v[192:195], v[106:109]
	v_mfma_f32_16x16x32_bf16 v[106:109], v[188:191], v[204:207], v[106:109]
	v_mfma_f32_16x16x32_bf16 v[110:113], v[180:183], v[204:207], v[110:113]
	v_mfma_f32_16x16x32_bf16 v[110:113], v[176:179], v[192:195], v[110:113]
	s_barrier
	s_mov_b32 m0, s34
	v_lshl_add_u64 v[172:173], s[14:15], 0, v[132:133]
	s_add_u32 s44, s14, 0x2b0000
	ds_read_b128 v[192:195], v145 offset:16384
	ds_read_b128 v[204:207], v145 offset:17408
	ds_read_b128 v[208:211], v145 offset:18432
	ds_read_b128 v[212:215], v145 offset:19456
	ds_read_b128 v[216:219], v145 offset:20480
	ds_read_b128 v[220:223], v145 offset:21504
	ds_read_b128 v[224:227], v145 offset:22528
	ds_read_b128 v[228:231], v145 offset:23552
	global_load_lds_dwordx4 v[172:173], off
	v_lshl_add_u64 v[196:197], s[14:15], 0, v[136:137]
	s_mov_b32 m0, s35
	s_addc_u32 s45, s15, 0
	global_load_lds_dwordx4 v[196:197], off
	v_lshl_add_u64 v[232:233], s[44:45], 0, v[132:133]
	s_mov_b32 m0, s36
	v_lshl_add_u64 v[234:235], s[16:17], 0, v[134:135]
	global_load_lds_dwordx4 v[232:233], off
	v_lshl_add_u64 v[232:233], s[44:45], 0, v[136:137]
	s_mov_b32 m0, s37
	s_nop 0
	global_load_lds_dwordx4 v[232:233], off
	v_lshl_add_u64 v[232:233], s[16:17], 0, v[130:131]
	s_mov_b32 m0, s21
	s_nop 0
	global_load_lds_dwordx4 v[232:233], off
	s_mov_b32 m0, s22
	s_nop 0
	global_load_lds_dwordx4 v[234:235], off
	s_waitcnt vmcnt(8)
	s_waitcnt lgkmcnt(0)
	s_barrier
	s_waitcnt lgkmcnt(0)
	v_mfma_f32_16x16x32_bf16 v[62:65], v[150:153], v[192:195], v[62:65]
	v_mfma_f32_16x16x32_bf16 v[62:65], v[154:157], v[204:207], v[62:65]
	v_mfma_f32_16x16x32_bf16 v[58:61], v[168:171], v[204:207], v[58:61]
	v_mfma_f32_16x16x32_bf16 v[58:61], v[158:161], v[192:195], v[58:61]
	v_mfma_f32_16x16x32_bf16 v[50:53], v[158:161], v[208:211], v[50:53]
	v_mfma_f32_16x16x32_bf16 v[50:53], v[168:171], v[212:215], v[50:53]
	v_mfma_f32_16x16x32_bf16 v[54:57], v[154:157], v[212:215], v[54:57]
	v_mfma_f32_16x16x32_bf16 v[54:57], v[150:153], v[208:211], v[54:57]
	v_mfma_f32_16x16x32_bf16 v[38:41], v[150:153], v[216:219], v[38:41]
	v_mfma_f32_16x16x32_bf16 v[38:41], v[154:157], v[220:223], v[38:41]
	v_mfma_f32_16x16x32_bf16 v[34:37], v[168:171], v[220:223], v[34:37]
	v_mfma_f32_16x16x32_bf16 v[34:37], v[158:161], v[216:219], v[34:37]
	v_mfma_f32_16x16x32_bf16 v[18:21], v[158:161], v[224:227], v[18:21]
	v_mfma_f32_16x16x32_bf16 v[18:21], v[168:171], v[228:231], v[18:21]
	v_mfma_f32_16x16x32_bf16 v[22:25], v[154:157], v[228:231], v[22:25]
	v_mfma_f32_16x16x32_bf16 v[22:25], v[150:153], v[224:227], v[22:25]
	v_mfma_f32_16x16x32_bf16 v[6:9], v[176:179], v[224:227], v[6:9]
	v_mfma_f32_16x16x32_bf16 v[6:9], v[180:183], v[228:231], v[6:9]
	v_mfma_f32_16x16x32_bf16 v[2:5], v[188:191], v[228:231], v[2:5]
	v_mfma_f32_16x16x32_bf16 v[2:5], v[184:187], v[224:227], v[2:5]
	v_mfma_f32_16x16x32_bf16 v[10:13], v[184:187], v[216:219], v[10:13]
	v_mfma_f32_16x16x32_bf16 v[10:13], v[188:191], v[220:223], v[10:13]
	v_mfma_f32_16x16x32_bf16 v[14:17], v[180:183], v[220:223], v[14:17]
	v_mfma_f32_16x16x32_bf16 v[14:17], v[176:179], v[216:219], v[14:17]
	v_mfma_f32_16x16x32_bf16 v[30:33], v[176:179], v[208:211], v[30:33]
	v_mfma_f32_16x16x32_bf16 v[30:33], v[180:183], v[212:215], v[30:33]
	v_mfma_f32_16x16x32_bf16 v[26:29], v[188:191], v[212:215], v[26:29]
	v_mfma_f32_16x16x32_bf16 v[26:29], v[184:187], v[208:211], v[26:29]
	v_mfma_f32_16x16x32_bf16 v[42:45], v[184:187], v[192:195], v[42:45]
	v_mfma_f32_16x16x32_bf16 v[42:45], v[188:191], v[204:207], v[42:45]
	v_mfma_f32_16x16x32_bf16 v[46:49], v[180:183], v[204:207], v[46:49]
	v_mfma_f32_16x16x32_bf16 v[46:49], v[176:179], v[192:195], v[46:49]
	s_barrier
	ds_read_b128 v[150:153], v146
	ds_read_b128 v[154:157], v146 offset:1024
	ds_read_b128 v[158:161], v146 offset:2048
	ds_read_b128 v[168:171], v146 offset:3072
	ds_read_b128 v[176:179], v147
	ds_read_b128 v[180:183], v147 offset:1024
	ds_read_b128 v[184:187], v147 offset:2048
	ds_read_b128 v[188:191], v147 offset:3072
	s_add_u32 s16, s16, 0x2b0000
	s_addc_u32 s17, s17, 0
	s_mov_b32 m0, s23
	v_lshl_add_u64 v[236:237], s[16:17], 0, v[130:131]
	ds_read_b128 v[192:195], v145 offset:32768
	ds_read_b128 v[204:207], v145 offset:33792
	ds_read_b128 v[208:211], v145 offset:34816
	ds_read_b128 v[212:215], v145 offset:35840
	ds_read_b128 v[216:219], v145 offset:36864
	ds_read_b128 v[220:223], v145 offset:37888
	ds_read_b128 v[224:227], v145 offset:38912
	ds_read_b128 v[228:231], v145 offset:39936
	global_load_lds_dwordx4 v[236:237], off
	v_lshl_add_u64 v[236:237], s[16:17], 0, v[134:135]
	s_mov_b32 m0, s24
	s_nop 0
	global_load_lds_dwordx4 v[236:237], off
	s_waitcnt vmcnt(8)
	s_waitcnt lgkmcnt(0)
	s_barrier
	s_waitcnt lgkmcnt(0)
	v_mfma_f32_16x16x32_bf16 v[126:129], v[150:153], v[192:195], v[126:129]
	v_mfma_f32_16x16x32_bf16 v[126:129], v[154:157], v[204:207], v[126:129]
	v_mfma_f32_16x16x32_bf16 v[122:125], v[168:171], v[204:207], v[122:125]
	v_mfma_f32_16x16x32_bf16 v[122:125], v[158:161], v[192:195], v[122:125]
	v_mfma_f32_16x16x32_bf16 v[114:117], v[158:161], v[208:211], v[114:117]
	v_mfma_f32_16x16x32_bf16 v[114:117], v[168:171], v[212:215], v[114:117]
	v_mfma_f32_16x16x32_bf16 v[118:121], v[154:157], v[212:215], v[118:121]
	v_mfma_f32_16x16x32_bf16 v[118:121], v[150:153], v[208:211], v[118:121]
	v_mfma_f32_16x16x32_bf16 v[102:105], v[150:153], v[216:219], v[102:105]
	v_mfma_f32_16x16x32_bf16 v[102:105], v[154:157], v[220:223], v[102:105]
	v_mfma_f32_16x16x32_bf16 v[98:101], v[168:171], v[220:223], v[98:101]
	v_mfma_f32_16x16x32_bf16 v[98:101], v[158:161], v[216:219], v[98:101]
	v_mfma_f32_16x16x32_bf16 v[82:85], v[158:161], v[224:227], v[82:85]
	v_mfma_f32_16x16x32_bf16 v[82:85], v[168:171], v[228:231], v[82:85]
	v_mfma_f32_16x16x32_bf16 v[86:89], v[154:157], v[228:231], v[86:89]
	v_mfma_f32_16x16x32_bf16 v[86:89], v[150:153], v[224:227], v[86:89]
	v_mfma_f32_16x16x32_bf16 v[70:73], v[176:179], v[224:227], v[70:73]
	v_mfma_f32_16x16x32_bf16 v[70:73], v[180:183], v[228:231], v[70:73]
	v_mfma_f32_16x16x32_bf16 v[66:69], v[188:191], v[228:231], v[66:69]
	v_mfma_f32_16x16x32_bf16 v[66:69], v[184:187], v[224:227], v[66:69]
	v_mfma_f32_16x16x32_bf16 v[74:77], v[184:187], v[216:219], v[74:77]
	v_mfma_f32_16x16x32_bf16 v[74:77], v[188:191], v[220:223], v[74:77]
	v_mfma_f32_16x16x32_bf16 v[78:81], v[180:183], v[220:223], v[78:81]
	v_mfma_f32_16x16x32_bf16 v[78:81], v[176:179], v[216:219], v[78:81]
	v_mfma_f32_16x16x32_bf16 v[94:97], v[176:179], v[208:211], v[94:97]
	v_mfma_f32_16x16x32_bf16 v[94:97], v[180:183], v[212:215], v[94:97]
	v_mfma_f32_16x16x32_bf16 v[90:93], v[188:191], v[212:215], v[90:93]
	v_mfma_f32_16x16x32_bf16 v[90:93], v[184:187], v[208:211], v[90:93]
	v_mfma_f32_16x16x32_bf16 v[106:109], v[184:187], v[192:195], v[106:109]
	v_mfma_f32_16x16x32_bf16 v[106:109], v[188:191], v[204:207], v[106:109]
	v_mfma_f32_16x16x32_bf16 v[110:113], v[180:183], v[204:207], v[110:113]
	v_mfma_f32_16x16x32_bf16 v[110:113], v[176:179], v[192:195], v[110:113]
	s_barrier
	s_mov_b32 m0, s38
	v_lshl_add_u64 v[172:173], v[172:173], 0, s[10:11]
	s_add_u32 s14, s14, 0x2b0080
	ds_read_b128 v[192:195], v145 offset:49152
	ds_read_b128 v[204:207], v145 offset:50176
	ds_read_b128 v[208:211], v145 offset:51200
	ds_read_b128 v[212:215], v145 offset:52224
	ds_read_b128 v[216:219], v145 offset:53248
	ds_read_b128 v[220:223], v145 offset:54272
	ds_read_b128 v[224:227], v145 offset:55296
	ds_read_b128 v[228:231], v145 offset:56320
	global_load_lds_dwordx4 v[172:173], off
	v_lshl_add_u64 v[172:173], v[196:197], 0, s[10:11]
	s_mov_b32 m0, s39
	s_addc_u32 s15, s15, 0
	global_load_lds_dwordx4 v[172:173], off
	v_lshl_add_u64 v[172:173], s[14:15], 0, v[132:133]
	s_mov_b32 m0, s40
	s_nop 0
	global_load_lds_dwordx4 v[172:173], off
	v_lshl_add_u64 v[172:173], s[14:15], 0, v[136:137]
	s_mov_b32 m0, s41
	s_nop 0
	global_load_lds_dwordx4 v[172:173], off
	v_lshl_add_u64 v[172:173], v[232:233], 0, s[10:11]
	s_mov_b32 m0, s26
	s_nop 0
	global_load_lds_dwordx4 v[172:173], off
	v_lshl_add_u64 v[172:173], v[234:235], 0, s[10:11]
	s_mov_b32 m0, s27
	s_nop 0
	global_load_lds_dwordx4 v[172:173], off
	s_waitcnt vmcnt(8)
	s_waitcnt lgkmcnt(0)
	s_barrier
	s_waitcnt lgkmcnt(0)
	v_mfma_f32_16x16x32_bf16 v[62:65], v[150:153], v[192:195], v[62:65]
	v_mfma_f32_16x16x32_bf16 v[62:65], v[154:157], v[204:207], v[62:65]
	v_mfma_f32_16x16x32_bf16 v[58:61], v[168:171], v[204:207], v[58:61]
	v_mfma_f32_16x16x32_bf16 v[58:61], v[158:161], v[192:195], v[58:61]
	v_mfma_f32_16x16x32_bf16 v[50:53], v[158:161], v[208:211], v[50:53]
	v_mfma_f32_16x16x32_bf16 v[50:53], v[168:171], v[212:215], v[50:53]
	v_mfma_f32_16x16x32_bf16 v[54:57], v[154:157], v[212:215], v[54:57]
	v_mfma_f32_16x16x32_bf16 v[54:57], v[150:153], v[208:211], v[54:57]
	v_mfma_f32_16x16x32_bf16 v[38:41], v[150:153], v[216:219], v[38:41]
	v_mfma_f32_16x16x32_bf16 v[38:41], v[154:157], v[220:223], v[38:41]
	v_mfma_f32_16x16x32_bf16 v[34:37], v[168:171], v[220:223], v[34:37]
	v_mfma_f32_16x16x32_bf16 v[34:37], v[158:161], v[216:219], v[34:37]
	v_mfma_f32_16x16x32_bf16 v[18:21], v[158:161], v[224:227], v[18:21]
	v_mfma_f32_16x16x32_bf16 v[18:21], v[168:171], v[228:231], v[18:21]
	v_mfma_f32_16x16x32_bf16 v[22:25], v[154:157], v[228:231], v[22:25]
	v_mfma_f32_16x16x32_bf16 v[22:25], v[150:153], v[224:227], v[22:25]
	v_mfma_f32_16x16x32_bf16 v[6:9], v[176:179], v[224:227], v[6:9]
	v_mfma_f32_16x16x32_bf16 v[6:9], v[180:183], v[228:231], v[6:9]
	v_mfma_f32_16x16x32_bf16 v[2:5], v[188:191], v[228:231], v[2:5]
	v_mfma_f32_16x16x32_bf16 v[2:5], v[184:187], v[224:227], v[2:5]
	v_mfma_f32_16x16x32_bf16 v[10:13], v[184:187], v[216:219], v[10:13]
	v_mfma_f32_16x16x32_bf16 v[10:13], v[188:191], v[220:223], v[10:13]
	v_mfma_f32_16x16x32_bf16 v[14:17], v[180:183], v[220:223], v[14:17]
	v_mfma_f32_16x16x32_bf16 v[14:17], v[176:179], v[216:219], v[14:17]
	v_mfma_f32_16x16x32_bf16 v[30:33], v[176:179], v[208:211], v[30:33]
	v_mfma_f32_16x16x32_bf16 v[30:33], v[180:183], v[212:215], v[30:33]
	v_mfma_f32_16x16x32_bf16 v[26:29], v[188:191], v[212:215], v[26:29]
	v_mfma_f32_16x16x32_bf16 v[26:29], v[184:187], v[208:211], v[26:29]
	v_mfma_f32_16x16x32_bf16 v[42:45], v[184:187], v[192:195], v[42:45]
	v_mfma_f32_16x16x32_bf16 v[42:45], v[188:191], v[204:207], v[42:45]
	v_mfma_f32_16x16x32_bf16 v[46:49], v[180:183], v[204:207], v[46:49]
	v_mfma_f32_16x16x32_bf16 v[46:49], v[176:179], v[192:195], v[46:49]
	s_barrier
	s_add_u32 s12, s12, 0x100
	s_addc_u32 s13, s13, 0
	s_cmp_ge_u32 s42, s19
	s_mov_b32 s15, s42
	s_cbranch_scc0 .LBB0_1432
	s_lshl_b32 s4, s18, 21
	v_readlane_b32 s0, v249, 29
	v_lshl_or_b32 v130, s20, 8, v148
	v_mov_b32_e32 v139, 0
	s_add_u32 s4, s0, s4
	v_readlane_b32 s0, v249, 31
	v_or_b32_e32 v130, s25, v130
	v_cvt_pk_bf16_f32 v70, v70, v71
	v_cvt_pk_bf16_f32 v71, v72, v73
	v_cvt_pk_bf16_f32 v72, v66, v67
	v_add_u32_e32 v66, 0x80, v138
	v_mov_b32_e32 v67, v139
	s_addc_u32 s5, s0, 0
	v_ashrrev_i32_e32 v131, 31, v130
	v_lshlrev_b64 v[132:133], 13, v[138:139]
	v_cvt_pk_bf16_f32 v110, v110, v111
	v_cvt_pk_bf16_f32 v111, v112, v113
	v_cvt_pk_bf16_f32 v112, v106, v107
	v_or_b32_e32 v106, 16, v138
	v_mov_b32_e32 v107, v139
	v_lshlrev_b64 v[66:67], 13, v[66:67]
	v_cvt_pk_bf16_f32 v46, v46, v47
	v_cvt_pk_bf16_f32 v47, v48, v49
	v_cvt_pk_bf16_f32 v48, v42, v43
	v_add_u32_e32 v42, 0x90, v138
	v_mov_b32_e32 v43, v139
	v_lshl_add_u64 v[132:133], s[4:5], 0, v[132:133]
	v_lshlrev_b64 v[130:131], 1, v[130:131]
	v_lshlrev_b64 v[106:107], 13, v[106:107]
	v_cvt_pk_bf16_f32 v94, v94, v95
	v_cvt_pk_bf16_f32 v95, v96, v97
	v_cvt_pk_bf16_f32 v96, v90, v91
	v_or_b32_e32 v90, 32, v138
	v_mov_b32_e32 v91, v139
	v_lshl_add_u64 v[66:67], s[4:5], 0, v[66:67]
	v_lshlrev_b64 v[42:43], 13, v[42:43]
	v_cvt_pk_bf16_f32 v30, v30, v31
	v_cvt_pk_bf16_f32 v31, v32, v33
	v_cvt_pk_bf16_f32 v32, v26, v27
	v_add_u32_e32 v26, 0xa0, v138
	v_mov_b32_e32 v27, v139
	v_lshl_add_u64 v[132:133], v[132:133], 0, v[130:131]
	v_cvt_pk_bf16_f32 v113, v108, v109
	v_lshl_add_u64 v[106:107], s[4:5], 0, v[106:107]
	v_lshlrev_b64 v[90:91], 13, v[90:91]
	v_cvt_pk_bf16_f32 v78, v78, v79
	v_cvt_pk_bf16_f32 v79, v80, v81
	v_cvt_pk_bf16_f32 v80, v74, v75
	v_or_b32_e32 v74, 48, v138
	v_mov_b32_e32 v75, v139
	v_lshl_add_u64 v[66:67], v[66:67], 0, v[130:131]
	v_cvt_pk_bf16_f32 v49, v44, v45
	v_lshl_add_u64 v[42:43], s[4:5], 0, v[42:43]
	v_lshlrev_b64 v[26:27], 13, v[26:27]
	v_add_u32_e32 v138, 0xb0, v138
	global_store_dwordx4 v[132:133], v[110:113], off offset:256
	v_cvt_pk_bf16_f32 v97, v92, v93
	v_lshl_add_u64 v[90:91], s[4:5], 0, v[90:91]
	v_lshl_add_u64 v[110:111], v[106:107], 0, v[130:131]
	v_lshlrev_b64 v[74:75], 13, v[74:75]
	global_store_dwordx4 v[66:67], v[46:49], off offset:256
	v_cvt_pk_bf16_f32 v33, v28, v29
	v_lshl_add_u64 v[26:27], s[4:5], 0, v[26:27]
	v_lshl_add_u64 v[46:47], v[42:43], 0, v[130:131]
	v_cvt_pk_bf16_f32 v14, v14, v15
	v_cvt_pk_bf16_f32 v15, v16, v17
	v_cvt_pk_bf16_f32 v16, v10, v11
	v_lshlrev_b64 v[10:11], 13, v[138:139]
	global_store_dwordx4 v[110:111], v[94:97], off offset:256
	v_cvt_pk_bf16_f32 v81, v76, v77
	v_lshl_add_u64 v[74:75], s[4:5], 0, v[74:75]
	v_lshl_add_u64 v[94:95], v[90:91], 0, v[130:131]
	global_store_dwordx4 v[46:47], v[30:33], off offset:256
	v_cvt_pk_bf16_f32 v17, v12, v13
	v_lshl_add_u64 v[10:11], s[4:5], 0, v[10:11]
	v_lshl_add_u64 v[30:31], v[26:27], 0, v[130:131]
	v_cvt_pk_bf16_f32 v126, v126, v127
	v_cvt_pk_bf16_f32 v127, v128, v129
	v_cvt_pk_bf16_f32 v128, v122, v123
	v_cvt_pk_bf16_f32 v129, v124, v125
	v_cvt_pk_bf16_f32 v106, v118, v119
	v_cvt_pk_bf16_f32 v107, v120, v121
	v_cvt_pk_bf16_f32 v108, v114, v115
	v_cvt_pk_bf16_f32 v109, v116, v117
	v_cvt_pk_bf16_f32 v90, v102, v103
	v_cvt_pk_bf16_f32 v91, v104, v105
	v_cvt_pk_bf16_f32 v92, v98, v99
	v_cvt_pk_bf16_f32 v93, v100, v101
	global_store_dwordx4 v[94:95], v[78:81], off offset:256
	v_cvt_pk_bf16_f32 v76, v82, v83
	v_cvt_pk_bf16_f32 v77, v84, v85
	v_lshl_add_u64 v[78:79], v[74:75], 0, v[130:131]
	v_cvt_pk_bf16_f32 v74, v86, v87
	v_cvt_pk_bf16_f32 v75, v88, v89
	v_cvt_pk_bf16_f32 v73, v68, v69
	v_cvt_pk_bf16_f32 v62, v62, v63
	v_cvt_pk_bf16_f32 v63, v64, v65
	v_cvt_pk_bf16_f32 v64, v58, v59
	v_cvt_pk_bf16_f32 v65, v60, v61
	v_cvt_pk_bf16_f32 v42, v54, v55
	v_cvt_pk_bf16_f32 v43, v56, v57
	v_cvt_pk_bf16_f32 v44, v50, v51
	v_cvt_pk_bf16_f32 v45, v52, v53
	v_cvt_pk_bf16_f32 v26, v38, v39
	v_cvt_pk_bf16_f32 v27, v40, v41
	v_cvt_pk_bf16_f32 v28, v34, v35
	v_cvt_pk_bf16_f32 v29, v36, v37
	global_store_dwordx4 v[30:31], v[14:17], off offset:256
	v_cvt_pk_bf16_f32 v12, v18, v19
	v_cvt_pk_bf16_f32 v13, v20, v21
	v_lshl_add_u64 v[14:15], v[10:11], 0, v[130:131]
	v_cvt_pk_bf16_f32 v10, v22, v23
	v_cvt_pk_bf16_f32 v11, v24, v25
	v_cvt_pk_bf16_f32 v6, v6, v7
	v_cvt_pk_bf16_f32 v7, v8, v9
	v_cvt_pk_bf16_f32 v8, v2, v3
	v_cvt_pk_bf16_f32 v9, v4, v5
	global_store_dwordx4 v[132:133], v[126:129], off
	global_store_dwordx4 v[110:111], v[106:109], off
	global_store_dwordx4 v[94:95], v[90:93], off
	global_store_dwordx4 v[78:79], v[74:77], off
	global_store_dwordx4 v[78:79], v[70:73], off offset:256
	global_store_dwordx4 v[66:67], v[62:65], off
	global_store_dwordx4 v[46:47], v[42:45], off
	global_store_dwordx4 v[30:31], v[26:29], off
	global_store_dwordx4 v[14:15], v[10:13], off
	global_store_dwordx4 v[14:15], v[6:9], off offset:256
	s_waitcnt vmcnt(0)
	s_cmpk_lt_u32 s3, 0x100
	s_cbranch_scc0 .LBB0_1435
	s_barrier

.LBB0_1565:
	ds_read_b128 v[130:133], v204
	ds_read_b128 v[134:137], v204 offset:1024
	ds_read_b128 v[138:141], v204 offset:2048
	ds_read_b128 v[142:145], v204 offset:3072
	ds_read_b128 v[146:149], v205
	ds_read_b128 v[150:153], v205 offset:1024
	ds_read_b128 v[154:157], v205 offset:2048
	ds_read_b128 v[158:161], v205 offset:3072
	s_add_u32 s8, s6, 0xfff00080
	s_addc_u32 s9, s7, -1
	s_cmp_eq_u32 s66, 60
	s_cselect_b32 s73, s41, s9
	s_cselect_b32 s72, s50, s8
	s_cselect_b32 s9, s13, s57
	s_cselect_b32 s8, s51, s56
	s_add_i32 m0, s42, 0xc000
	ds_read_b128 v[184:187], v206
	ds_read_b128 v[188:191], v206 offset:1024
	ds_read_b128 v[192:195], v206 offset:2048
	ds_read_b128 v[210:213], v206 offset:3072
	ds_read_b128 v[214:217], v206 offset:4096
	ds_read_b128 v[218:221], v206 offset:5120
	ds_read_b128 v[222:225], v206 offset:6144
	ds_read_b128 v[226:229], v206 offset:7168
	global_load_lds_dwordx4 v180, s[6:7]
	s_add_i32 m0, s42, 0xe000
	s_nop 0
	global_load_lds_dwordx4 v182, s[6:7]
	s_waitcnt vmcnt(8)
	s_waitcnt lgkmcnt(0)
	s_barrier
	s_waitcnt lgkmcnt(0)
	v_mfma_f32_16x16x32_bf16 v[126:129], v[130:133], v[184:187], v[126:129]
	v_mfma_f32_16x16x32_bf16 v[126:129], v[134:137], v[188:191], v[126:129]
	v_mfma_f32_16x16x32_bf16 v[122:125], v[142:145], v[188:191], v[122:125]
	v_mfma_f32_16x16x32_bf16 v[122:125], v[138:141], v[184:187], v[122:125]
	v_mfma_f32_16x16x32_bf16 v[106:109], v[138:141], v[192:195], v[106:109]
	v_mfma_f32_16x16x32_bf16 v[106:109], v[142:145], v[210:213], v[106:109]
	v_mfma_f32_16x16x32_bf16 v[110:113], v[134:137], v[210:213], v[110:113]
	v_mfma_f32_16x16x32_bf16 v[110:113], v[130:133], v[192:195], v[110:113]
	v_mfma_f32_16x16x32_bf16 v[94:97], v[130:133], v[214:217], v[94:97]
	v_mfma_f32_16x16x32_bf16 v[94:97], v[134:137], v[218:221], v[94:97]
	v_mfma_f32_16x16x32_bf16 v[90:93], v[142:145], v[218:221], v[90:93]
	v_mfma_f32_16x16x32_bf16 v[90:93], v[138:141], v[214:217], v[90:93]
	v_mfma_f32_16x16x32_bf16 v[74:77], v[138:141], v[222:225], v[74:77]
	v_mfma_f32_16x16x32_bf16 v[74:77], v[142:145], v[226:229], v[74:77]
	v_mfma_f32_16x16x32_bf16 v[78:81], v[134:137], v[226:229], v[78:81]
	v_mfma_f32_16x16x32_bf16 v[78:81], v[130:133], v[222:225], v[78:81]
	v_mfma_f32_16x16x32_bf16 v[70:73], v[146:149], v[222:225], v[70:73]
	v_mfma_f32_16x16x32_bf16 v[70:73], v[150:153], v[226:229], v[70:73]
	v_mfma_f32_16x16x32_bf16 v[66:69], v[158:161], v[226:229], v[66:69]
	v_mfma_f32_16x16x32_bf16 v[66:69], v[154:157], v[222:225], v[66:69]
	v_mfma_f32_16x16x32_bf16 v[82:85], v[154:157], v[214:217], v[82:85]
	v_mfma_f32_16x16x32_bf16 v[82:85], v[158:161], v[218:221], v[82:85]
	v_mfma_f32_16x16x32_bf16 v[86:89], v[150:153], v[218:221], v[86:89]
	v_mfma_f32_16x16x32_bf16 v[86:89], v[146:149], v[214:217], v[86:89]
	v_mfma_f32_16x16x32_bf16 v[102:105], v[146:149], v[192:195], v[102:105]
	v_mfma_f32_16x16x32_bf16 v[102:105], v[150:153], v[210:213], v[102:105]
	v_mfma_f32_16x16x32_bf16 v[98:101], v[158:161], v[210:213], v[98:101]
	v_mfma_f32_16x16x32_bf16 v[98:101], v[154:157], v[192:195], v[98:101]
	v_mfma_f32_16x16x32_bf16 v[114:117], v[154:157], v[184:187], v[114:117]
	v_mfma_f32_16x16x32_bf16 v[114:117], v[158:161], v[188:191], v[114:117]
	v_mfma_f32_16x16x32_bf16 v[118:121], v[150:153], v[188:191], v[118:121]
	v_mfma_f32_16x16x32_bf16 v[118:121], v[146:149], v[184:187], v[118:121]
	s_barrier
	s_add_i32 s67, s54, s35
	s_mov_b32 m0, s67
	ds_read_b128 v[184:187], v206 offset:16384
	ds_read_b128 v[188:191], v206 offset:17408
	ds_read_b128 v[192:195], v206 offset:18432
	ds_read_b128 v[210:213], v206 offset:19456
	ds_read_b128 v[214:217], v206 offset:20480
	ds_read_b128 v[218:221], v206 offset:21504
	ds_read_b128 v[222:225], v206 offset:22528
	ds_read_b128 v[226:229], v206 offset:23552
	global_load_lds_dwordx4 v168, s[8:9]
	s_add_i32 m0, s67, 0x2000
	s_add_u32 s68, s8, 0x100000
	s_addc_u32 s69, s9, 0
	s_add_i32 s67, s55, s35
	global_load_lds_dwordx4 v170, s[8:9]
	s_mov_b32 m0, s67
	s_nop 0
	global_load_lds_dwordx4 v168, s[68:69]
	s_add_i32 m0, s67, 0x2000
	s_nop 0
	global_load_lds_dwordx4 v170, s[68:69]
	s_mov_b32 m0, s42
	s_nop 0
	global_load_lds_dwordx4 v168, s[72:73]
	s_mov_b32 m0, s43
	s_nop 0
	global_load_lds_dwordx4 v170, s[72:73]
	s_waitcnt vmcnt(8)
	s_waitcnt lgkmcnt(0)
	s_barrier
	s_waitcnt lgkmcnt(0)
	v_mfma_f32_16x16x32_bf16 v[62:65], v[130:133], v[184:187], v[62:65]
	v_mfma_f32_16x16x32_bf16 v[62:65], v[134:137], v[188:191], v[62:65]
	v_mfma_f32_16x16x32_bf16 v[58:61], v[142:145], v[188:191], v[58:61]
	v_mfma_f32_16x16x32_bf16 v[58:61], v[138:141], v[184:187], v[58:61]
	v_mfma_f32_16x16x32_bf16 v[42:45], v[138:141], v[192:195], v[42:45]
	v_mfma_f32_16x16x32_bf16 v[42:45], v[142:145], v[210:213], v[42:45]
	v_mfma_f32_16x16x32_bf16 v[46:49], v[134:137], v[210:213], v[46:49]
	v_mfma_f32_16x16x32_bf16 v[46:49], v[130:133], v[192:195], v[46:49]
	v_mfma_f32_16x16x32_bf16 v[30:33], v[130:133], v[214:217], v[30:33]
	v_mfma_f32_16x16x32_bf16 v[30:33], v[134:137], v[218:221], v[30:33]
	v_mfma_f32_16x16x32_bf16 v[26:29], v[142:145], v[218:221], v[26:29]
	v_mfma_f32_16x16x32_bf16 v[26:29], v[138:141], v[214:217], v[26:29]
	v_mfma_f32_16x16x32_bf16 v[10:13], v[138:141], v[222:225], v[10:13]
	v_mfma_f32_16x16x32_bf16 v[10:13], v[142:145], v[226:229], v[10:13]
	v_mfma_f32_16x16x32_bf16 v[14:17], v[134:137], v[226:229], v[14:17]
	v_mfma_f32_16x16x32_bf16 v[14:17], v[130:133], v[222:225], v[14:17]
	v_mfma_f32_16x16x32_bf16 v[6:9], v[146:149], v[222:225], v[6:9]
	v_mfma_f32_16x16x32_bf16 v[6:9], v[150:153], v[226:229], v[6:9]
	v_mfma_f32_16x16x32_bf16 v[2:5], v[158:161], v[226:229], v[2:5]
	v_mfma_f32_16x16x32_bf16 v[2:5], v[154:157], v[222:225], v[2:5]
	v_mfma_f32_16x16x32_bf16 v[18:21], v[154:157], v[214:217], v[18:21]
	v_mfma_f32_16x16x32_bf16 v[18:21], v[158:161], v[218:221], v[18:21]
	v_mfma_f32_16x16x32_bf16 v[22:25], v[150:153], v[218:221], v[22:25]
	v_mfma_f32_16x16x32_bf16 v[22:25], v[146:149], v[214:217], v[22:25]
	v_mfma_f32_16x16x32_bf16 v[38:41], v[146:149], v[192:195], v[38:41]
	v_mfma_f32_16x16x32_bf16 v[38:41], v[150:153], v[210:213], v[38:41]
	v_mfma_f32_16x16x32_bf16 v[34:37], v[158:161], v[210:213], v[34:37]
	v_mfma_f32_16x16x32_bf16 v[34:37], v[154:157], v[192:195], v[34:37]
	v_mfma_f32_16x16x32_bf16 v[50:53], v[154:157], v[184:187], v[50:53]
	v_mfma_f32_16x16x32_bf16 v[50:53], v[158:161], v[188:191], v[50:53]
	v_mfma_f32_16x16x32_bf16 v[54:57], v[150:153], v[188:191], v[54:57]
	v_mfma_f32_16x16x32_bf16 v[54:57], v[146:149], v[184:187], v[54:57]
	s_barrier
	s_add_i32 s67, 0, 0x18000
	s_add_i32 s70, 0, 0x1c000
	v_add_u32_e32 v142, s67, v203
	v_add_u32_e32 v158, s70, v203
	ds_read_b128 v[130:133], v142
	ds_read_b128 v[134:137], v142 offset:1024
	ds_read_b128 v[138:141], v142 offset:2048
	ds_read_b128 v[142:145], v142 offset:3072
	ds_read_b128 v[146:149], v158
	ds_read_b128 v[150:153], v158 offset:1024
	ds_read_b128 v[154:157], v158 offset:2048
	ds_read_b128 v[158:161], v158 offset:3072
	s_add_u32 s68, s72, 0x100000
	s_addc_u32 s69, s73, 0
	s_mov_b32 m0, s44
	ds_read_b128 v[184:187], v206 offset:32768
	ds_read_b128 v[188:191], v206 offset:33792
	ds_read_b128 v[192:195], v206 offset:34816
	ds_read_b128 v[210:213], v206 offset:35840
	ds_read_b128 v[214:217], v206 offset:36864
	ds_read_b128 v[218:221], v206 offset:37888
	ds_read_b128 v[222:225], v206 offset:38912
	ds_read_b128 v[226:229], v206 offset:39936
	global_load_lds_dwordx4 v168, s[68:69]
	s_mov_b32 m0, s45
	s_nop 0
	global_load_lds_dwordx4 v170, s[68:69]
	s_waitcnt vmcnt(8)
	s_waitcnt lgkmcnt(0)
	s_barrier
	s_waitcnt lgkmcnt(0)
	v_mfma_f32_16x16x32_bf16 v[126:129], v[130:133], v[184:187], v[126:129]
	v_mfma_f32_16x16x32_bf16 v[126:129], v[134:137], v[188:191], v[126:129]
	v_mfma_f32_16x16x32_bf16 v[122:125], v[142:145], v[188:191], v[122:125]
	v_mfma_f32_16x16x32_bf16 v[122:125], v[138:141], v[184:187], v[122:125]
	v_mfma_f32_16x16x32_bf16 v[106:109], v[138:141], v[192:195], v[106:109]
	v_mfma_f32_16x16x32_bf16 v[106:109], v[142:145], v[210:213], v[106:109]
	v_mfma_f32_16x16x32_bf16 v[110:113], v[134:137], v[210:213], v[110:113]
	v_mfma_f32_16x16x32_bf16 v[110:113], v[130:133], v[192:195], v[110:113]
	v_mfma_f32_16x16x32_bf16 v[94:97], v[130:133], v[214:217], v[94:97]
	v_mfma_f32_16x16x32_bf16 v[94:97], v[134:137], v[218:221], v[94:97]
	v_mfma_f32_16x16x32_bf16 v[90:93], v[142:145], v[218:221], v[90:93]
	v_mfma_f32_16x16x32_bf16 v[90:93], v[138:141], v[214:217], v[90:93]
	v_mfma_f32_16x16x32_bf16 v[74:77], v[138:141], v[222:225], v[74:77]
	v_mfma_f32_16x16x32_bf16 v[74:77], v[142:145], v[226:229], v[74:77]
	v_mfma_f32_16x16x32_bf16 v[78:81], v[134:137], v[226:229], v[78:81]
	v_mfma_f32_16x16x32_bf16 v[78:81], v[130:133], v[222:225], v[78:81]
	v_mfma_f32_16x16x32_bf16 v[70:73], v[146:149], v[222:225], v[70:73]
	v_mfma_f32_16x16x32_bf16 v[70:73], v[150:153], v[226:229], v[70:73]
	v_mfma_f32_16x16x32_bf16 v[66:69], v[158:161], v[226:229], v[66:69]
	v_mfma_f32_16x16x32_bf16 v[66:69], v[154:157], v[222:225], v[66:69]
	v_mfma_f32_16x16x32_bf16 v[82:85], v[154:157], v[214:217], v[82:85]
	v_mfma_f32_16x16x32_bf16 v[82:85], v[158:161], v[218:221], v[82:85]
	v_mfma_f32_16x16x32_bf16 v[86:89], v[150:153], v[218:221], v[86:89]
	v_mfma_f32_16x16x32_bf16 v[86:89], v[146:149], v[214:217], v[86:89]
	v_mfma_f32_16x16x32_bf16 v[102:105], v[146:149], v[192:195], v[102:105]
	v_mfma_f32_16x16x32_bf16 v[102:105], v[150:153], v[210:213], v[102:105]
	v_mfma_f32_16x16x32_bf16 v[98:101], v[158:161], v[210:213], v[98:101]
	v_mfma_f32_16x16x32_bf16 v[98:101], v[154:157], v[192:195], v[98:101]
	v_mfma_f32_16x16x32_bf16 v[114:117], v[154:157], v[184:187], v[114:117]
	v_mfma_f32_16x16x32_bf16 v[114:117], v[158:161], v[188:191], v[114:117]
	v_mfma_f32_16x16x32_bf16 v[118:121], v[150:153], v[188:191], v[118:121]
	v_mfma_f32_16x16x32_bf16 v[118:121], v[146:149], v[184:187], v[118:121]
	s_barrier
	s_add_u32 s68, s72, 0x80
	s_addc_u32 s69, s73, 0
	s_add_u32 s8, s8, 0x80
	s_addc_u32 s9, s9, 0
	s_add_i32 s67, s67, s35
	s_mov_b32 m0, s67
	ds_read_b128 v[184:187], v206 offset:49152
	ds_read_b128 v[188:191], v206 offset:50176
	ds_read_b128 v[192:195], v206 offset:51200
	ds_read_b128 v[210:213], v206 offset:52224
	ds_read_b128 v[214:217], v206 offset:53248
	ds_read_b128 v[218:221], v206 offset:54272
	ds_read_b128 v[222:225], v206 offset:55296
	ds_read_b128 v[226:229], v206 offset:56320
	global_load_lds_dwordx4 v168, s[8:9]
	s_add_i32 m0, s67, 0x2000
	s_add_i32 s67, s70, s35
	global_load_lds_dwordx4 v170, s[8:9]
	s_add_u32 s8, s8, 0x100000
	s_addc_u32 s9, s9, 0
	s_mov_b32 m0, s67
	s_nop 0
	global_load_lds_dwordx4 v168, s[8:9]
	s_add_i32 m0, s67, 0x2000
	s_nop 0
	global_load_lds_dwordx4 v170, s[8:9]
	s_mov_b32 m0, s48
	s_nop 0
	global_load_lds_dwordx4 v168, s[68:69]
	s_mov_b32 m0, s49
	s_nop 0
	global_load_lds_dwordx4 v170, s[68:69]
	s_waitcnt vmcnt(8)
	s_waitcnt lgkmcnt(0)
	s_barrier
	s_waitcnt lgkmcnt(0)
	v_mfma_f32_16x16x32_bf16 v[62:65], v[130:133], v[184:187], v[62:65]
	v_mfma_f32_16x16x32_bf16 v[62:65], v[134:137], v[188:191], v[62:65]
	v_mfma_f32_16x16x32_bf16 v[58:61], v[142:145], v[188:191], v[58:61]
	v_mfma_f32_16x16x32_bf16 v[58:61], v[138:141], v[184:187], v[58:61]
	v_mfma_f32_16x16x32_bf16 v[42:45], v[138:141], v[192:195], v[42:45]
	v_mfma_f32_16x16x32_bf16 v[42:45], v[142:145], v[210:213], v[42:45]
	v_mfma_f32_16x16x32_bf16 v[46:49], v[134:137], v[210:213], v[46:49]
	v_mfma_f32_16x16x32_bf16 v[46:49], v[130:133], v[192:195], v[46:49]
	v_mfma_f32_16x16x32_bf16 v[30:33], v[130:133], v[214:217], v[30:33]
	v_mfma_f32_16x16x32_bf16 v[30:33], v[134:137], v[218:221], v[30:33]
	v_mfma_f32_16x16x32_bf16 v[26:29], v[142:145], v[218:221], v[26:29]
	v_mfma_f32_16x16x32_bf16 v[26:29], v[138:141], v[214:217], v[26:29]
	v_mfma_f32_16x16x32_bf16 v[10:13], v[138:141], v[222:225], v[10:13]
	v_mfma_f32_16x16x32_bf16 v[10:13], v[142:145], v[226:229], v[10:13]
	v_mfma_f32_16x16x32_bf16 v[14:17], v[134:137], v[226:229], v[14:17]
	v_mfma_f32_16x16x32_bf16 v[14:17], v[130:133], v[222:225], v[14:17]
	v_mfma_f32_16x16x32_bf16 v[6:9], v[146:149], v[222:225], v[6:9]
	v_mfma_f32_16x16x32_bf16 v[6:9], v[150:153], v[226:229], v[6:9]
	v_mfma_f32_16x16x32_bf16 v[2:5], v[158:161], v[226:229], v[2:5]
	v_mfma_f32_16x16x32_bf16 v[2:5], v[154:157], v[222:225], v[2:5]
	v_mfma_f32_16x16x32_bf16 v[18:21], v[154:157], v[214:217], v[18:21]
	v_mfma_f32_16x16x32_bf16 v[18:21], v[158:161], v[218:221], v[18:21]
	v_mfma_f32_16x16x32_bf16 v[22:25], v[150:153], v[218:221], v[22:25]
	v_mfma_f32_16x16x32_bf16 v[22:25], v[146:149], v[214:217], v[22:25]
	v_mfma_f32_16x16x32_bf16 v[38:41], v[146:149], v[192:195], v[38:41]
	v_mfma_f32_16x16x32_bf16 v[38:41], v[150:153], v[210:213], v[38:41]
	v_mfma_f32_16x16x32_bf16 v[34:37], v[158:161], v[210:213], v[34:37]
	v_mfma_f32_16x16x32_bf16 v[34:37], v[154:157], v[192:195], v[34:37]
	v_mfma_f32_16x16x32_bf16 v[50:53], v[154:157], v[184:187], v[50:53]
	v_mfma_f32_16x16x32_bf16 v[50:53], v[158:161], v[188:191], v[50:53]
	v_mfma_f32_16x16x32_bf16 v[54:57], v[150:153], v[188:191], v[54:57]
	v_mfma_f32_16x16x32_bf16 v[54:57], v[146:149], v[184:187], v[54:57]
	s_barrier
	s_add_i32 s66, s66, 2
	s_add_u32 s6, s6, 0x100
	s_addc_u32 s7, s7, 0
	s_add_u32 s56, s56, 0x100
	s_addc_u32 s57, s57, 0
	s_cmp_gt_u32 s66, 61
	s_cbranch_scc0 .LBB0_1565
	s_and_b64 vcc, exec, s[24:25]
	s_cbranch_vccz .LBB0_1568
	s_barrier

.LBB0_2230:
	ds_read_b128 v[142:145], v154
	ds_read_b128 v[158:161], v154 offset:1024
	ds_read_b128 v[168:171], v154 offset:2048
	ds_read_b128 v[176:179], v154 offset:3072
	ds_read_b128 v[180:183], v155
	ds_read_b128 v[184:187], v155 offset:1024
	ds_read_b128 v[188:191], v155 offset:2048
	ds_read_b128 v[192:195], v155 offset:3072
	s_add_u32 s24, s22, 0xfff00080
	s_addc_u32 s25, s23, -1
	s_cmp_eq_u32 s48, 60
	s_cselect_b32 s27, s19, s25
	s_cselect_b32 s26, s44, s24
	s_cselect_b32 s25, s7, s47
	s_cselect_b32 s24, s45, s46
	s_mov_b32 m0, s40
	ds_read_b128 v[204:207], v156
	ds_read_b128 v[208:211], v156 offset:1024
	ds_read_b128 v[212:215], v156 offset:2048
	ds_read_b128 v[216:219], v156 offset:3072
	ds_read_b128 v[220:223], v156 offset:4096
	ds_read_b128 v[224:227], v156 offset:5120
	ds_read_b128 v[228:231], v156 offset:6144
	ds_read_b128 v[232:235], v156 offset:7168
	global_load_lds_dwordx4 v138, s[22:23]
	s_mov_b32 m0, s41
	s_nop 0
	global_load_lds_dwordx4 v140, s[22:23]
	s_waitcnt vmcnt(8)
	s_waitcnt lgkmcnt(0)
	s_barrier
	s_waitcnt lgkmcnt(0)
	v_mfma_f32_16x16x32_bf16 v[126:129], v[142:145], v[204:207], v[126:129]
	v_mfma_f32_16x16x32_bf16 v[126:129], v[158:161], v[208:211], v[126:129]
	v_mfma_f32_16x16x32_bf16 v[122:125], v[176:179], v[208:211], v[122:125]
	v_mfma_f32_16x16x32_bf16 v[122:125], v[168:171], v[204:207], v[122:125]
	v_mfma_f32_16x16x32_bf16 v[106:109], v[168:171], v[212:215], v[106:109]
	v_mfma_f32_16x16x32_bf16 v[106:109], v[176:179], v[216:219], v[106:109]
	v_mfma_f32_16x16x32_bf16 v[110:113], v[158:161], v[216:219], v[110:113]
	v_mfma_f32_16x16x32_bf16 v[110:113], v[142:145], v[212:215], v[110:113]
	v_mfma_f32_16x16x32_bf16 v[94:97], v[142:145], v[220:223], v[94:97]
	v_mfma_f32_16x16x32_bf16 v[94:97], v[158:161], v[224:227], v[94:97]
	v_mfma_f32_16x16x32_bf16 v[90:93], v[176:179], v[224:227], v[90:93]
	v_mfma_f32_16x16x32_bf16 v[90:93], v[168:171], v[220:223], v[90:93]
	v_mfma_f32_16x16x32_bf16 v[74:77], v[168:171], v[228:231], v[74:77]
	v_mfma_f32_16x16x32_bf16 v[74:77], v[176:179], v[232:235], v[74:77]
	v_mfma_f32_16x16x32_bf16 v[78:81], v[158:161], v[232:235], v[78:81]
	v_mfma_f32_16x16x32_bf16 v[78:81], v[142:145], v[228:231], v[78:81]
	v_mfma_f32_16x16x32_bf16 v[70:73], v[180:183], v[228:231], v[70:73]
	v_mfma_f32_16x16x32_bf16 v[70:73], v[184:187], v[232:235], v[70:73]
	v_mfma_f32_16x16x32_bf16 v[66:69], v[192:195], v[232:235], v[66:69]
	v_mfma_f32_16x16x32_bf16 v[66:69], v[188:191], v[228:231], v[66:69]
	v_mfma_f32_16x16x32_bf16 v[82:85], v[188:191], v[220:223], v[82:85]
	v_mfma_f32_16x16x32_bf16 v[82:85], v[192:195], v[224:227], v[82:85]
	v_mfma_f32_16x16x32_bf16 v[86:89], v[184:187], v[224:227], v[86:89]
	v_mfma_f32_16x16x32_bf16 v[86:89], v[180:183], v[220:223], v[86:89]
	v_mfma_f32_16x16x32_bf16 v[102:105], v[180:183], v[212:215], v[102:105]
	v_mfma_f32_16x16x32_bf16 v[102:105], v[184:187], v[216:219], v[102:105]
	v_mfma_f32_16x16x32_bf16 v[98:101], v[192:195], v[216:219], v[98:101]
	v_mfma_f32_16x16x32_bf16 v[98:101], v[188:191], v[212:215], v[98:101]
	v_mfma_f32_16x16x32_bf16 v[114:117], v[188:191], v[204:207], v[114:117]
	v_mfma_f32_16x16x32_bf16 v[114:117], v[192:195], v[208:211], v[114:117]
	v_mfma_f32_16x16x32_bf16 v[118:121], v[184:187], v[208:211], v[118:121]
	v_mfma_f32_16x16x32_bf16 v[118:121], v[180:183], v[204:207], v[118:121]
	s_barrier
	s_add_i32 s49, s38, s28
	s_mov_b32 m0, s49
	ds_read_b128 v[204:207], v156 offset:16384
	ds_read_b128 v[208:211], v156 offset:17408
	ds_read_b128 v[212:215], v156 offset:18432
	ds_read_b128 v[216:219], v156 offset:19456
	ds_read_b128 v[220:223], v156 offset:20480
	ds_read_b128 v[224:227], v156 offset:21504
	ds_read_b128 v[228:231], v156 offset:22528
	ds_read_b128 v[232:235], v156 offset:23552
	global_load_lds_dwordx4 v132, s[24:25]
	s_add_i32 m0, s49, 0x2000
	s_add_u32 s50, s24, 0x100000
	s_addc_u32 s51, s25, 0
	s_add_i32 s49, s39, s28
	global_load_lds_dwordx4 v136, s[24:25]
	s_mov_b32 m0, s49
	s_nop 0
	global_load_lds_dwordx4 v132, s[50:51]
	s_add_i32 m0, s49, 0x2000
	s_nop 0
	global_load_lds_dwordx4 v136, s[50:51]
	s_mov_b32 m0, s30
	s_nop 0
	global_load_lds_dwordx4 v130, s[26:27]
	s_mov_b32 m0, s31
	s_nop 0
	global_load_lds_dwordx4 v134, s[26:27]
	s_waitcnt vmcnt(8)
	s_waitcnt lgkmcnt(0)
	s_barrier
	s_waitcnt lgkmcnt(0)
	v_mfma_f32_16x16x32_bf16 v[62:65], v[142:145], v[204:207], v[62:65]
	v_mfma_f32_16x16x32_bf16 v[62:65], v[158:161], v[208:211], v[62:65]
	v_mfma_f32_16x16x32_bf16 v[58:61], v[176:179], v[208:211], v[58:61]
	v_mfma_f32_16x16x32_bf16 v[58:61], v[168:171], v[204:207], v[58:61]
	v_mfma_f32_16x16x32_bf16 v[42:45], v[168:171], v[212:215], v[42:45]
	v_mfma_f32_16x16x32_bf16 v[42:45], v[176:179], v[216:219], v[42:45]
	v_mfma_f32_16x16x32_bf16 v[46:49], v[158:161], v[216:219], v[46:49]
	v_mfma_f32_16x16x32_bf16 v[46:49], v[142:145], v[212:215], v[46:49]
	v_mfma_f32_16x16x32_bf16 v[30:33], v[142:145], v[220:223], v[30:33]
	v_mfma_f32_16x16x32_bf16 v[30:33], v[158:161], v[224:227], v[30:33]
	v_mfma_f32_16x16x32_bf16 v[26:29], v[176:179], v[224:227], v[26:29]
	v_mfma_f32_16x16x32_bf16 v[26:29], v[168:171], v[220:223], v[26:29]
	v_mfma_f32_16x16x32_bf16 v[10:13], v[168:171], v[228:231], v[10:13]
	v_mfma_f32_16x16x32_bf16 v[10:13], v[176:179], v[232:235], v[10:13]
	v_mfma_f32_16x16x32_bf16 v[14:17], v[158:161], v[232:235], v[14:17]
	v_mfma_f32_16x16x32_bf16 v[14:17], v[142:145], v[228:231], v[14:17]
	v_mfma_f32_16x16x32_bf16 v[6:9], v[180:183], v[228:231], v[6:9]
	v_mfma_f32_16x16x32_bf16 v[6:9], v[184:187], v[232:235], v[6:9]
	v_mfma_f32_16x16x32_bf16 v[2:5], v[192:195], v[232:235], v[2:5]
	v_mfma_f32_16x16x32_bf16 v[2:5], v[188:191], v[228:231], v[2:5]
	v_mfma_f32_16x16x32_bf16 v[18:21], v[188:191], v[220:223], v[18:21]
	v_mfma_f32_16x16x32_bf16 v[18:21], v[192:195], v[224:227], v[18:21]
	v_mfma_f32_16x16x32_bf16 v[22:25], v[184:187], v[224:227], v[22:25]
	v_mfma_f32_16x16x32_bf16 v[22:25], v[180:183], v[220:223], v[22:25]
	v_mfma_f32_16x16x32_bf16 v[38:41], v[180:183], v[212:215], v[38:41]
	v_mfma_f32_16x16x32_bf16 v[38:41], v[184:187], v[216:219], v[38:41]
	v_mfma_f32_16x16x32_bf16 v[34:37], v[192:195], v[216:219], v[34:37]
	v_mfma_f32_16x16x32_bf16 v[34:37], v[188:191], v[212:215], v[34:37]
	v_mfma_f32_16x16x32_bf16 v[50:53], v[188:191], v[204:207], v[50:53]
	v_mfma_f32_16x16x32_bf16 v[50:53], v[192:195], v[208:211], v[50:53]
	v_mfma_f32_16x16x32_bf16 v[54:57], v[184:187], v[208:211], v[54:57]
	v_mfma_f32_16x16x32_bf16 v[54:57], v[180:183], v[204:207], v[54:57]
	s_barrier
	s_add_i32 s49, 0, 0x18000
	v_add_u32_e32 v157, s49, v152
	s_add_i32 s50, 0, 0x1c000
	ds_read_b128 v[142:145], v157
	ds_read_b128 v[158:161], v157 offset:1024
	ds_read_b128 v[168:171], v157 offset:2048
	ds_read_b128 v[176:179], v157 offset:3072
	v_add_u32_e32 v157, s50, v152
	ds_read_b128 v[180:183], v157
	ds_read_b128 v[184:187], v157 offset:1024
	ds_read_b128 v[188:191], v157 offset:2048
	ds_read_b128 v[192:195], v157 offset:3072
	s_add_u32 s26, s26, 0x100000
	s_addc_u32 s27, s27, 0
	s_mov_b32 m0, s33
	ds_read_b128 v[204:207], v156 offset:32768
	ds_read_b128 v[208:211], v156 offset:33792
	ds_read_b128 v[212:215], v156 offset:34816
	ds_read_b128 v[216:219], v156 offset:35840
	ds_read_b128 v[220:223], v156 offset:36864
	ds_read_b128 v[224:227], v156 offset:37888
	ds_read_b128 v[228:231], v156 offset:38912
	ds_read_b128 v[232:235], v156 offset:39936
	global_load_lds_dwordx4 v130, s[26:27]
	s_mov_b32 m0, s34
	s_nop 0
	global_load_lds_dwordx4 v134, s[26:27]
	s_waitcnt vmcnt(8)
	s_waitcnt lgkmcnt(0)
	s_barrier
	s_waitcnt lgkmcnt(0)
	v_mfma_f32_16x16x32_bf16 v[126:129], v[142:145], v[204:207], v[126:129]
	v_mfma_f32_16x16x32_bf16 v[126:129], v[158:161], v[208:211], v[126:129]
	v_mfma_f32_16x16x32_bf16 v[122:125], v[176:179], v[208:211], v[122:125]
	v_mfma_f32_16x16x32_bf16 v[122:125], v[168:171], v[204:207], v[122:125]
	v_mfma_f32_16x16x32_bf16 v[106:109], v[168:171], v[212:215], v[106:109]
	v_mfma_f32_16x16x32_bf16 v[106:109], v[176:179], v[216:219], v[106:109]
	v_mfma_f32_16x16x32_bf16 v[110:113], v[158:161], v[216:219], v[110:113]
	v_mfma_f32_16x16x32_bf16 v[110:113], v[142:145], v[212:215], v[110:113]
	v_mfma_f32_16x16x32_bf16 v[94:97], v[142:145], v[220:223], v[94:97]
	v_mfma_f32_16x16x32_bf16 v[94:97], v[158:161], v[224:227], v[94:97]
	v_mfma_f32_16x16x32_bf16 v[90:93], v[176:179], v[224:227], v[90:93]
	v_mfma_f32_16x16x32_bf16 v[90:93], v[168:171], v[220:223], v[90:93]
	v_mfma_f32_16x16x32_bf16 v[74:77], v[168:171], v[228:231], v[74:77]
	v_mfma_f32_16x16x32_bf16 v[74:77], v[176:179], v[232:235], v[74:77]
	v_mfma_f32_16x16x32_bf16 v[78:81], v[158:161], v[232:235], v[78:81]
	v_mfma_f32_16x16x32_bf16 v[78:81], v[142:145], v[228:231], v[78:81]
	v_mfma_f32_16x16x32_bf16 v[70:73], v[180:183], v[228:231], v[70:73]
	v_mfma_f32_16x16x32_bf16 v[70:73], v[184:187], v[232:235], v[70:73]
	v_mfma_f32_16x16x32_bf16 v[66:69], v[192:195], v[232:235], v[66:69]
	v_mfma_f32_16x16x32_bf16 v[66:69], v[188:191], v[228:231], v[66:69]
	v_mfma_f32_16x16x32_bf16 v[82:85], v[188:191], v[220:223], v[82:85]
	v_mfma_f32_16x16x32_bf16 v[82:85], v[192:195], v[224:227], v[82:85]
	v_mfma_f32_16x16x32_bf16 v[86:89], v[184:187], v[224:227], v[86:89]
	v_mfma_f32_16x16x32_bf16 v[86:89], v[180:183], v[220:223], v[86:89]
	v_mfma_f32_16x16x32_bf16 v[102:105], v[180:183], v[212:215], v[102:105]
	v_mfma_f32_16x16x32_bf16 v[102:105], v[184:187], v[216:219], v[102:105]
	v_mfma_f32_16x16x32_bf16 v[98:101], v[192:195], v[216:219], v[98:101]
	v_mfma_f32_16x16x32_bf16 v[98:101], v[188:191], v[212:215], v[98:101]
	v_mfma_f32_16x16x32_bf16 v[114:117], v[188:191], v[204:207], v[114:117]
	v_mfma_f32_16x16x32_bf16 v[114:117], v[192:195], v[208:211], v[114:117]
	v_mfma_f32_16x16x32_bf16 v[118:121], v[184:187], v[208:211], v[118:121]
	v_mfma_f32_16x16x32_bf16 v[118:121], v[180:183], v[204:207], v[118:121]
	s_barrier
	s_add_u32 s98, s26, 0xfff00080
	s_addc_u32 s99, s27, -1
	s_add_u32 s24, s24, 0x80
	s_addc_u32 s25, s25, 0
	s_add_i32 s26, s49, s28
	s_mov_b32 m0, s26
	ds_read_b128 v[204:207], v156 offset:49152
	ds_read_b128 v[208:211], v156 offset:50176
	ds_read_b128 v[212:215], v156 offset:51200
	ds_read_b128 v[216:219], v156 offset:52224
	ds_read_b128 v[220:223], v156 offset:53248
	ds_read_b128 v[224:227], v156 offset:54272
	ds_read_b128 v[228:231], v156 offset:55296
	ds_read_b128 v[232:235], v156 offset:56320
	global_load_lds_dwordx4 v132, s[24:25]
	s_add_i32 m0, s26, 0x2000
	s_add_i32 s26, s50, s28
	global_load_lds_dwordx4 v136, s[24:25]
	s_add_u32 s24, s24, 0x100000
	s_addc_u32 s25, s25, 0
	s_mov_b32 m0, s26
	s_nop 0
	global_load_lds_dwordx4 v132, s[24:25]
	s_add_i32 m0, s26, 0x2000
	s_nop 0
	global_load_lds_dwordx4 v136, s[24:25]
	s_mov_b32 m0, s36
	s_nop 0
	global_load_lds_dwordx4 v130, s[98:99]
	s_mov_b32 m0, s37
	s_nop 0
	global_load_lds_dwordx4 v134, s[98:99]
	s_waitcnt vmcnt(8)
	s_waitcnt lgkmcnt(0)
	s_barrier
	s_waitcnt lgkmcnt(0)
	v_mfma_f32_16x16x32_bf16 v[62:65], v[142:145], v[204:207], v[62:65]
	v_mfma_f32_16x16x32_bf16 v[62:65], v[158:161], v[208:211], v[62:65]
	v_mfma_f32_16x16x32_bf16 v[58:61], v[176:179], v[208:211], v[58:61]
	v_mfma_f32_16x16x32_bf16 v[58:61], v[168:171], v[204:207], v[58:61]
	v_mfma_f32_16x16x32_bf16 v[42:45], v[168:171], v[212:215], v[42:45]
	v_mfma_f32_16x16x32_bf16 v[42:45], v[176:179], v[216:219], v[42:45]
	v_mfma_f32_16x16x32_bf16 v[46:49], v[158:161], v[216:219], v[46:49]
	v_mfma_f32_16x16x32_bf16 v[46:49], v[142:145], v[212:215], v[46:49]
	v_mfma_f32_16x16x32_bf16 v[30:33], v[142:145], v[220:223], v[30:33]
	v_mfma_f32_16x16x32_bf16 v[30:33], v[158:161], v[224:227], v[30:33]
	v_mfma_f32_16x16x32_bf16 v[26:29], v[176:179], v[224:227], v[26:29]
	v_mfma_f32_16x16x32_bf16 v[26:29], v[168:171], v[220:223], v[26:29]
	v_mfma_f32_16x16x32_bf16 v[10:13], v[168:171], v[228:231], v[10:13]
	v_mfma_f32_16x16x32_bf16 v[10:13], v[176:179], v[232:235], v[10:13]
	v_mfma_f32_16x16x32_bf16 v[14:17], v[158:161], v[232:235], v[14:17]
	v_mfma_f32_16x16x32_bf16 v[14:17], v[142:145], v[228:231], v[14:17]
	v_mfma_f32_16x16x32_bf16 v[6:9], v[180:183], v[228:231], v[6:9]
	v_mfma_f32_16x16x32_bf16 v[6:9], v[184:187], v[232:235], v[6:9]
	v_mfma_f32_16x16x32_bf16 v[2:5], v[192:195], v[232:235], v[2:5]
	v_mfma_f32_16x16x32_bf16 v[2:5], v[188:191], v[228:231], v[2:5]
	v_mfma_f32_16x16x32_bf16 v[18:21], v[188:191], v[220:223], v[18:21]
	v_mfma_f32_16x16x32_bf16 v[18:21], v[192:195], v[224:227], v[18:21]
	v_mfma_f32_16x16x32_bf16 v[22:25], v[184:187], v[224:227], v[22:25]
	v_mfma_f32_16x16x32_bf16 v[22:25], v[180:183], v[220:223], v[22:25]
	v_mfma_f32_16x16x32_bf16 v[38:41], v[180:183], v[212:215], v[38:41]
	v_mfma_f32_16x16x32_bf16 v[38:41], v[184:187], v[216:219], v[38:41]
	v_mfma_f32_16x16x32_bf16 v[34:37], v[192:195], v[216:219], v[34:37]
	v_mfma_f32_16x16x32_bf16 v[34:37], v[188:191], v[212:215], v[34:37]
	v_mfma_f32_16x16x32_bf16 v[50:53], v[188:191], v[204:207], v[50:53]
	v_mfma_f32_16x16x32_bf16 v[50:53], v[192:195], v[208:211], v[50:53]
	v_mfma_f32_16x16x32_bf16 v[54:57], v[184:187], v[208:211], v[54:57]
	v_mfma_f32_16x16x32_bf16 v[54:57], v[180:183], v[204:207], v[54:57]
	s_barrier
	s_add_i32 s48, s48, 2
	s_add_u32 s22, s22, 0x100
	s_addc_u32 s23, s23, 0
	s_add_u32 s46, s46, 0x100
	s_addc_u32 s47, s47, 0
	s_cmp_gt_u32 s48, 61
	s_cbranch_scc0 .LBB0_2230
	s_and_b64 vcc, exec, s[16:17]
	s_cbranch_vccz .LBB0_2233
	s_barrier

.LBB0_2240:
	s_add_i32 s20, s24, 0x100
	s_and_b64 s[18:19], s[18:19], exec
	s_cselect_b32 s19, 0, s20
	s_cselect_b32 s18, 0, 0
	s_add_u32 s20, s8, s19
	ds_read_b128 v[144:147], v139
	ds_read_b128 v[150:153], v139 offset:1024
	ds_read_b128 v[154:157], v139 offset:2048
	ds_read_b128 v[158:161], v139 offset:3072
	ds_read_b128 v[168:171], v140
	ds_read_b128 v[176:179], v140 offset:1024
	ds_read_b128 v[180:183], v140 offset:2048
	ds_read_b128 v[184:187], v140 offset:3072
	s_addc_u32 s21, s9, s18
	s_add_u32 s22, s10, s19
	s_addc_u32 s23, s11, s18
	s_add_u32 s28, s12, s24
	s_addc_u32 s29, s13, 0
	s_add_u32 s24, s22, 0x100000
	s_addc_u32 s25, s23, 0
	s_add_u32 s18, s20, 0x100000
	s_addc_u32 s19, s21, 0
	s_add_u32 s26, s22, 0x100080
	s_addc_u32 s27, s23, 0
	v_lshl_add_u64 v[172:173], s[28:29], 0, v[130:131]
	s_mov_b32 m0, s38
	v_lshl_add_u64 v[172:173], v[172:173], 0, s[14:15]
	ds_read_b128 v[188:191], v141
	ds_read_b128 v[192:195], v141 offset:1024
	ds_read_b128 v[204:207], v141 offset:2048
	ds_read_b128 v[208:211], v141 offset:3072
	ds_read_b128 v[212:215], v141 offset:4096
	ds_read_b128 v[216:219], v141 offset:5120
	ds_read_b128 v[220:223], v141 offset:6144
	ds_read_b128 v[224:227], v141 offset:7168
	global_load_lds_dwordx4 v[172:173], off
	v_lshl_add_u64 v[172:173], s[28:29], 0, v[134:135]
	v_lshl_add_u64 v[172:173], v[172:173], 0, s[14:15]
	s_mov_b32 m0, s39
	s_nop 0
	global_load_lds_dwordx4 v[172:173], off
	s_waitcnt vmcnt(8)
	s_waitcnt lgkmcnt(0)
	s_barrier
	s_waitcnt lgkmcnt(0)
	v_mfma_f32_16x16x32_bf16 v[126:129], v[144:147], v[188:191], v[126:129]
	v_mfma_f32_16x16x32_bf16 v[126:129], v[150:153], v[192:195], v[126:129]
	v_mfma_f32_16x16x32_bf16 v[122:125], v[158:161], v[192:195], v[122:125]
	v_mfma_f32_16x16x32_bf16 v[122:125], v[154:157], v[188:191], v[122:125]
	v_mfma_f32_16x16x32_bf16 v[114:117], v[154:157], v[204:207], v[114:117]
	v_mfma_f32_16x16x32_bf16 v[114:117], v[158:161], v[208:211], v[114:117]
	v_mfma_f32_16x16x32_bf16 v[118:121], v[150:153], v[208:211], v[118:121]
	v_mfma_f32_16x16x32_bf16 v[118:121], v[144:147], v[204:207], v[118:121]
	v_mfma_f32_16x16x32_bf16 v[102:105], v[144:147], v[212:215], v[102:105]
	v_mfma_f32_16x16x32_bf16 v[102:105], v[150:153], v[216:219], v[102:105]
	v_mfma_f32_16x16x32_bf16 v[98:101], v[158:161], v[216:219], v[98:101]
	v_mfma_f32_16x16x32_bf16 v[98:101], v[154:157], v[212:215], v[98:101]
	v_mfma_f32_16x16x32_bf16 v[82:85], v[154:157], v[220:223], v[82:85]
	v_mfma_f32_16x16x32_bf16 v[82:85], v[158:161], v[224:227], v[82:85]
	v_mfma_f32_16x16x32_bf16 v[86:89], v[150:153], v[224:227], v[86:89]
	v_mfma_f32_16x16x32_bf16 v[86:89], v[144:147], v[220:223], v[86:89]
	v_mfma_f32_16x16x32_bf16 v[70:73], v[168:171], v[220:223], v[70:73]
	v_mfma_f32_16x16x32_bf16 v[70:73], v[176:179], v[224:227], v[70:73]
	v_mfma_f32_16x16x32_bf16 v[66:69], v[184:187], v[224:227], v[66:69]
	v_mfma_f32_16x16x32_bf16 v[66:69], v[180:183], v[220:223], v[66:69]
	v_mfma_f32_16x16x32_bf16 v[74:77], v[180:183], v[212:215], v[74:77]
	v_mfma_f32_16x16x32_bf16 v[74:77], v[184:187], v[216:219], v[74:77]
	v_mfma_f32_16x16x32_bf16 v[78:81], v[176:179], v[216:219], v[78:81]
	v_mfma_f32_16x16x32_bf16 v[78:81], v[168:171], v[212:215], v[78:81]
	v_mfma_f32_16x16x32_bf16 v[94:97], v[168:171], v[204:207], v[94:97]
	v_mfma_f32_16x16x32_bf16 v[94:97], v[176:179], v[208:211], v[94:97]
	v_mfma_f32_16x16x32_bf16 v[90:93], v[184:187], v[208:211], v[90:93]
	v_mfma_f32_16x16x32_bf16 v[90:93], v[180:183], v[204:207], v[90:93]
	v_mfma_f32_16x16x32_bf16 v[106:109], v[180:183], v[188:191], v[106:109]
	v_mfma_f32_16x16x32_bf16 v[106:109], v[184:187], v[192:195], v[106:109]
	v_mfma_f32_16x16x32_bf16 v[110:113], v[176:179], v[192:195], v[110:113]
	v_mfma_f32_16x16x32_bf16 v[110:113], v[168:171], v[188:191], v[110:113]
	s_barrier
	s_mov_b32 m0, s40
	v_lshl_add_u64 v[172:173], s[22:23], 0, v[132:133]
	ds_read_b128 v[188:191], v141 offset:16384
	ds_read_b128 v[192:195], v141 offset:17408
	ds_read_b128 v[204:207], v141 offset:18432
	ds_read_b128 v[208:211], v141 offset:19456
	ds_read_b128 v[212:215], v141 offset:20480
	ds_read_b128 v[216:219], v141 offset:21504
	ds_read_b128 v[220:223], v141 offset:22528
	ds_read_b128 v[224:227], v141 offset:23552
	global_load_lds_dwordx4 v[172:173], off
	v_lshl_add_u64 v[196:197], s[22:23], 0, v[136:137]
	s_mov_b32 m0, s41
	v_lshl_add_u64 v[228:229], s[24:25], 0, v[132:133]
	global_load_lds_dwordx4 v[196:197], off
	s_mov_b32 m0, s42
	v_lshl_add_u64 v[230:231], s[20:21], 0, v[134:135]
	global_load_lds_dwordx4 v[228:229], off
	v_lshl_add_u64 v[228:229], s[24:25], 0, v[136:137]
	s_mov_b32 m0, s43
	s_nop 0
	global_load_lds_dwordx4 v[228:229], off
	v_lshl_add_u64 v[228:229], s[20:21], 0, v[130:131]
	s_mov_b32 m0, s7
	s_nop 0
	global_load_lds_dwordx4 v[228:229], off
	s_mov_b32 m0, s31
	s_nop 0
	global_load_lds_dwordx4 v[230:231], off
	s_waitcnt vmcnt(8)
	s_waitcnt lgkmcnt(0)
	s_barrier
	s_waitcnt lgkmcnt(0)
	v_mfma_f32_16x16x32_bf16 v[62:65], v[144:147], v[188:191], v[62:65]
	v_mfma_f32_16x16x32_bf16 v[62:65], v[150:153], v[192:195], v[62:65]
	v_mfma_f32_16x16x32_bf16 v[58:61], v[158:161], v[192:195], v[58:61]
	v_mfma_f32_16x16x32_bf16 v[58:61], v[154:157], v[188:191], v[58:61]
	v_mfma_f32_16x16x32_bf16 v[50:53], v[154:157], v[204:207], v[50:53]
	v_mfma_f32_16x16x32_bf16 v[50:53], v[158:161], v[208:211], v[50:53]
	v_mfma_f32_16x16x32_bf16 v[54:57], v[150:153], v[208:211], v[54:57]
	v_mfma_f32_16x16x32_bf16 v[54:57], v[144:147], v[204:207], v[54:57]
	v_mfma_f32_16x16x32_bf16 v[38:41], v[144:147], v[212:215], v[38:41]
	v_mfma_f32_16x16x32_bf16 v[38:41], v[150:153], v[216:219], v[38:41]
	v_mfma_f32_16x16x32_bf16 v[34:37], v[158:161], v[216:219], v[34:37]
	v_mfma_f32_16x16x32_bf16 v[34:37], v[154:157], v[212:215], v[34:37]
	v_mfma_f32_16x16x32_bf16 v[18:21], v[154:157], v[220:223], v[18:21]
	v_mfma_f32_16x16x32_bf16 v[18:21], v[158:161], v[224:227], v[18:21]
	v_mfma_f32_16x16x32_bf16 v[22:25], v[150:153], v[224:227], v[22:25]
	v_mfma_f32_16x16x32_bf16 v[22:25], v[144:147], v[220:223], v[22:25]
	v_mfma_f32_16x16x32_bf16 v[6:9], v[168:171], v[220:223], v[6:9]
	v_mfma_f32_16x16x32_bf16 v[6:9], v[176:179], v[224:227], v[6:9]
	v_mfma_f32_16x16x32_bf16 v[2:5], v[184:187], v[224:227], v[2:5]
	v_mfma_f32_16x16x32_bf16 v[2:5], v[180:183], v[220:223], v[2:5]
	v_mfma_f32_16x16x32_bf16 v[10:13], v[180:183], v[212:215], v[10:13]
	v_mfma_f32_16x16x32_bf16 v[10:13], v[184:187], v[216:219], v[10:13]
	v_mfma_f32_16x16x32_bf16 v[14:17], v[176:179], v[216:219], v[14:17]
	v_mfma_f32_16x16x32_bf16 v[14:17], v[168:171], v[212:215], v[14:17]
	v_mfma_f32_16x16x32_bf16 v[30:33], v[168:171], v[204:207], v[30:33]
	v_mfma_f32_16x16x32_bf16 v[30:33], v[176:179], v[208:211], v[30:33]
	v_mfma_f32_16x16x32_bf16 v[26:29], v[184:187], v[208:211], v[26:29]
	v_mfma_f32_16x16x32_bf16 v[26:29], v[180:183], v[204:207], v[26:29]
	v_mfma_f32_16x16x32_bf16 v[42:45], v[180:183], v[188:191], v[42:45]
	v_mfma_f32_16x16x32_bf16 v[42:45], v[184:187], v[192:195], v[42:45]
	v_mfma_f32_16x16x32_bf16 v[46:49], v[176:179], v[192:195], v[46:49]
	v_mfma_f32_16x16x32_bf16 v[46:49], v[168:171], v[188:191], v[46:49]
	s_barrier
	ds_read_b128 v[144:147], v142
	ds_read_b128 v[150:153], v142 offset:1024
	ds_read_b128 v[154:157], v142 offset:2048
	ds_read_b128 v[158:161], v142 offset:3072
	ds_read_b128 v[168:171], v143
	ds_read_b128 v[176:179], v143 offset:1024
	ds_read_b128 v[180:183], v143 offset:2048
	ds_read_b128 v[184:187], v143 offset:3072
	s_mov_b32 m0, s33
	v_lshl_add_u64 v[232:233], s[18:19], 0, v[130:131]
	ds_read_b128 v[188:191], v141 offset:32768
	ds_read_b128 v[192:195], v141 offset:33792
	ds_read_b128 v[204:207], v141 offset:34816
	ds_read_b128 v[208:211], v141 offset:35840
	ds_read_b128 v[212:215], v141 offset:36864
	ds_read_b128 v[216:219], v141 offset:37888
	ds_read_b128 v[220:223], v141 offset:38912
	ds_read_b128 v[224:227], v141 offset:39936
	global_load_lds_dwordx4 v[232:233], off
	v_lshl_add_u64 v[232:233], s[18:19], 0, v[134:135]
	s_mov_b32 m0, s34
	s_nop 0
	global_load_lds_dwordx4 v[232:233], off
	s_waitcnt vmcnt(8)
	s_waitcnt lgkmcnt(0)
	s_barrier
	s_waitcnt lgkmcnt(0)
	v_mfma_f32_16x16x32_bf16 v[126:129], v[144:147], v[188:191], v[126:129]
	v_mfma_f32_16x16x32_bf16 v[126:129], v[150:153], v[192:195], v[126:129]
	v_mfma_f32_16x16x32_bf16 v[122:125], v[158:161], v[192:195], v[122:125]
	v_mfma_f32_16x16x32_bf16 v[122:125], v[154:157], v[188:191], v[122:125]
	v_mfma_f32_16x16x32_bf16 v[114:117], v[154:157], v[204:207], v[114:117]
	v_mfma_f32_16x16x32_bf16 v[114:117], v[158:161], v[208:211], v[114:117]
	v_mfma_f32_16x16x32_bf16 v[118:121], v[150:153], v[208:211], v[118:121]
	v_mfma_f32_16x16x32_bf16 v[118:121], v[144:147], v[204:207], v[118:121]
	v_mfma_f32_16x16x32_bf16 v[102:105], v[144:147], v[212:215], v[102:105]
	v_mfma_f32_16x16x32_bf16 v[102:105], v[150:153], v[216:219], v[102:105]
	v_mfma_f32_16x16x32_bf16 v[98:101], v[158:161], v[216:219], v[98:101]
	v_mfma_f32_16x16x32_bf16 v[98:101], v[154:157], v[212:215], v[98:101]
	v_mfma_f32_16x16x32_bf16 v[82:85], v[154:157], v[220:223], v[82:85]
	v_mfma_f32_16x16x32_bf16 v[82:85], v[158:161], v[224:227], v[82:85]
	v_mfma_f32_16x16x32_bf16 v[86:89], v[150:153], v[224:227], v[86:89]
	v_mfma_f32_16x16x32_bf16 v[86:89], v[144:147], v[220:223], v[86:89]
	v_mfma_f32_16x16x32_bf16 v[70:73], v[168:171], v[220:223], v[70:73]
	v_mfma_f32_16x16x32_bf16 v[70:73], v[176:179], v[224:227], v[70:73]
	v_mfma_f32_16x16x32_bf16 v[66:69], v[184:187], v[224:227], v[66:69]
	v_mfma_f32_16x16x32_bf16 v[66:69], v[180:183], v[220:223], v[66:69]
	v_mfma_f32_16x16x32_bf16 v[74:77], v[180:183], v[212:215], v[74:77]
	v_mfma_f32_16x16x32_bf16 v[74:77], v[184:187], v[216:219], v[74:77]
	v_mfma_f32_16x16x32_bf16 v[78:81], v[176:179], v[216:219], v[78:81]
	v_mfma_f32_16x16x32_bf16 v[78:81], v[168:171], v[212:215], v[78:81]
	v_mfma_f32_16x16x32_bf16 v[94:97], v[168:171], v[204:207], v[94:97]
	v_mfma_f32_16x16x32_bf16 v[94:97], v[176:179], v[208:211], v[94:97]
	v_mfma_f32_16x16x32_bf16 v[90:93], v[184:187], v[208:211], v[90:93]
	v_mfma_f32_16x16x32_bf16 v[90:93], v[180:183], v[204:207], v[90:93]
	v_mfma_f32_16x16x32_bf16 v[106:109], v[180:183], v[188:191], v[106:109]
	v_mfma_f32_16x16x32_bf16 v[106:109], v[184:187], v[192:195], v[106:109]
	v_mfma_f32_16x16x32_bf16 v[110:113], v[176:179], v[192:195], v[110:113]
	v_mfma_f32_16x16x32_bf16 v[110:113], v[168:171], v[188:191], v[110:113]
	s_barrier
	s_mov_b32 m0, s44
	v_lshl_add_u64 v[172:173], v[172:173], 0, s[14:15]
	ds_read_b128 v[188:191], v141 offset:49152
	ds_read_b128 v[192:195], v141 offset:50176
	ds_read_b128 v[204:207], v141 offset:51200
	ds_read_b128 v[208:211], v141 offset:52224
	ds_read_b128 v[212:215], v141 offset:53248
	ds_read_b128 v[216:219], v141 offset:54272
	ds_read_b128 v[220:223], v141 offset:55296
	ds_read_b128 v[224:227], v141 offset:56320
	global_load_lds_dwordx4 v[172:173], off
	v_lshl_add_u64 v[172:173], v[196:197], 0, s[14:15]
	s_mov_b32 m0, s45
	s_nop 0
	global_load_lds_dwordx4 v[172:173], off
	v_lshl_add_u64 v[172:173], s[26:27], 0, v[132:133]
	s_mov_b32 m0, s46
	s_nop 0
	global_load_lds_dwordx4 v[172:173], off
	v_lshl_add_u64 v[172:173], s[26:27], 0, v[136:137]
	s_mov_b32 m0, s47
	s_nop 0
	global_load_lds_dwordx4 v[172:173], off
	v_lshl_add_u64 v[172:173], v[228:229], 0, s[14:15]
	s_mov_b32 m0, s36
	s_nop 0
	global_load_lds_dwordx4 v[172:173], off
	v_lshl_add_u64 v[172:173], v[230:231], 0, s[14:15]
	s_mov_b32 m0, s37
	s_nop 0
	global_load_lds_dwordx4 v[172:173], off
	s_waitcnt vmcnt(8)
	s_waitcnt lgkmcnt(0)
	s_barrier
	s_waitcnt lgkmcnt(0)
	v_mfma_f32_16x16x32_bf16 v[62:65], v[144:147], v[188:191], v[62:65]
	v_mfma_f32_16x16x32_bf16 v[62:65], v[150:153], v[192:195], v[62:65]
	v_mfma_f32_16x16x32_bf16 v[58:61], v[158:161], v[192:195], v[58:61]
	v_mfma_f32_16x16x32_bf16 v[58:61], v[154:157], v[188:191], v[58:61]
	v_mfma_f32_16x16x32_bf16 v[50:53], v[154:157], v[204:207], v[50:53]
	v_mfma_f32_16x16x32_bf16 v[50:53], v[158:161], v[208:211], v[50:53]
	v_mfma_f32_16x16x32_bf16 v[54:57], v[150:153], v[208:211], v[54:57]
	v_mfma_f32_16x16x32_bf16 v[54:57], v[144:147], v[204:207], v[54:57]
	v_mfma_f32_16x16x32_bf16 v[38:41], v[144:147], v[212:215], v[38:41]
	v_mfma_f32_16x16x32_bf16 v[38:41], v[150:153], v[216:219], v[38:41]
	v_mfma_f32_16x16x32_bf16 v[34:37], v[158:161], v[216:219], v[34:37]
	v_mfma_f32_16x16x32_bf16 v[34:37], v[154:157], v[212:215], v[34:37]
	v_mfma_f32_16x16x32_bf16 v[18:21], v[154:157], v[220:223], v[18:21]
	v_mfma_f32_16x16x32_bf16 v[18:21], v[158:161], v[224:227], v[18:21]
	v_mfma_f32_16x16x32_bf16 v[22:25], v[150:153], v[224:227], v[22:25]
	v_mfma_f32_16x16x32_bf16 v[22:25], v[144:147], v[220:223], v[22:25]
	v_mfma_f32_16x16x32_bf16 v[6:9], v[168:171], v[220:223], v[6:9]
	v_mfma_f32_16x16x32_bf16 v[6:9], v[176:179], v[224:227], v[6:9]
	v_mfma_f32_16x16x32_bf16 v[2:5], v[184:187], v[224:227], v[2:5]
	v_mfma_f32_16x16x32_bf16 v[2:5], v[180:183], v[220:223], v[2:5]
	v_mfma_f32_16x16x32_bf16 v[10:13], v[180:183], v[212:215], v[10:13]
	v_mfma_f32_16x16x32_bf16 v[10:13], v[184:187], v[216:219], v[10:13]
	v_mfma_f32_16x16x32_bf16 v[14:17], v[176:179], v[216:219], v[14:17]
	v_mfma_f32_16x16x32_bf16 v[14:17], v[168:171], v[212:215], v[14:17]
	v_mfma_f32_16x16x32_bf16 v[30:33], v[168:171], v[204:207], v[30:33]
	v_mfma_f32_16x16x32_bf16 v[30:33], v[176:179], v[208:211], v[30:33]
	v_mfma_f32_16x16x32_bf16 v[26:29], v[184:187], v[208:211], v[26:29]
	v_mfma_f32_16x16x32_bf16 v[26:29], v[180:183], v[204:207], v[26:29]
	v_mfma_f32_16x16x32_bf16 v[42:45], v[180:183], v[188:191], v[42:45]
	v_mfma_f32_16x16x32_bf16 v[42:45], v[184:187], v[192:195], v[42:45]
	v_mfma_f32_16x16x32_bf16 v[46:49], v[176:179], v[192:195], v[46:49]
	v_mfma_f32_16x16x32_bf16 v[46:49], v[168:171], v[188:191], v[46:49]
	s_barrier
	s_andn2_b64 vcc, exec, s[16:17]
	s_mov_b64 s[18:19], -1
	s_mov_b64 s[16:17], 0
	s_movk_i32 s24, 0x100
	s_cbranch_vccz .LBB0_2240
	s_lshl_b32 s7, s30, 21
	v_readlane_b32 s0, v249, 29
	v_lshl_or_b32 v130, s6, 8, v148
	v_mov_b32_e32 v139, 0
	s_add_u32 s8, s0, s7
	v_readlane_b32 s0, v249, 31
	v_or_b32_e32 v130, s35, v130
	v_cvt_pk_bf16_f32 v70, v70, v71
	v_cvt_pk_bf16_f32 v71, v72, v73
	v_cvt_pk_bf16_f32 v72, v66, v67
	v_add_u32_e32 v66, 0x80, v138
	v_mov_b32_e32 v67, v139
	s_addc_u32 s9, s0, 0
	v_ashrrev_i32_e32 v131, 31, v130
	v_lshlrev_b64 v[132:133], 13, v[138:139]
	v_cvt_pk_bf16_f32 v110, v110, v111
	v_cvt_pk_bf16_f32 v111, v112, v113
	v_cvt_pk_bf16_f32 v112, v106, v107
	v_or_b32_e32 v106, 16, v138
	v_mov_b32_e32 v107, v139
	v_lshlrev_b64 v[66:67], 13, v[66:67]
	v_cvt_pk_bf16_f32 v46, v46, v47
	v_cvt_pk_bf16_f32 v47, v48, v49
	v_cvt_pk_bf16_f32 v48, v42, v43
	v_add_u32_e32 v42, 0x90, v138
	v_mov_b32_e32 v43, v139
	v_lshl_add_u64 v[132:133], s[8:9], 0, v[132:133]
	v_lshlrev_b64 v[130:131], 1, v[130:131]
	v_lshlrev_b64 v[106:107], 13, v[106:107]
	v_cvt_pk_bf16_f32 v94, v94, v95
	v_cvt_pk_bf16_f32 v95, v96, v97
	v_cvt_pk_bf16_f32 v96, v90, v91
	v_or_b32_e32 v90, 32, v138
	v_mov_b32_e32 v91, v139
	v_lshl_add_u64 v[66:67], s[8:9], 0, v[66:67]
	v_lshlrev_b64 v[42:43], 13, v[42:43]
	v_cvt_pk_bf16_f32 v30, v30, v31
	v_cvt_pk_bf16_f32 v31, v32, v33
	v_cvt_pk_bf16_f32 v32, v26, v27
	v_add_u32_e32 v26, 0xa0, v138
	v_mov_b32_e32 v27, v139
	v_lshl_add_u64 v[132:133], v[132:133], 0, v[130:131]
	v_cvt_pk_bf16_f32 v113, v108, v109
	v_lshl_add_u64 v[106:107], s[8:9], 0, v[106:107]
	v_lshlrev_b64 v[90:91], 13, v[90:91]
	v_cvt_pk_bf16_f32 v78, v78, v79
	v_cvt_pk_bf16_f32 v79, v80, v81
	v_cvt_pk_bf16_f32 v80, v74, v75
	v_or_b32_e32 v74, 48, v138
	v_mov_b32_e32 v75, v139
	v_lshl_add_u64 v[66:67], v[66:67], 0, v[130:131]
	v_cvt_pk_bf16_f32 v49, v44, v45
	v_lshl_add_u64 v[42:43], s[8:9], 0, v[42:43]
	v_lshlrev_b64 v[26:27], 13, v[26:27]
	v_add_u32_e32 v138, 0xb0, v138
	global_store_dwordx4 v[132:133], v[110:113], off offset:256
	v_cvt_pk_bf16_f32 v97, v92, v93
	v_lshl_add_u64 v[90:91], s[8:9], 0, v[90:91]
	v_lshl_add_u64 v[110:111], v[106:107], 0, v[130:131]
	v_lshlrev_b64 v[74:75], 13, v[74:75]
	global_store_dwordx4 v[66:67], v[46:49], off offset:256
	v_cvt_pk_bf16_f32 v33, v28, v29
	v_lshl_add_u64 v[26:27], s[8:9], 0, v[26:27]
	v_lshl_add_u64 v[46:47], v[42:43], 0, v[130:131]
	v_cvt_pk_bf16_f32 v14, v14, v15
	v_cvt_pk_bf16_f32 v15, v16, v17
	v_cvt_pk_bf16_f32 v16, v10, v11
	v_lshlrev_b64 v[10:11], 13, v[138:139]
	global_store_dwordx4 v[110:111], v[94:97], off offset:256
	v_cvt_pk_bf16_f32 v81, v76, v77
	v_lshl_add_u64 v[74:75], s[8:9], 0, v[74:75]
	v_lshl_add_u64 v[94:95], v[90:91], 0, v[130:131]
	global_store_dwordx4 v[46:47], v[30:33], off offset:256
	v_cvt_pk_bf16_f32 v17, v12, v13
	v_lshl_add_u64 v[10:11], s[8:9], 0, v[10:11]
	v_lshl_add_u64 v[30:31], v[26:27], 0, v[130:131]
	v_cvt_pk_bf16_f32 v126, v126, v127
	v_cvt_pk_bf16_f32 v127, v128, v129
	v_cvt_pk_bf16_f32 v128, v122, v123
	v_cvt_pk_bf16_f32 v129, v124, v125
	v_cvt_pk_bf16_f32 v106, v118, v119
	v_cvt_pk_bf16_f32 v107, v120, v121
	v_cvt_pk_bf16_f32 v108, v114, v115
	v_cvt_pk_bf16_f32 v109, v116, v117
	v_cvt_pk_bf16_f32 v90, v102, v103
	v_cvt_pk_bf16_f32 v91, v104, v105
	v_cvt_pk_bf16_f32 v92, v98, v99
	v_cvt_pk_bf16_f32 v93, v100, v101
	global_store_dwordx4 v[94:95], v[78:81], off offset:256
	v_cvt_pk_bf16_f32 v76, v82, v83
	v_cvt_pk_bf16_f32 v77, v84, v85
	v_lshl_add_u64 v[78:79], v[74:75], 0, v[130:131]
	v_cvt_pk_bf16_f32 v74, v86, v87
	v_cvt_pk_bf16_f32 v75, v88, v89
	v_cvt_pk_bf16_f32 v73, v68, v69
	v_cvt_pk_bf16_f32 v62, v62, v63
	v_cvt_pk_bf16_f32 v63, v64, v65
	v_cvt_pk_bf16_f32 v64, v58, v59
	v_cvt_pk_bf16_f32 v65, v60, v61
	v_cvt_pk_bf16_f32 v42, v54, v55
	v_cvt_pk_bf16_f32 v43, v56, v57
	v_cvt_pk_bf16_f32 v44, v50, v51
	v_cvt_pk_bf16_f32 v45, v52, v53
	v_cvt_pk_bf16_f32 v26, v38, v39
	v_cvt_pk_bf16_f32 v27, v40, v41
	v_cvt_pk_bf16_f32 v28, v34, v35
	v_cvt_pk_bf16_f32 v29, v36, v37
	global_store_dwordx4 v[30:31], v[14:17], off offset:256
	v_cvt_pk_bf16_f32 v12, v18, v19
	v_cvt_pk_bf16_f32 v13, v20, v21
	v_lshl_add_u64 v[14:15], v[10:11], 0, v[130:131]
	v_cvt_pk_bf16_f32 v10, v22, v23
	v_cvt_pk_bf16_f32 v11, v24, v25
	v_cvt_pk_bf16_f32 v6, v6, v7
	v_cvt_pk_bf16_f32 v7, v8, v9
	v_cvt_pk_bf16_f32 v8, v2, v3
	v_cvt_pk_bf16_f32 v9, v4, v5
	global_store_dwordx4 v[132:133], v[126:129], off
	global_store_dwordx4 v[110:111], v[106:109], off
	global_store_dwordx4 v[94:95], v[90:93], off
	global_store_dwordx4 v[78:79], v[74:77], off
	global_store_dwordx4 v[78:79], v[70:73], off offset:256
	global_store_dwordx4 v[66:67], v[62:65], off
	global_store_dwordx4 v[46:47], v[42:45], off
	global_store_dwordx4 v[30:31], v[26:29], off
	global_store_dwordx4 v[14:15], v[10:13], off
	global_store_dwordx4 v[14:15], v[6:9], off offset:256
	s_waitcnt vmcnt(0)
	s_cmpk_lt_u32 s3, 0x100
	s_cbranch_scc0 .LBB0_2243
	s_barrier

.LBB0_2373:
	s_add_u32 s60, s20, 0xfff00000
	s_addc_u32 s61, s21, -1
	s_mov_b32 m0, s35
	ds_read_b128 v[142:145], v148
	global_load_lds_dwordx4 v130, s[60:61]
	s_mov_b32 m0, s36
	ds_read_b128 v[154:157], v148 offset:1024
	global_load_lds_dwordx4 v134, s[60:61]
	s_mov_b32 m0, s40
	ds_read_b128 v[158:161], v148 offset:2048
	global_load_lds_dwordx4 v138, s[20:21]
	s_mov_b32 m0, s41
	ds_read_b128 v[168:171], v148 offset:3072
	global_load_lds_dwordx4 v140, s[20:21]
	ds_read_b128 v[176:179], v149
	ds_read_b128 v[180:183], v149 offset:1024
	ds_read_b128 v[184:187], v149 offset:2048
	ds_read_b128 v[188:191], v149 offset:3072
	s_add_u32 s22, s20, 0xfff00080
	s_addc_u32 s23, s21, -1
	s_cmp_eq_u32 s57, 60
	s_cselect_b32 s25, s52, s23
	s_cselect_b32 s24, s53, s22
	s_cselect_b32 s23, s7, s56
	s_cselect_b32 s22, s54, s55
	ds_read_b128 v[192:195], v150
	ds_read_b128 v[204:207], v150 offset:1024
	ds_read_b128 v[208:211], v150 offset:2048
	ds_read_b128 v[212:215], v150 offset:3072
	ds_read_b128 v[216:219], v150 offset:4096
	ds_read_b128 v[220:223], v150 offset:5120
	ds_read_b128 v[224:227], v150 offset:6144
	ds_read_b128 v[228:231], v150 offset:7168
	s_waitcnt vmcnt(8)
	s_waitcnt lgkmcnt(0)
	s_barrier
	s_waitcnt lgkmcnt(0)
	v_mfma_f32_16x16x32_bf16 v[126:129], v[142:145], v[192:195], v[126:129]
	v_mfma_f32_16x16x32_bf16 v[126:129], v[154:157], v[204:207], v[126:129]
	v_mfma_f32_16x16x32_bf16 v[122:125], v[168:171], v[204:207], v[122:125]
	v_mfma_f32_16x16x32_bf16 v[122:125], v[158:161], v[192:195], v[122:125]
	v_mfma_f32_16x16x32_bf16 v[106:109], v[158:161], v[208:211], v[106:109]
	v_mfma_f32_16x16x32_bf16 v[106:109], v[168:171], v[212:215], v[106:109]
	v_mfma_f32_16x16x32_bf16 v[110:113], v[154:157], v[212:215], v[110:113]
	v_mfma_f32_16x16x32_bf16 v[110:113], v[142:145], v[208:211], v[110:113]
	v_mfma_f32_16x16x32_bf16 v[94:97], v[142:145], v[216:219], v[94:97]
	v_mfma_f32_16x16x32_bf16 v[94:97], v[154:157], v[220:223], v[94:97]
	v_mfma_f32_16x16x32_bf16 v[90:93], v[168:171], v[220:223], v[90:93]
	v_mfma_f32_16x16x32_bf16 v[90:93], v[158:161], v[216:219], v[90:93]
	v_mfma_f32_16x16x32_bf16 v[74:77], v[158:161], v[224:227], v[74:77]
	v_mfma_f32_16x16x32_bf16 v[74:77], v[168:171], v[228:231], v[74:77]
	v_mfma_f32_16x16x32_bf16 v[78:81], v[154:157], v[228:231], v[78:81]
	v_mfma_f32_16x16x32_bf16 v[78:81], v[142:145], v[224:227], v[78:81]
	v_mfma_f32_16x16x32_bf16 v[70:73], v[176:179], v[224:227], v[70:73]
	v_mfma_f32_16x16x32_bf16 v[70:73], v[180:183], v[228:231], v[70:73]
	v_mfma_f32_16x16x32_bf16 v[66:69], v[188:191], v[228:231], v[66:69]
	v_mfma_f32_16x16x32_bf16 v[66:69], v[184:187], v[224:227], v[66:69]
	v_mfma_f32_16x16x32_bf16 v[82:85], v[184:187], v[216:219], v[82:85]
	v_mfma_f32_16x16x32_bf16 v[82:85], v[188:191], v[220:223], v[82:85]
	v_mfma_f32_16x16x32_bf16 v[86:89], v[180:183], v[220:223], v[86:89]
	v_mfma_f32_16x16x32_bf16 v[86:89], v[176:179], v[216:219], v[86:89]
	v_mfma_f32_16x16x32_bf16 v[102:105], v[176:179], v[208:211], v[102:105]
	v_mfma_f32_16x16x32_bf16 v[102:105], v[180:183], v[212:215], v[102:105]
	v_mfma_f32_16x16x32_bf16 v[98:101], v[188:191], v[212:215], v[98:101]
	v_mfma_f32_16x16x32_bf16 v[98:101], v[184:187], v[208:211], v[98:101]
	v_mfma_f32_16x16x32_bf16 v[114:117], v[184:187], v[192:195], v[114:117]
	v_mfma_f32_16x16x32_bf16 v[114:117], v[188:191], v[204:207], v[114:117]
	v_mfma_f32_16x16x32_bf16 v[118:121], v[180:183], v[204:207], v[118:121]
	v_mfma_f32_16x16x32_bf16 v[118:121], v[176:179], v[192:195], v[118:121]
	s_barrier
	s_mov_b32 m0, s42
	s_add_u32 s60, s22, 0x100000
	global_load_lds_dwordx4 v132, s[22:23]
	s_mov_b32 m0, s43
	s_addc_u32 s61, s23, 0
	global_load_lds_dwordx4 v136, s[22:23]
	s_mov_b32 m0, s44
	ds_read_b128 v[192:195], v150 offset:16384
	global_load_lds_dwordx4 v132, s[60:61]
	s_mov_b32 m0, s45
	ds_read_b128 v[204:207], v150 offset:17408
	global_load_lds_dwordx4 v136, s[60:61]
	ds_read_b128 v[208:211], v150 offset:18432
	ds_read_b128 v[212:215], v150 offset:19456
	ds_read_b128 v[216:219], v150 offset:20480
	ds_read_b128 v[220:223], v150 offset:21504
	ds_read_b128 v[224:227], v150 offset:22528
	ds_read_b128 v[228:231], v150 offset:23552
	s_waitcnt vmcnt(6)
	s_waitcnt lgkmcnt(0)
	s_barrier
	s_waitcnt lgkmcnt(0)
	v_mfma_f32_16x16x32_bf16 v[62:65], v[142:145], v[192:195], v[62:65]
	v_mfma_f32_16x16x32_bf16 v[62:65], v[154:157], v[204:207], v[62:65]
	v_mfma_f32_16x16x32_bf16 v[58:61], v[168:171], v[204:207], v[58:61]
	v_mfma_f32_16x16x32_bf16 v[58:61], v[158:161], v[192:195], v[58:61]
	v_mfma_f32_16x16x32_bf16 v[42:45], v[158:161], v[208:211], v[42:45]
	v_mfma_f32_16x16x32_bf16 v[42:45], v[168:171], v[212:215], v[42:45]
	v_mfma_f32_16x16x32_bf16 v[46:49], v[154:157], v[212:215], v[46:49]
	v_mfma_f32_16x16x32_bf16 v[46:49], v[142:145], v[208:211], v[46:49]
	v_mfma_f32_16x16x32_bf16 v[30:33], v[142:145], v[216:219], v[30:33]
	v_mfma_f32_16x16x32_bf16 v[30:33], v[154:157], v[220:223], v[30:33]
	v_mfma_f32_16x16x32_bf16 v[26:29], v[168:171], v[220:223], v[26:29]
	v_mfma_f32_16x16x32_bf16 v[26:29], v[158:161], v[216:219], v[26:29]
	v_mfma_f32_16x16x32_bf16 v[10:13], v[158:161], v[224:227], v[10:13]
	v_mfma_f32_16x16x32_bf16 v[10:13], v[168:171], v[228:231], v[10:13]
	v_mfma_f32_16x16x32_bf16 v[14:17], v[154:157], v[228:231], v[14:17]
	v_mfma_f32_16x16x32_bf16 v[14:17], v[142:145], v[224:227], v[14:17]
	v_mfma_f32_16x16x32_bf16 v[6:9], v[176:179], v[224:227], v[6:9]
	v_mfma_f32_16x16x32_bf16 v[6:9], v[180:183], v[228:231], v[6:9]
	v_mfma_f32_16x16x32_bf16 v[2:5], v[188:191], v[228:231], v[2:5]
	v_mfma_f32_16x16x32_bf16 v[2:5], v[184:187], v[224:227], v[2:5]
	v_mfma_f32_16x16x32_bf16 v[18:21], v[184:187], v[216:219], v[18:21]
	v_mfma_f32_16x16x32_bf16 v[18:21], v[188:191], v[220:223], v[18:21]
	v_mfma_f32_16x16x32_bf16 v[22:25], v[180:183], v[220:223], v[22:25]
	v_mfma_f32_16x16x32_bf16 v[22:25], v[176:179], v[216:219], v[22:25]
	v_mfma_f32_16x16x32_bf16 v[38:41], v[176:179], v[208:211], v[38:41]
	v_mfma_f32_16x16x32_bf16 v[38:41], v[180:183], v[212:215], v[38:41]
	v_mfma_f32_16x16x32_bf16 v[34:37], v[188:191], v[212:215], v[34:37]
	v_mfma_f32_16x16x32_bf16 v[34:37], v[184:187], v[208:211], v[34:37]
	v_mfma_f32_16x16x32_bf16 v[50:53], v[184:187], v[192:195], v[50:53]
	v_mfma_f32_16x16x32_bf16 v[50:53], v[188:191], v[204:207], v[50:53]
	v_mfma_f32_16x16x32_bf16 v[54:57], v[180:183], v[204:207], v[54:57]
	v_mfma_f32_16x16x32_bf16 v[54:57], v[176:179], v[192:195], v[54:57]
	s_barrier
	s_mov_b32 m0, s29
	ds_read_b128 v[142:145], v151
	global_load_lds_dwordx4 v130, s[24:25]
	s_mov_b32 m0, s30
	ds_read_b128 v[154:157], v151 offset:1024
	global_load_lds_dwordx4 v134, s[24:25]
	s_add_u32 s24, s24, 0x100000
	s_addc_u32 s25, s25, 0
	s_mov_b32 m0, s31
	ds_read_b128 v[158:161], v151 offset:2048
	global_load_lds_dwordx4 v130, s[24:25]
	s_mov_b32 m0, s33
	ds_read_b128 v[168:171], v151 offset:3072
	global_load_lds_dwordx4 v134, s[24:25]
	ds_read_b128 v[176:179], v152
	ds_read_b128 v[180:183], v152 offset:1024
	ds_read_b128 v[184:187], v152 offset:2048
	ds_read_b128 v[188:191], v152 offset:3072
	ds_read_b128 v[192:195], v150 offset:32768
	ds_read_b128 v[204:207], v150 offset:33792
	ds_read_b128 v[208:211], v150 offset:34816
	ds_read_b128 v[212:215], v150 offset:35840
	ds_read_b128 v[216:219], v150 offset:36864
	ds_read_b128 v[220:223], v150 offset:37888
	ds_read_b128 v[224:227], v150 offset:38912
	ds_read_b128 v[228:231], v150 offset:39936
	s_waitcnt vmcnt(8)
	s_waitcnt lgkmcnt(0)
	s_barrier
	s_waitcnt lgkmcnt(0)
	v_mfma_f32_16x16x32_bf16 v[126:129], v[142:145], v[192:195], v[126:129]
	v_mfma_f32_16x16x32_bf16 v[126:129], v[154:157], v[204:207], v[126:129]
	v_mfma_f32_16x16x32_bf16 v[122:125], v[168:171], v[204:207], v[122:125]
	v_mfma_f32_16x16x32_bf16 v[122:125], v[158:161], v[192:195], v[122:125]
	v_mfma_f32_16x16x32_bf16 v[106:109], v[158:161], v[208:211], v[106:109]
	v_mfma_f32_16x16x32_bf16 v[106:109], v[168:171], v[212:215], v[106:109]
	v_mfma_f32_16x16x32_bf16 v[110:113], v[154:157], v[212:215], v[110:113]
	v_mfma_f32_16x16x32_bf16 v[110:113], v[142:145], v[208:211], v[110:113]
	v_mfma_f32_16x16x32_bf16 v[94:97], v[142:145], v[216:219], v[94:97]
	v_mfma_f32_16x16x32_bf16 v[94:97], v[154:157], v[220:223], v[94:97]
	v_mfma_f32_16x16x32_bf16 v[90:93], v[168:171], v[220:223], v[90:93]
	v_mfma_f32_16x16x32_bf16 v[90:93], v[158:161], v[216:219], v[90:93]
	v_mfma_f32_16x16x32_bf16 v[74:77], v[158:161], v[224:227], v[74:77]
	v_mfma_f32_16x16x32_bf16 v[74:77], v[168:171], v[228:231], v[74:77]
	v_mfma_f32_16x16x32_bf16 v[78:81], v[154:157], v[228:231], v[78:81]
	v_mfma_f32_16x16x32_bf16 v[78:81], v[142:145], v[224:227], v[78:81]
	v_mfma_f32_16x16x32_bf16 v[70:73], v[176:179], v[224:227], v[70:73]
	v_mfma_f32_16x16x32_bf16 v[70:73], v[180:183], v[228:231], v[70:73]
	v_mfma_f32_16x16x32_bf16 v[66:69], v[188:191], v[228:231], v[66:69]
	v_mfma_f32_16x16x32_bf16 v[66:69], v[184:187], v[224:227], v[66:69]
	v_mfma_f32_16x16x32_bf16 v[82:85], v[184:187], v[216:219], v[82:85]
	v_mfma_f32_16x16x32_bf16 v[82:85], v[188:191], v[220:223], v[82:85]
	v_mfma_f32_16x16x32_bf16 v[86:89], v[180:183], v[220:223], v[86:89]
	v_mfma_f32_16x16x32_bf16 v[86:89], v[176:179], v[216:219], v[86:89]
	v_mfma_f32_16x16x32_bf16 v[102:105], v[176:179], v[208:211], v[102:105]
	v_mfma_f32_16x16x32_bf16 v[102:105], v[180:183], v[212:215], v[102:105]
	v_mfma_f32_16x16x32_bf16 v[98:101], v[188:191], v[212:215], v[98:101]
	v_mfma_f32_16x16x32_bf16 v[98:101], v[184:187], v[208:211], v[98:101]
	v_mfma_f32_16x16x32_bf16 v[114:117], v[184:187], v[192:195], v[114:117]
	v_mfma_f32_16x16x32_bf16 v[114:117], v[188:191], v[204:207], v[114:117]
	v_mfma_f32_16x16x32_bf16 v[118:121], v[180:183], v[204:207], v[118:121]
	v_mfma_f32_16x16x32_bf16 v[118:121], v[176:179], v[192:195], v[118:121]
	s_barrier
	s_mov_b32 m0, s46
	s_add_u32 s22, s22, 0x80
	s_addc_u32 s23, s23, 0
	global_load_lds_dwordx4 v132, s[22:23]
	s_mov_b32 m0, s47
	ds_read_b128 v[192:195], v150 offset:49152
	global_load_lds_dwordx4 v136, s[22:23]
	s_mov_b32 m0, s48
	s_add_u32 s22, s22, 0x100000
	s_addc_u32 s23, s23, 0
	global_load_lds_dwordx4 v132, s[22:23]
	s_mov_b32 m0, s49
	ds_read_b128 v[204:207], v150 offset:50176
	global_load_lds_dwordx4 v136, s[22:23]
	ds_read_b128 v[208:211], v150 offset:51200
	ds_read_b128 v[212:215], v150 offset:52224
	ds_read_b128 v[216:219], v150 offset:53248
	ds_read_b128 v[220:223], v150 offset:54272
	ds_read_b128 v[224:227], v150 offset:55296
	ds_read_b128 v[228:231], v150 offset:56320
	s_waitcnt vmcnt(6)
	s_waitcnt lgkmcnt(0)
	s_barrier
	s_waitcnt lgkmcnt(0)
	v_mfma_f32_16x16x32_bf16 v[62:65], v[142:145], v[192:195], v[62:65]
	v_mfma_f32_16x16x32_bf16 v[62:65], v[154:157], v[204:207], v[62:65]
	v_mfma_f32_16x16x32_bf16 v[58:61], v[168:171], v[204:207], v[58:61]
	v_mfma_f32_16x16x32_bf16 v[58:61], v[158:161], v[192:195], v[58:61]
	v_mfma_f32_16x16x32_bf16 v[42:45], v[158:161], v[208:211], v[42:45]
	v_mfma_f32_16x16x32_bf16 v[42:45], v[168:171], v[212:215], v[42:45]
	v_mfma_f32_16x16x32_bf16 v[46:49], v[154:157], v[212:215], v[46:49]
	v_mfma_f32_16x16x32_bf16 v[46:49], v[142:145], v[208:211], v[46:49]
	v_mfma_f32_16x16x32_bf16 v[30:33], v[142:145], v[216:219], v[30:33]
	v_mfma_f32_16x16x32_bf16 v[30:33], v[154:157], v[220:223], v[30:33]
	v_mfma_f32_16x16x32_bf16 v[26:29], v[168:171], v[220:223], v[26:29]
	v_mfma_f32_16x16x32_bf16 v[26:29], v[158:161], v[216:219], v[26:29]
	v_mfma_f32_16x16x32_bf16 v[10:13], v[158:161], v[224:227], v[10:13]
	v_mfma_f32_16x16x32_bf16 v[10:13], v[168:171], v[228:231], v[10:13]
	v_mfma_f32_16x16x32_bf16 v[14:17], v[154:157], v[228:231], v[14:17]
	v_mfma_f32_16x16x32_bf16 v[14:17], v[142:145], v[224:227], v[14:17]
	v_mfma_f32_16x16x32_bf16 v[6:9], v[176:179], v[224:227], v[6:9]
	v_mfma_f32_16x16x32_bf16 v[6:9], v[180:183], v[228:231], v[6:9]
	v_mfma_f32_16x16x32_bf16 v[2:5], v[188:191], v[228:231], v[2:5]
	v_mfma_f32_16x16x32_bf16 v[2:5], v[184:187], v[224:227], v[2:5]
	v_mfma_f32_16x16x32_bf16 v[18:21], v[184:187], v[216:219], v[18:21]
	v_mfma_f32_16x16x32_bf16 v[18:21], v[188:191], v[220:223], v[18:21]
	v_mfma_f32_16x16x32_bf16 v[22:25], v[180:183], v[220:223], v[22:25]
	v_mfma_f32_16x16x32_bf16 v[22:25], v[176:179], v[216:219], v[22:25]
	v_mfma_f32_16x16x32_bf16 v[38:41], v[176:179], v[208:211], v[38:41]
	v_mfma_f32_16x16x32_bf16 v[38:41], v[180:183], v[212:215], v[38:41]
	v_mfma_f32_16x16x32_bf16 v[34:37], v[188:191], v[212:215], v[34:37]
	v_mfma_f32_16x16x32_bf16 v[34:37], v[184:187], v[208:211], v[34:37]
	v_mfma_f32_16x16x32_bf16 v[50:53], v[184:187], v[192:195], v[50:53]
	v_mfma_f32_16x16x32_bf16 v[50:53], v[188:191], v[204:207], v[50:53]
	v_mfma_f32_16x16x32_bf16 v[54:57], v[180:183], v[204:207], v[54:57]
	v_mfma_f32_16x16x32_bf16 v[54:57], v[176:179], v[192:195], v[54:57]
	s_barrier
	s_add_i32 s57, s57, 2
	s_add_u32 s20, s20, 0x100
	s_addc_u32 s21, s21, 0
	s_add_u32 s55, s55, 0x100
	s_addc_u32 s56, s56, 0
	s_cmp_gt_u32 s57, 61
	s_cbranch_scc0 .LBB0_2373
	s_and_b64 vcc, exec, s[16:17]
	s_cbranch_vccz .LBB0_2376
	s_barrier

.LBB0_2618:
	s_add_u32 s64, s28, 0xffd50000
	s_addc_u32 s65, s29, -1
	s_mov_b32 m0, s44
	ds_read_b128 v[142:145], v156
	global_load_lds_dwordx4 v130, s[64:65]
	s_mov_b32 m0, s45
	ds_read_b128 v[168:171], v156 offset:1024
	global_load_lds_dwordx4 v134, s[64:65]
	s_mov_b32 m0, s46
	ds_read_b128 v[172:175], v156 offset:2048
	global_load_lds_dwordx4 v138, s[28:29]
	s_mov_b32 m0, s47
	ds_read_b128 v[176:179], v156 offset:3072
	global_load_lds_dwordx4 v140, s[28:29]
	ds_read_b128 v[180:183], v157
	ds_read_b128 v[184:187], v157 offset:1024
	ds_read_b128 v[188:191], v157 offset:2048
	ds_read_b128 v[192:195], v157 offset:3072
	s_add_u32 s30, s28, 0xffd50080
	s_addc_u32 s31, s29, -1
	s_cmpk_eq_i32 s62, 0xa8
	s_cselect_b32 s35, s25, s31
	s_cselect_b32 s34, s24, s30
	s_cselect_b32 s31, s23, s61
	s_cselect_b32 s30, s22, s60
	ds_read_b128 v[196:199], v158
	ds_read_b128 v[200:203], v158 offset:1024
	ds_read_b128 v[204:207], v158 offset:2048
	ds_read_b128 v[208:211], v158 offset:3072
	ds_read_b128 v[212:215], v158 offset:4096
	ds_read_b128 v[216:219], v158 offset:5120
	ds_read_b128 v[220:223], v158 offset:6144
	ds_read_b128 v[224:227], v158 offset:7168
	s_waitcnt vmcnt(8)
	s_waitcnt lgkmcnt(0)
	s_barrier
	s_waitcnt lgkmcnt(0)
	v_mfma_f32_16x16x32_bf16 v[126:129], v[142:145], v[196:199], v[126:129]
	v_mfma_f32_16x16x32_bf16 v[126:129], v[168:171], v[200:203], v[126:129]
	v_mfma_f32_16x16x32_bf16 v[122:125], v[176:179], v[200:203], v[122:125]
	v_mfma_f32_16x16x32_bf16 v[122:125], v[172:175], v[196:199], v[122:125]
	v_mfma_f32_16x16x32_bf16 v[106:109], v[172:175], v[204:207], v[106:109]
	v_mfma_f32_16x16x32_bf16 v[106:109], v[176:179], v[208:211], v[106:109]
	v_mfma_f32_16x16x32_bf16 v[110:113], v[168:171], v[208:211], v[110:113]
	v_mfma_f32_16x16x32_bf16 v[110:113], v[142:145], v[204:207], v[110:113]
	v_mfma_f32_16x16x32_bf16 v[94:97], v[142:145], v[212:215], v[94:97]
	v_mfma_f32_16x16x32_bf16 v[94:97], v[168:171], v[216:219], v[94:97]
	v_mfma_f32_16x16x32_bf16 v[90:93], v[176:179], v[216:219], v[90:93]
	v_mfma_f32_16x16x32_bf16 v[90:93], v[172:175], v[212:215], v[90:93]
	v_mfma_f32_16x16x32_bf16 v[74:77], v[172:175], v[220:223], v[74:77]
	v_mfma_f32_16x16x32_bf16 v[74:77], v[176:179], v[224:227], v[74:77]
	v_mfma_f32_16x16x32_bf16 v[78:81], v[168:171], v[224:227], v[78:81]
	v_mfma_f32_16x16x32_bf16 v[78:81], v[142:145], v[220:223], v[78:81]
	v_mfma_f32_16x16x32_bf16 v[70:73], v[180:183], v[220:223], v[70:73]
	v_mfma_f32_16x16x32_bf16 v[70:73], v[184:187], v[224:227], v[70:73]
	v_mfma_f32_16x16x32_bf16 v[66:69], v[192:195], v[224:227], v[66:69]
	v_mfma_f32_16x16x32_bf16 v[66:69], v[188:191], v[220:223], v[66:69]
	v_mfma_f32_16x16x32_bf16 v[82:85], v[188:191], v[212:215], v[82:85]
	v_mfma_f32_16x16x32_bf16 v[82:85], v[192:195], v[216:219], v[82:85]
	v_mfma_f32_16x16x32_bf16 v[86:89], v[184:187], v[216:219], v[86:89]
	v_mfma_f32_16x16x32_bf16 v[86:89], v[180:183], v[212:215], v[86:89]
	v_mfma_f32_16x16x32_bf16 v[102:105], v[180:183], v[204:207], v[102:105]
	v_mfma_f32_16x16x32_bf16 v[102:105], v[184:187], v[208:211], v[102:105]
	v_mfma_f32_16x16x32_bf16 v[98:101], v[192:195], v[208:211], v[98:101]
	v_mfma_f32_16x16x32_bf16 v[98:101], v[188:191], v[204:207], v[98:101]
	v_mfma_f32_16x16x32_bf16 v[114:117], v[188:191], v[196:199], v[114:117]
	v_mfma_f32_16x16x32_bf16 v[114:117], v[192:195], v[200:203], v[114:117]
	v_mfma_f32_16x16x32_bf16 v[118:121], v[184:187], v[200:203], v[118:121]
	v_mfma_f32_16x16x32_bf16 v[118:121], v[180:183], v[196:199], v[118:121]
	s_barrier
	s_mov_b32 m0, s48
	s_add_u32 s64, s30, 0x2b0000
	global_load_lds_dwordx4 v132, s[30:31]
	s_mov_b32 m0, s49
	s_addc_u32 s65, s31, 0
	global_load_lds_dwordx4 v136, s[30:31]
	s_mov_b32 m0, s50
	ds_read_b128 v[196:199], v158 offset:16384
	global_load_lds_dwordx4 v132, s[64:65]
	s_mov_b32 m0, s51
	ds_read_b128 v[200:203], v158 offset:17408
	global_load_lds_dwordx4 v136, s[64:65]
	ds_read_b128 v[204:207], v158 offset:18432
	ds_read_b128 v[208:211], v158 offset:19456
	ds_read_b128 v[212:215], v158 offset:20480
	ds_read_b128 v[216:219], v158 offset:21504
	ds_read_b128 v[220:223], v158 offset:22528
	ds_read_b128 v[224:227], v158 offset:23552
	s_waitcnt vmcnt(6)
	s_waitcnt lgkmcnt(0)
	s_barrier
	s_waitcnt lgkmcnt(0)
	v_mfma_f32_16x16x32_bf16 v[62:65], v[142:145], v[196:199], v[62:65]
	v_mfma_f32_16x16x32_bf16 v[62:65], v[168:171], v[200:203], v[62:65]
	v_mfma_f32_16x16x32_bf16 v[58:61], v[176:179], v[200:203], v[58:61]
	v_mfma_f32_16x16x32_bf16 v[58:61], v[172:175], v[196:199], v[58:61]
	v_mfma_f32_16x16x32_bf16 v[42:45], v[172:175], v[204:207], v[42:45]
	v_mfma_f32_16x16x32_bf16 v[42:45], v[176:179], v[208:211], v[42:45]
	v_mfma_f32_16x16x32_bf16 v[46:49], v[168:171], v[208:211], v[46:49]
	v_mfma_f32_16x16x32_bf16 v[46:49], v[142:145], v[204:207], v[46:49]
	v_mfma_f32_16x16x32_bf16 v[30:33], v[142:145], v[212:215], v[30:33]
	v_mfma_f32_16x16x32_bf16 v[30:33], v[168:171], v[216:219], v[30:33]
	v_mfma_f32_16x16x32_bf16 v[26:29], v[176:179], v[216:219], v[26:29]
	v_mfma_f32_16x16x32_bf16 v[26:29], v[172:175], v[212:215], v[26:29]
	v_mfma_f32_16x16x32_bf16 v[10:13], v[172:175], v[220:223], v[10:13]
	v_mfma_f32_16x16x32_bf16 v[10:13], v[176:179], v[224:227], v[10:13]
	v_mfma_f32_16x16x32_bf16 v[14:17], v[168:171], v[224:227], v[14:17]
	v_mfma_f32_16x16x32_bf16 v[14:17], v[142:145], v[220:223], v[14:17]
	v_mfma_f32_16x16x32_bf16 v[6:9], v[180:183], v[220:223], v[6:9]
	v_mfma_f32_16x16x32_bf16 v[6:9], v[184:187], v[224:227], v[6:9]
	v_mfma_f32_16x16x32_bf16 v[2:5], v[192:195], v[224:227], v[2:5]
	v_mfma_f32_16x16x32_bf16 v[2:5], v[188:191], v[220:223], v[2:5]
	v_mfma_f32_16x16x32_bf16 v[18:21], v[188:191], v[212:215], v[18:21]
	v_mfma_f32_16x16x32_bf16 v[18:21], v[192:195], v[216:219], v[18:21]
	v_mfma_f32_16x16x32_bf16 v[22:25], v[184:187], v[216:219], v[22:25]
	v_mfma_f32_16x16x32_bf16 v[22:25], v[180:183], v[212:215], v[22:25]
	v_mfma_f32_16x16x32_bf16 v[38:41], v[180:183], v[204:207], v[38:41]
	v_mfma_f32_16x16x32_bf16 v[38:41], v[184:187], v[208:211], v[38:41]
	v_mfma_f32_16x16x32_bf16 v[34:37], v[192:195], v[208:211], v[34:37]
	v_mfma_f32_16x16x32_bf16 v[34:37], v[188:191], v[204:207], v[34:37]
	v_mfma_f32_16x16x32_bf16 v[50:53], v[188:191], v[196:199], v[50:53]
	v_mfma_f32_16x16x32_bf16 v[50:53], v[192:195], v[200:203], v[50:53]
	v_mfma_f32_16x16x32_bf16 v[54:57], v[184:187], v[200:203], v[54:57]
	v_mfma_f32_16x16x32_bf16 v[54:57], v[180:183], v[196:199], v[54:57]
	s_barrier
	s_mov_b32 m0, s39
	ds_read_b128 v[142:145], v159
	global_load_lds_dwordx4 v130, s[34:35]
	s_mov_b32 m0, s40
	ds_read_b128 v[168:171], v159 offset:1024
	global_load_lds_dwordx4 v134, s[34:35]
	s_add_u32 s34, s34, 0x2b0000
	s_addc_u32 s35, s35, 0
	s_mov_b32 m0, s41
	ds_read_b128 v[172:175], v159 offset:2048
	global_load_lds_dwordx4 v130, s[34:35]
	s_mov_b32 m0, s42
	ds_read_b128 v[176:179], v159 offset:3072
	global_load_lds_dwordx4 v134, s[34:35]
	ds_read_b128 v[180:183], v160
	ds_read_b128 v[184:187], v160 offset:1024
	ds_read_b128 v[188:191], v160 offset:2048
	ds_read_b128 v[192:195], v160 offset:3072
	ds_read_b128 v[196:199], v158 offset:32768
	ds_read_b128 v[200:203], v158 offset:33792
	ds_read_b128 v[204:207], v158 offset:34816
	ds_read_b128 v[208:211], v158 offset:35840
	ds_read_b128 v[212:215], v158 offset:36864
	ds_read_b128 v[216:219], v158 offset:37888
	ds_read_b128 v[220:223], v158 offset:38912
	ds_read_b128 v[224:227], v158 offset:39936
	s_waitcnt vmcnt(8)
	s_waitcnt lgkmcnt(0)
	s_barrier
	s_waitcnt lgkmcnt(0)
	v_mfma_f32_16x16x32_bf16 v[126:129], v[142:145], v[196:199], v[126:129]
	v_mfma_f32_16x16x32_bf16 v[126:129], v[168:171], v[200:203], v[126:129]
	v_mfma_f32_16x16x32_bf16 v[122:125], v[176:179], v[200:203], v[122:125]
	v_mfma_f32_16x16x32_bf16 v[122:125], v[172:175], v[196:199], v[122:125]
	v_mfma_f32_16x16x32_bf16 v[106:109], v[172:175], v[204:207], v[106:109]
	v_mfma_f32_16x16x32_bf16 v[106:109], v[176:179], v[208:211], v[106:109]
	v_mfma_f32_16x16x32_bf16 v[110:113], v[168:171], v[208:211], v[110:113]
	v_mfma_f32_16x16x32_bf16 v[110:113], v[142:145], v[204:207], v[110:113]
	v_mfma_f32_16x16x32_bf16 v[94:97], v[142:145], v[212:215], v[94:97]
	v_mfma_f32_16x16x32_bf16 v[94:97], v[168:171], v[216:219], v[94:97]
	v_mfma_f32_16x16x32_bf16 v[90:93], v[176:179], v[216:219], v[90:93]
	v_mfma_f32_16x16x32_bf16 v[90:93], v[172:175], v[212:215], v[90:93]
	v_mfma_f32_16x16x32_bf16 v[74:77], v[172:175], v[220:223], v[74:77]
	v_mfma_f32_16x16x32_bf16 v[74:77], v[176:179], v[224:227], v[74:77]
	v_mfma_f32_16x16x32_bf16 v[78:81], v[168:171], v[224:227], v[78:81]
	v_mfma_f32_16x16x32_bf16 v[78:81], v[142:145], v[220:223], v[78:81]
	v_mfma_f32_16x16x32_bf16 v[70:73], v[180:183], v[220:223], v[70:73]
	v_mfma_f32_16x16x32_bf16 v[70:73], v[184:187], v[224:227], v[70:73]
	v_mfma_f32_16x16x32_bf16 v[66:69], v[192:195], v[224:227], v[66:69]
	v_mfma_f32_16x16x32_bf16 v[66:69], v[188:191], v[220:223], v[66:69]
	v_mfma_f32_16x16x32_bf16 v[82:85], v[188:191], v[212:215], v[82:85]
	v_mfma_f32_16x16x32_bf16 v[82:85], v[192:195], v[216:219], v[82:85]
	v_mfma_f32_16x16x32_bf16 v[86:89], v[184:187], v[216:219], v[86:89]
	v_mfma_f32_16x16x32_bf16 v[86:89], v[180:183], v[212:215], v[86:89]
	v_mfma_f32_16x16x32_bf16 v[102:105], v[180:183], v[204:207], v[102:105]
	v_mfma_f32_16x16x32_bf16 v[102:105], v[184:187], v[208:211], v[102:105]
	v_mfma_f32_16x16x32_bf16 v[98:101], v[192:195], v[208:211], v[98:101]
	v_mfma_f32_16x16x32_bf16 v[98:101], v[188:191], v[204:207], v[98:101]
	v_mfma_f32_16x16x32_bf16 v[114:117], v[188:191], v[196:199], v[114:117]
	v_mfma_f32_16x16x32_bf16 v[114:117], v[192:195], v[200:203], v[114:117]
	v_mfma_f32_16x16x32_bf16 v[118:121], v[184:187], v[200:203], v[118:121]
	v_mfma_f32_16x16x32_bf16 v[118:121], v[180:183], v[196:199], v[118:121]
	s_barrier
	s_mov_b32 m0, s52
	s_add_u32 s30, s30, 0x80
	s_addc_u32 s31, s31, 0
	global_load_lds_dwordx4 v132, s[30:31]
	s_mov_b32 m0, s53
	ds_read_b128 v[196:199], v158 offset:49152
	global_load_lds_dwordx4 v136, s[30:31]
	s_mov_b32 m0, s54
	s_add_u32 s30, s30, 0x2b0000
	s_addc_u32 s31, s31, 0
	global_load_lds_dwordx4 v132, s[30:31]
	s_mov_b32 m0, s55
	ds_read_b128 v[200:203], v158 offset:50176
	global_load_lds_dwordx4 v136, s[30:31]
	ds_read_b128 v[204:207], v158 offset:51200
	ds_read_b128 v[208:211], v158 offset:52224
	ds_read_b128 v[212:215], v158 offset:53248
	ds_read_b128 v[216:219], v158 offset:54272
	ds_read_b128 v[220:223], v158 offset:55296
	ds_read_b128 v[224:227], v158 offset:56320
	s_waitcnt vmcnt(6)
	s_waitcnt lgkmcnt(0)
	s_barrier
	s_waitcnt lgkmcnt(0)
	v_mfma_f32_16x16x32_bf16 v[62:65], v[142:145], v[196:199], v[62:65]
	v_mfma_f32_16x16x32_bf16 v[62:65], v[168:171], v[200:203], v[62:65]
	v_mfma_f32_16x16x32_bf16 v[58:61], v[176:179], v[200:203], v[58:61]
	v_mfma_f32_16x16x32_bf16 v[58:61], v[172:175], v[196:199], v[58:61]
	v_mfma_f32_16x16x32_bf16 v[42:45], v[172:175], v[204:207], v[42:45]
	v_mfma_f32_16x16x32_bf16 v[42:45], v[176:179], v[208:211], v[42:45]
	v_mfma_f32_16x16x32_bf16 v[46:49], v[168:171], v[208:211], v[46:49]
	v_mfma_f32_16x16x32_bf16 v[46:49], v[142:145], v[204:207], v[46:49]
	v_mfma_f32_16x16x32_bf16 v[30:33], v[142:145], v[212:215], v[30:33]
	v_mfma_f32_16x16x32_bf16 v[30:33], v[168:171], v[216:219], v[30:33]
	v_mfma_f32_16x16x32_bf16 v[26:29], v[176:179], v[216:219], v[26:29]
	v_mfma_f32_16x16x32_bf16 v[26:29], v[172:175], v[212:215], v[26:29]
	v_mfma_f32_16x16x32_bf16 v[10:13], v[172:175], v[220:223], v[10:13]
	v_mfma_f32_16x16x32_bf16 v[10:13], v[176:179], v[224:227], v[10:13]
	v_mfma_f32_16x16x32_bf16 v[14:17], v[168:171], v[224:227], v[14:17]
	v_mfma_f32_16x16x32_bf16 v[14:17], v[142:145], v[220:223], v[14:17]
	v_mfma_f32_16x16x32_bf16 v[6:9], v[180:183], v[220:223], v[6:9]
	v_mfma_f32_16x16x32_bf16 v[6:9], v[184:187], v[224:227], v[6:9]
	v_mfma_f32_16x16x32_bf16 v[2:5], v[192:195], v[224:227], v[2:5]
	v_mfma_f32_16x16x32_bf16 v[2:5], v[188:191], v[220:223], v[2:5]
	v_mfma_f32_16x16x32_bf16 v[18:21], v[188:191], v[212:215], v[18:21]
	v_mfma_f32_16x16x32_bf16 v[18:21], v[192:195], v[216:219], v[18:21]
	v_mfma_f32_16x16x32_bf16 v[22:25], v[184:187], v[216:219], v[22:25]
	v_mfma_f32_16x16x32_bf16 v[22:25], v[180:183], v[212:215], v[22:25]
	v_mfma_f32_16x16x32_bf16 v[38:41], v[180:183], v[204:207], v[38:41]
	v_mfma_f32_16x16x32_bf16 v[38:41], v[184:187], v[208:211], v[38:41]
	v_mfma_f32_16x16x32_bf16 v[34:37], v[192:195], v[208:211], v[34:37]
	v_mfma_f32_16x16x32_bf16 v[34:37], v[188:191], v[204:207], v[34:37]
	v_mfma_f32_16x16x32_bf16 v[50:53], v[188:191], v[196:199], v[50:53]
	v_mfma_f32_16x16x32_bf16 v[50:53], v[192:195], v[200:203], v[50:53]
	v_mfma_f32_16x16x32_bf16 v[54:57], v[184:187], v[200:203], v[54:57]
	v_mfma_f32_16x16x32_bf16 v[54:57], v[180:183], v[196:199], v[54:57]
	s_barrier
	s_add_i32 s62, s62, 2
	s_add_u32 s28, s28, 0x100
	s_addc_u32 s29, s29, 0
	s_add_u32 s60, s60, 0x100
	s_addc_u32 s61, s61, 0
	s_cmpk_gt_u32 s62, 0xa9
	s_cbranch_scc0 .LBB0_2618
	s_and_b64 vcc, exec, s[12:13]
	s_cbranch_vccz .LBB0_2621
	s_barrier

.LBB0_2632:
	ds_read_b128 v[150:153], v1
	ds_read_b128 v[154:157], v1 offset:1024
	ds_read_b128 v[158:161], v1 offset:2048
	ds_read_b128 v[166:169], v1 offset:3072
	ds_read_b128 v[170:173], v139
	ds_read_b128 v[174:177], v139 offset:1024
	ds_read_b128 v[178:181], v139 offset:2048
	ds_read_b128 v[182:185], v139 offset:3072
	s_add_i32 s38, s13, 2
	s_add_u32 s12, s10, 0xc2050080
	s_addc_u32 s14, s11, -1
	s_cmp_lg_u32 s26, s13
	s_cselect_b32 s12, s12, 0
	s_cselect_b32 s13, s14, 0
	s_add_u32 s14, s4, s12
	s_addc_u32 s15, s5, s13
	s_add_u32 s12, s6, s12
	s_addc_u32 s13, s7, s13
	s_mov_b32 m0, s27
	v_lshl_add_u64 v[162:163], v[140:141], 0, s[10:11]
	ds_read_b128 v[186:189], v144
	ds_read_b128 v[190:193], v144 offset:1024
	ds_read_b128 v[194:197], v144 offset:2048
	ds_read_b128 v[198:201], v144 offset:3072
	ds_read_b128 v[202:205], v144 offset:4096
	ds_read_b128 v[206:209], v144 offset:5120
	ds_read_b128 v[210:213], v144 offset:6144
	ds_read_b128 v[214:217], v144 offset:7168
	global_load_lds_dwordx4 v[162:163], off
	v_lshl_add_u64 v[162:163], v[142:143], 0, s[10:11]
	s_mov_b32 m0, s28
	s_nop 0
	global_load_lds_dwordx4 v[162:163], off
	s_waitcnt vmcnt(8)
	s_waitcnt lgkmcnt(0)
	s_barrier
	s_waitcnt lgkmcnt(0)
	v_mfma_f32_16x16x32_bf16 v[126:129], v[150:153], v[186:189], v[126:129]
	v_mfma_f32_16x16x32_bf16 v[126:129], v[154:157], v[190:193], v[126:129]
	v_mfma_f32_16x16x32_bf16 v[122:125], v[166:169], v[190:193], v[122:125]
	v_mfma_f32_16x16x32_bf16 v[122:125], v[158:161], v[186:189], v[122:125]
	v_mfma_f32_16x16x32_bf16 v[114:117], v[158:161], v[194:197], v[114:117]
	v_mfma_f32_16x16x32_bf16 v[114:117], v[166:169], v[198:201], v[114:117]
	v_mfma_f32_16x16x32_bf16 v[118:121], v[154:157], v[198:201], v[118:121]
	v_mfma_f32_16x16x32_bf16 v[118:121], v[150:153], v[194:197], v[118:121]
	v_mfma_f32_16x16x32_bf16 v[102:105], v[150:153], v[202:205], v[102:105]
	v_mfma_f32_16x16x32_bf16 v[102:105], v[154:157], v[206:209], v[102:105]
	v_mfma_f32_16x16x32_bf16 v[98:101], v[166:169], v[206:209], v[98:101]
	v_mfma_f32_16x16x32_bf16 v[98:101], v[158:161], v[202:205], v[98:101]
	v_mfma_f32_16x16x32_bf16 v[82:85], v[158:161], v[210:213], v[82:85]
	v_mfma_f32_16x16x32_bf16 v[82:85], v[166:169], v[214:217], v[82:85]
	v_mfma_f32_16x16x32_bf16 v[86:89], v[154:157], v[214:217], v[86:89]
	v_mfma_f32_16x16x32_bf16 v[86:89], v[150:153], v[210:213], v[86:89]
	v_mfma_f32_16x16x32_bf16 v[70:73], v[170:173], v[210:213], v[70:73]
	v_mfma_f32_16x16x32_bf16 v[70:73], v[174:177], v[214:217], v[70:73]
	v_mfma_f32_16x16x32_bf16 v[66:69], v[182:185], v[214:217], v[66:69]
	v_mfma_f32_16x16x32_bf16 v[66:69], v[178:181], v[210:213], v[66:69]
	v_mfma_f32_16x16x32_bf16 v[74:77], v[178:181], v[202:205], v[74:77]
	v_mfma_f32_16x16x32_bf16 v[74:77], v[182:185], v[206:209], v[74:77]
	v_mfma_f32_16x16x32_bf16 v[78:81], v[174:177], v[206:209], v[78:81]
	v_mfma_f32_16x16x32_bf16 v[78:81], v[170:173], v[202:205], v[78:81]
	v_mfma_f32_16x16x32_bf16 v[94:97], v[170:173], v[194:197], v[94:97]
	v_mfma_f32_16x16x32_bf16 v[94:97], v[174:177], v[198:201], v[94:97]
	v_mfma_f32_16x16x32_bf16 v[90:93], v[182:185], v[198:201], v[90:93]
	v_mfma_f32_16x16x32_bf16 v[90:93], v[178:181], v[194:197], v[90:93]
	v_mfma_f32_16x16x32_bf16 v[106:109], v[178:181], v[186:189], v[106:109]
	v_mfma_f32_16x16x32_bf16 v[106:109], v[182:185], v[190:193], v[106:109]
	v_mfma_f32_16x16x32_bf16 v[110:113], v[174:177], v[190:193], v[110:113]
	v_mfma_f32_16x16x32_bf16 v[110:113], v[170:173], v[186:189], v[110:113]
	s_barrier
	s_mov_b32 m0, s29
	v_lshl_add_u64 v[162:163], s[12:13], 0, v[132:133]
	s_add_u32 s40, s12, 0x2b0000
	ds_read_b128 v[186:189], v144 offset:16384
	ds_read_b128 v[190:193], v144 offset:17408
	ds_read_b128 v[194:197], v144 offset:18432
	ds_read_b128 v[198:201], v144 offset:19456
	ds_read_b128 v[202:205], v144 offset:20480
	ds_read_b128 v[206:209], v144 offset:21504
	ds_read_b128 v[210:213], v144 offset:22528
	ds_read_b128 v[214:217], v144 offset:23552
	global_load_lds_dwordx4 v[162:163], off
	v_lshl_add_u64 v[218:219], s[12:13], 0, v[136:137]
	s_mov_b32 m0, s30
	s_addc_u32 s41, s13, 0
	global_load_lds_dwordx4 v[218:219], off
	v_lshl_add_u64 v[220:221], s[40:41], 0, v[132:133]
	s_mov_b32 m0, s31
	v_lshl_add_u64 v[222:223], s[14:15], 0, v[134:135]
	global_load_lds_dwordx4 v[220:221], off
	v_lshl_add_u64 v[220:221], s[40:41], 0, v[136:137]
	s_mov_b32 m0, s33
	s_nop 0
	global_load_lds_dwordx4 v[220:221], off
	v_lshl_add_u64 v[220:221], s[14:15], 0, v[130:131]
	s_mov_b32 m0, s19
	s_nop 0
	global_load_lds_dwordx4 v[220:221], off
	s_mov_b32 m0, s20
	s_nop 0
	global_load_lds_dwordx4 v[222:223], off
	s_waitcnt vmcnt(8)
	s_waitcnt lgkmcnt(0)
	s_barrier
	s_waitcnt lgkmcnt(0)
	v_mfma_f32_16x16x32_bf16 v[62:65], v[150:153], v[186:189], v[62:65]
	v_mfma_f32_16x16x32_bf16 v[62:65], v[154:157], v[190:193], v[62:65]
	v_mfma_f32_16x16x32_bf16 v[58:61], v[166:169], v[190:193], v[58:61]
	v_mfma_f32_16x16x32_bf16 v[58:61], v[158:161], v[186:189], v[58:61]
	v_mfma_f32_16x16x32_bf16 v[50:53], v[158:161], v[194:197], v[50:53]
	v_mfma_f32_16x16x32_bf16 v[50:53], v[166:169], v[198:201], v[50:53]
	v_mfma_f32_16x16x32_bf16 v[54:57], v[154:157], v[198:201], v[54:57]
	v_mfma_f32_16x16x32_bf16 v[54:57], v[150:153], v[194:197], v[54:57]
	v_mfma_f32_16x16x32_bf16 v[38:41], v[150:153], v[202:205], v[38:41]
	v_mfma_f32_16x16x32_bf16 v[38:41], v[154:157], v[206:209], v[38:41]
	v_mfma_f32_16x16x32_bf16 v[34:37], v[166:169], v[206:209], v[34:37]
	v_mfma_f32_16x16x32_bf16 v[34:37], v[158:161], v[202:205], v[34:37]
	v_mfma_f32_16x16x32_bf16 v[18:21], v[158:161], v[210:213], v[18:21]
	v_mfma_f32_16x16x32_bf16 v[18:21], v[166:169], v[214:217], v[18:21]
	v_mfma_f32_16x16x32_bf16 v[22:25], v[154:157], v[214:217], v[22:25]
	v_mfma_f32_16x16x32_bf16 v[22:25], v[150:153], v[210:213], v[22:25]
	v_mfma_f32_16x16x32_bf16 v[6:9], v[170:173], v[210:213], v[6:9]
	v_mfma_f32_16x16x32_bf16 v[6:9], v[174:177], v[214:217], v[6:9]
	v_mfma_f32_16x16x32_bf16 v[2:5], v[182:185], v[214:217], v[2:5]
	v_mfma_f32_16x16x32_bf16 v[2:5], v[178:181], v[210:213], v[2:5]
	v_mfma_f32_16x16x32_bf16 v[10:13], v[178:181], v[202:205], v[10:13]
	v_mfma_f32_16x16x32_bf16 v[10:13], v[182:185], v[206:209], v[10:13]
	v_mfma_f32_16x16x32_bf16 v[14:17], v[174:177], v[206:209], v[14:17]
	v_mfma_f32_16x16x32_bf16 v[14:17], v[170:173], v[202:205], v[14:17]
	v_mfma_f32_16x16x32_bf16 v[30:33], v[170:173], v[194:197], v[30:33]
	v_mfma_f32_16x16x32_bf16 v[30:33], v[174:177], v[198:201], v[30:33]
	v_mfma_f32_16x16x32_bf16 v[26:29], v[182:185], v[198:201], v[26:29]
	v_mfma_f32_16x16x32_bf16 v[26:29], v[178:181], v[194:197], v[26:29]
	v_mfma_f32_16x16x32_bf16 v[42:45], v[178:181], v[186:189], v[42:45]
	v_mfma_f32_16x16x32_bf16 v[42:45], v[182:185], v[190:193], v[42:45]
	v_mfma_f32_16x16x32_bf16 v[46:49], v[174:177], v[190:193], v[46:49]
	v_mfma_f32_16x16x32_bf16 v[46:49], v[170:173], v[186:189], v[46:49]
	s_barrier
	ds_read_b128 v[150:153], v145
	ds_read_b128 v[154:157], v145 offset:1024
	ds_read_b128 v[158:161], v145 offset:2048
	ds_read_b128 v[166:169], v145 offset:3072
	ds_read_b128 v[170:173], v146
	ds_read_b128 v[174:177], v146 offset:1024
	ds_read_b128 v[178:181], v146 offset:2048
	ds_read_b128 v[182:185], v146 offset:3072
	s_add_u32 s14, s14, 0x2b0000
	s_addc_u32 s15, s15, 0
	s_mov_b32 m0, s21
	v_lshl_add_u64 v[224:225], s[14:15], 0, v[130:131]
	ds_read_b128 v[186:189], v144 offset:32768
	ds_read_b128 v[190:193], v144 offset:33792
	ds_read_b128 v[194:197], v144 offset:34816
	ds_read_b128 v[198:201], v144 offset:35840
	ds_read_b128 v[202:205], v144 offset:36864
	ds_read_b128 v[206:209], v144 offset:37888
	ds_read_b128 v[210:213], v144 offset:38912
	ds_read_b128 v[214:217], v144 offset:39936
	global_load_lds_dwordx4 v[224:225], off
	v_lshl_add_u64 v[224:225], s[14:15], 0, v[134:135]
	s_mov_b32 m0, s22
	s_nop 0
	global_load_lds_dwordx4 v[224:225], off
	s_waitcnt vmcnt(8)
	s_waitcnt lgkmcnt(0)
	s_barrier
	s_waitcnt lgkmcnt(0)
	v_mfma_f32_16x16x32_bf16 v[126:129], v[150:153], v[186:189], v[126:129]
	v_mfma_f32_16x16x32_bf16 v[126:129], v[154:157], v[190:193], v[126:129]
	v_mfma_f32_16x16x32_bf16 v[122:125], v[166:169], v[190:193], v[122:125]
	v_mfma_f32_16x16x32_bf16 v[122:125], v[158:161], v[186:189], v[122:125]
	v_mfma_f32_16x16x32_bf16 v[114:117], v[158:161], v[194:197], v[114:117]
	v_mfma_f32_16x16x32_bf16 v[114:117], v[166:169], v[198:201], v[114:117]
	v_mfma_f32_16x16x32_bf16 v[118:121], v[154:157], v[198:201], v[118:121]
	v_mfma_f32_16x16x32_bf16 v[118:121], v[150:153], v[194:197], v[118:121]
	v_mfma_f32_16x16x32_bf16 v[102:105], v[150:153], v[202:205], v[102:105]
	v_mfma_f32_16x16x32_bf16 v[102:105], v[154:157], v[206:209], v[102:105]
	v_mfma_f32_16x16x32_bf16 v[98:101], v[166:169], v[206:209], v[98:101]
	v_mfma_f32_16x16x32_bf16 v[98:101], v[158:161], v[202:205], v[98:101]
	v_mfma_f32_16x16x32_bf16 v[82:85], v[158:161], v[210:213], v[82:85]
	v_mfma_f32_16x16x32_bf16 v[82:85], v[166:169], v[214:217], v[82:85]
	v_mfma_f32_16x16x32_bf16 v[86:89], v[154:157], v[214:217], v[86:89]
	v_mfma_f32_16x16x32_bf16 v[86:89], v[150:153], v[210:213], v[86:89]
	v_mfma_f32_16x16x32_bf16 v[70:73], v[170:173], v[210:213], v[70:73]
	v_mfma_f32_16x16x32_bf16 v[70:73], v[174:177], v[214:217], v[70:73]
	v_mfma_f32_16x16x32_bf16 v[66:69], v[182:185], v[214:217], v[66:69]
	v_mfma_f32_16x16x32_bf16 v[66:69], v[178:181], v[210:213], v[66:69]
	v_mfma_f32_16x16x32_bf16 v[74:77], v[178:181], v[202:205], v[74:77]
	v_mfma_f32_16x16x32_bf16 v[74:77], v[182:185], v[206:209], v[74:77]
	v_mfma_f32_16x16x32_bf16 v[78:81], v[174:177], v[206:209], v[78:81]
	v_mfma_f32_16x16x32_bf16 v[78:81], v[170:173], v[202:205], v[78:81]
	v_mfma_f32_16x16x32_bf16 v[94:97], v[170:173], v[194:197], v[94:97]
	v_mfma_f32_16x16x32_bf16 v[94:97], v[174:177], v[198:201], v[94:97]
	v_mfma_f32_16x16x32_bf16 v[90:93], v[182:185], v[198:201], v[90:93]
	v_mfma_f32_16x16x32_bf16 v[90:93], v[178:181], v[194:197], v[90:93]
	v_mfma_f32_16x16x32_bf16 v[106:109], v[178:181], v[186:189], v[106:109]
	v_mfma_f32_16x16x32_bf16 v[106:109], v[182:185], v[190:193], v[106:109]
	v_mfma_f32_16x16x32_bf16 v[110:113], v[174:177], v[190:193], v[110:113]
	v_mfma_f32_16x16x32_bf16 v[110:113], v[170:173], v[186:189], v[110:113]
	s_barrier
	s_mov_b32 m0, s34
	v_lshl_add_u64 v[162:163], v[162:163], 0, s[8:9]
	s_add_u32 s12, s12, 0x2b0080
	ds_read_b128 v[186:189], v144 offset:49152
	ds_read_b128 v[190:193], v144 offset:50176
	ds_read_b128 v[194:197], v144 offset:51200
	ds_read_b128 v[198:201], v144 offset:52224
	ds_read_b128 v[202:205], v144 offset:53248
	ds_read_b128 v[206:209], v144 offset:54272
	ds_read_b128 v[210:213], v144 offset:55296
	ds_read_b128 v[214:217], v144 offset:56320
	global_load_lds_dwordx4 v[162:163], off
	v_lshl_add_u64 v[162:163], v[218:219], 0, s[8:9]
	s_mov_b32 m0, s35
	s_addc_u32 s13, s13, 0
	global_load_lds_dwordx4 v[162:163], off
	v_lshl_add_u64 v[162:163], s[12:13], 0, v[132:133]
	s_mov_b32 m0, s36
	s_nop 0
	global_load_lds_dwordx4 v[162:163], off
	v_lshl_add_u64 v[162:163], s[12:13], 0, v[136:137]
	s_mov_b32 m0, s37
	s_nop 0
	global_load_lds_dwordx4 v[162:163], off
	v_lshl_add_u64 v[162:163], v[220:221], 0, s[8:9]
	s_mov_b32 m0, s24
	s_nop 0
	global_load_lds_dwordx4 v[162:163], off
	v_lshl_add_u64 v[162:163], v[222:223], 0, s[8:9]
	s_mov_b32 m0, s25
	s_nop 0
	global_load_lds_dwordx4 v[162:163], off
	s_waitcnt vmcnt(8)
	s_waitcnt lgkmcnt(0)
	s_barrier
	s_waitcnt lgkmcnt(0)
	v_mfma_f32_16x16x32_bf16 v[62:65], v[150:153], v[186:189], v[62:65]
	v_mfma_f32_16x16x32_bf16 v[62:65], v[154:157], v[190:193], v[62:65]
	v_mfma_f32_16x16x32_bf16 v[58:61], v[166:169], v[190:193], v[58:61]
	v_mfma_f32_16x16x32_bf16 v[58:61], v[158:161], v[186:189], v[58:61]
	v_mfma_f32_16x16x32_bf16 v[50:53], v[158:161], v[194:197], v[50:53]
	v_mfma_f32_16x16x32_bf16 v[50:53], v[166:169], v[198:201], v[50:53]
	v_mfma_f32_16x16x32_bf16 v[54:57], v[154:157], v[198:201], v[54:57]
	v_mfma_f32_16x16x32_bf16 v[54:57], v[150:153], v[194:197], v[54:57]
	v_mfma_f32_16x16x32_bf16 v[38:41], v[150:153], v[202:205], v[38:41]
	v_mfma_f32_16x16x32_bf16 v[38:41], v[154:157], v[206:209], v[38:41]
	v_mfma_f32_16x16x32_bf16 v[34:37], v[166:169], v[206:209], v[34:37]
	v_mfma_f32_16x16x32_bf16 v[34:37], v[158:161], v[202:205], v[34:37]
	v_mfma_f32_16x16x32_bf16 v[18:21], v[158:161], v[210:213], v[18:21]
	v_mfma_f32_16x16x32_bf16 v[18:21], v[166:169], v[214:217], v[18:21]
	v_mfma_f32_16x16x32_bf16 v[22:25], v[154:157], v[214:217], v[22:25]
	v_mfma_f32_16x16x32_bf16 v[22:25], v[150:153], v[210:213], v[22:25]
	v_mfma_f32_16x16x32_bf16 v[6:9], v[170:173], v[210:213], v[6:9]
	v_mfma_f32_16x16x32_bf16 v[6:9], v[174:177], v[214:217], v[6:9]
	v_mfma_f32_16x16x32_bf16 v[2:5], v[182:185], v[214:217], v[2:5]
	v_mfma_f32_16x16x32_bf16 v[2:5], v[178:181], v[210:213], v[2:5]
	v_mfma_f32_16x16x32_bf16 v[10:13], v[178:181], v[202:205], v[10:13]
	v_mfma_f32_16x16x32_bf16 v[10:13], v[182:185], v[206:209], v[10:13]
	v_mfma_f32_16x16x32_bf16 v[14:17], v[174:177], v[206:209], v[14:17]
	v_mfma_f32_16x16x32_bf16 v[14:17], v[170:173], v[202:205], v[14:17]
	v_mfma_f32_16x16x32_bf16 v[30:33], v[170:173], v[194:197], v[30:33]
	v_mfma_f32_16x16x32_bf16 v[30:33], v[174:177], v[198:201], v[30:33]
	v_mfma_f32_16x16x32_bf16 v[26:29], v[182:185], v[198:201], v[26:29]
	v_mfma_f32_16x16x32_bf16 v[26:29], v[178:181], v[194:197], v[26:29]
	v_mfma_f32_16x16x32_bf16 v[42:45], v[178:181], v[186:189], v[42:45]
	v_mfma_f32_16x16x32_bf16 v[42:45], v[182:185], v[190:193], v[42:45]
	v_mfma_f32_16x16x32_bf16 v[46:49], v[174:177], v[190:193], v[46:49]
	v_mfma_f32_16x16x32_bf16 v[46:49], v[170:173], v[186:189], v[46:49]
	s_barrier
	s_add_u32 s10, s10, 0x100
	s_addc_u32 s11, s11, 0
	s_cmp_ge_u32 s38, s17
	s_mov_b32 s13, s38
	s_cbranch_scc0 .LBB0_2632
	s_lshl_b32 s4, s16, 21
	v_readlane_b32 s2, v249, 29
	v_lshl_or_b32 v1, s18, 8, v148
	v_mov_b32_e32 v139, 0
	s_add_u32 s4, s2, s4
	v_readlane_b32 s2, v249, 31
	v_or_b32_e32 v130, s23, v1
	v_cvt_pk_bf16_f32 v70, v70, v71
	v_cvt_pk_bf16_f32 v71, v72, v73
	v_cvt_pk_bf16_f32 v72, v66, v67
	v_add_u32_e32 v66, 0x80, v138
	v_mov_b32_e32 v67, v139
	s_addc_u32 s5, s2, 0
	v_ashrrev_i32_e32 v131, 31, v130
	v_lshlrev_b64 v[132:133], 13, v[138:139]
	v_cvt_pk_bf16_f32 v110, v110, v111
	v_cvt_pk_bf16_f32 v111, v112, v113
	v_cvt_pk_bf16_f32 v112, v106, v107
	v_or_b32_e32 v106, 16, v138
	v_mov_b32_e32 v107, v139
	v_lshlrev_b64 v[66:67], 13, v[66:67]
	v_cvt_pk_bf16_f32 v46, v46, v47
	v_cvt_pk_bf16_f32 v47, v48, v49
	v_cvt_pk_bf16_f32 v48, v42, v43
	v_add_u32_e32 v42, 0x90, v138
	v_mov_b32_e32 v43, v139
	v_lshl_add_u64 v[132:133], s[4:5], 0, v[132:133]
	v_lshlrev_b64 v[130:131], 1, v[130:131]
	v_lshlrev_b64 v[106:107], 13, v[106:107]
	v_cvt_pk_bf16_f32 v94, v94, v95
	v_cvt_pk_bf16_f32 v95, v96, v97
	v_cvt_pk_bf16_f32 v96, v90, v91
	v_or_b32_e32 v90, 32, v138
	v_mov_b32_e32 v91, v139
	v_lshl_add_u64 v[66:67], s[4:5], 0, v[66:67]
	v_lshlrev_b64 v[42:43], 13, v[42:43]
	v_cvt_pk_bf16_f32 v30, v30, v31
	v_cvt_pk_bf16_f32 v31, v32, v33
	v_cvt_pk_bf16_f32 v32, v26, v27
	v_add_u32_e32 v26, 0xa0, v138
	v_mov_b32_e32 v27, v139
	v_lshl_add_u64 v[132:133], v[132:133], 0, v[130:131]
	v_cvt_pk_bf16_f32 v113, v108, v109
	v_lshl_add_u64 v[106:107], s[4:5], 0, v[106:107]
	v_lshlrev_b64 v[90:91], 13, v[90:91]
	v_cvt_pk_bf16_f32 v78, v78, v79
	v_cvt_pk_bf16_f32 v79, v80, v81
	v_cvt_pk_bf16_f32 v80, v74, v75
	v_or_b32_e32 v74, 48, v138
	v_mov_b32_e32 v75, v139
	v_lshl_add_u64 v[66:67], v[66:67], 0, v[130:131]
	v_cvt_pk_bf16_f32 v49, v44, v45
	v_lshl_add_u64 v[42:43], s[4:5], 0, v[42:43]
	v_lshlrev_b64 v[26:27], 13, v[26:27]
	v_add_u32_e32 v138, 0xb0, v138
	global_store_dwordx4 v[132:133], v[110:113], off offset:256
	v_cvt_pk_bf16_f32 v97, v92, v93
	v_lshl_add_u64 v[90:91], s[4:5], 0, v[90:91]
	v_lshl_add_u64 v[110:111], v[106:107], 0, v[130:131]
	v_lshlrev_b64 v[74:75], 13, v[74:75]
	global_store_dwordx4 v[66:67], v[46:49], off offset:256
	v_cvt_pk_bf16_f32 v33, v28, v29
	v_lshl_add_u64 v[26:27], s[4:5], 0, v[26:27]
	v_lshl_add_u64 v[46:47], v[42:43], 0, v[130:131]
	v_cvt_pk_bf16_f32 v14, v14, v15
	v_cvt_pk_bf16_f32 v15, v16, v17
	v_cvt_pk_bf16_f32 v16, v10, v11
	v_lshlrev_b64 v[10:11], 13, v[138:139]
	global_store_dwordx4 v[110:111], v[94:97], off offset:256
	v_cvt_pk_bf16_f32 v81, v76, v77
	v_lshl_add_u64 v[74:75], s[4:5], 0, v[74:75]
	v_lshl_add_u64 v[94:95], v[90:91], 0, v[130:131]
	global_store_dwordx4 v[46:47], v[30:33], off offset:256
	v_cvt_pk_bf16_f32 v17, v12, v13
	v_lshl_add_u64 v[10:11], s[4:5], 0, v[10:11]
	v_lshl_add_u64 v[30:31], v[26:27], 0, v[130:131]
	v_cvt_pk_bf16_f32 v126, v126, v127
	v_cvt_pk_bf16_f32 v127, v128, v129
	v_cvt_pk_bf16_f32 v128, v122, v123
	v_cvt_pk_bf16_f32 v129, v124, v125
	v_cvt_pk_bf16_f32 v106, v118, v119
	v_cvt_pk_bf16_f32 v107, v120, v121
	v_cvt_pk_bf16_f32 v108, v114, v115
	v_cvt_pk_bf16_f32 v109, v116, v117
	v_cvt_pk_bf16_f32 v90, v102, v103
	v_cvt_pk_bf16_f32 v91, v104, v105
	v_cvt_pk_bf16_f32 v92, v98, v99
	v_cvt_pk_bf16_f32 v93, v100, v101
	global_store_dwordx4 v[94:95], v[78:81], off offset:256
	v_cvt_pk_bf16_f32 v76, v82, v83
	v_cvt_pk_bf16_f32 v77, v84, v85
	v_lshl_add_u64 v[78:79], v[74:75], 0, v[130:131]
	v_cvt_pk_bf16_f32 v74, v86, v87
	v_cvt_pk_bf16_f32 v75, v88, v89
	v_cvt_pk_bf16_f32 v73, v68, v69
	v_cvt_pk_bf16_f32 v62, v62, v63
	v_cvt_pk_bf16_f32 v63, v64, v65
	v_cvt_pk_bf16_f32 v64, v58, v59
	v_cvt_pk_bf16_f32 v65, v60, v61
	v_cvt_pk_bf16_f32 v42, v54, v55
	v_cvt_pk_bf16_f32 v43, v56, v57
	v_cvt_pk_bf16_f32 v44, v50, v51
	v_cvt_pk_bf16_f32 v45, v52, v53
	v_cvt_pk_bf16_f32 v26, v38, v39
	v_cvt_pk_bf16_f32 v27, v40, v41
	v_cvt_pk_bf16_f32 v28, v34, v35
	v_cvt_pk_bf16_f32 v29, v36, v37
	global_store_dwordx4 v[30:31], v[14:17], off offset:256
	v_cvt_pk_bf16_f32 v12, v18, v19
	v_cvt_pk_bf16_f32 v13, v20, v21
	v_lshl_add_u64 v[14:15], v[10:11], 0, v[130:131]
	v_cvt_pk_bf16_f32 v10, v22, v23
	v_cvt_pk_bf16_f32 v11, v24, v25
	v_cvt_pk_bf16_f32 v6, v6, v7
	v_cvt_pk_bf16_f32 v7, v8, v9
	v_cvt_pk_bf16_f32 v8, v2, v3
	v_cvt_pk_bf16_f32 v9, v4, v5
	global_store_dwordx4 v[132:133], v[126:129], off
	global_store_dwordx4 v[110:111], v[106:109], off
	global_store_dwordx4 v[94:95], v[90:93], off
	global_store_dwordx4 v[78:79], v[74:77], off
	global_store_dwordx4 v[78:79], v[70:73], off offset:256
	global_store_dwordx4 v[66:67], v[62:65], off
	global_store_dwordx4 v[46:47], v[42:45], off
	global_store_dwordx4 v[30:31], v[26:29], off
	global_store_dwordx4 v[14:15], v[10:13], off
	global_store_dwordx4 v[14:15], v[6:9], off offset:256
	s_waitcnt vmcnt(0)
	s_cmpk_lt_u32 s3, 0x100
	s_cbranch_scc0 .LBB0_2635
	s_barrier
